# GEMM K-loop: trailing s_barrier of each 16-MFMA block issued one MFMA early (after 15th)
# speedup vs baseline: 1.0103x; 1.0103x over previous
; #define PG8_STAGE(bufoff, gbase, voff) do { _Pragma("unroll") for (int _i = 0; _i < 2; ++_i) \
;         __builtin_amdgcn_global_load_lds((const unsigned*)((const char*)(gbase) + (voff)[_i]), (LAS unsigned*)(lds + (bufoff) + ldsw + _i * 8192), 16, 0, 0); } while (0)
; #define PG8_WAIT_V(n) asm volatile("s_waitcnt vmcnt(" #n ")" ::: "memory")
; template <class Epi>
; __device__ __forceinline__ void gemm_phase(ldsp lds, const Gemm g, const StaticOrder& S, const Epi& E) {
;     ...
;         for (int t = 0; t < nt; t += 2) {
;             const bool last = (t == nt - 2);
;             const char* a1 = cA + (size_t)(t + 1) * kstep;
;             const char* a2 = last ? nA : cA + (size_t)(t + 2) * kstep; const char* b2 = last ? nB : cB + (size_t)(t + 2) * kstep;
;             const char* a3 = a2 + kstep; const char* b3 = b2 + kstep;
;             if constexpr (Epi::NPRE > 0) { if (last) E.pre(pre, cur, wr, fr); }
;             if constexpr (Epi::MID_T > 0) { if (t == Epi::MID_T) E.mid(acc, cur, wr, wc, fr, fq); }
;             PG8_LDB(B0, 0, 0); PG8_SCHED; PG8_LDA(At, 0, 0); PG8_STAGE(PG8_SA(1, 1), a1 + hstep, voffA);
;             PG8_WAIT_L(8); PG8_WAIT_V(10); PG8_BAR; PG8_WAIT_L(0); PG8_MMA(0, 0, At, B0); PG8_BAR; PG8_SCHED;
;             PG8_LDB(B1, 0, 1); PG8_STAGE(PG8_SB(0, 0), b2, voffB);
;             PG8_WAIT_V(10); PG8_BAR; PG8_WAIT_L(0); PG8_MMA(0, 1, At, B1); PG8_BAR;
;             PG8_LDA(At, 0, 1); PG8_STAGE(PG8_SA(0, 0), a2, voffA);
;             PG8_WAIT_V(10); PG8_BAR; PG8_WAIT_L(0); PG8_MMA(1, 0, At, B0); PG8_BAR; PG8_SCHED;
;             PG8_STAGE(PG8_SB(0, 1), b2 + hstep, voffB);
;             PG8_WAIT_V(10); PG8_BAR; PG8_MMA(1, 1, At, B1); PG8_BAR;
;             PG8_LDB(B0, 1, 0); PG8_SCHED; PG8_LDA(At, 1, 0); PG8_STAGE(PG8_SA(0, 1), a2 + hstep, voffA);
;             PG8_WAIT_L(8); PG8_WAIT_V(10); PG8_BAR; PG8_WAIT_L(0); PG8_MMA(0, 0, At, B0); PG8_BAR; PG8_SCHED;
;             PG8_LDB(B1, 1, 1); PG8_STAGE(PG8_SB(1, 0), b3, voffB);
;             PG8_WAIT_V(10); PG8_BAR; PG8_WAIT_L(0); PG8_MMA(0, 1, At, B1); PG8_BAR;
;             PG8_LDA(At, 1, 1); PG8_STAGE(PG8_SA(1, 0), a3, voffA);
;             PG8_WAIT_V(10); PG8_BAR; PG8_WAIT_L(0); PG8_MMA(1, 0, At, B0); PG8_BAR; PG8_SCHED;
;             PG8_STAGE(PG8_SB(1, 1), b3 + hstep, voffB);
;             PG8_WAIT_V(10); PG8_BAR; PG8_MMA(1, 1, At, B1); PG8_BAR;
;         }
.LBB0_133:
	v_add_u32_e32 v147, s57, v181
	ds_read_b128 v[166:169], v147
	ds_read_b128 v[170:173], v147 offset:1024
	ds_read_b128 v[174:177], v147 offset:2048
	ds_read_b128 v[184:187], v147 offset:3072
	s_add_u32 s38, s4, 0xfff80080
	s_addc_u32 s39, s5, -1
	s_and_b64 s[36:37], s[36:37], exec
	s_cselect_b32 s39, s7, s39
	s_cselect_b32 s38, s29, s38
	s_cselect_b32 s37, s27, s42
	s_cselect_b32 s36, s40, s41
	v_lshl_add_u64 v[178:179], s[4:5], 0, v[138:139]
	s_add_i32 m0, s45, 0xc000
	ds_read_b128 v[188:191], v183
	ds_read_b128 v[192:195], v183 offset:1024
	ds_read_b128 v[196:199], v183 offset:2048
	ds_read_b128 v[200:203], v183 offset:3072
	ds_read_b128 v[204:207], v183 offset:4096
	ds_read_b128 v[208:211], v183 offset:5120
	ds_read_b128 v[212:215], v183 offset:6144
	ds_read_b128 v[216:219], v183 offset:7168
	global_load_lds_dwordx4 v[178:179], off
	v_lshl_add_u64 v[178:179], s[4:5], 0, v[140:141]
	s_add_i32 m0, s45, 0xe000
	s_nop 0
	global_load_lds_dwordx4 v[178:179], off
	s_waitcnt lgkmcnt(8)
	s_waitcnt vmcnt(10)
	s_barrier
	s_waitcnt lgkmcnt(0)
	s_setprio 1
	s_waitcnt lgkmcnt(0)
	v_mfma_f32_16x16x32_bf16 v[60:63], v[166:169], v[188:191], v[60:63]
	v_mfma_f32_16x16x32_bf16 v[56:59], v[174:177], v[188:191], v[56:59]
	v_mfma_f32_16x16x32_bf16 v[52:55], v[166:169], v[196:199], v[52:55]
	v_mfma_f32_16x16x32_bf16 v[48:51], v[174:177], v[196:199], v[48:51]
	v_mfma_f32_16x16x32_bf16 v[44:47], v[166:169], v[204:207], v[44:47]
	v_mfma_f32_16x16x32_bf16 v[40:43], v[174:177], v[204:207], v[40:43]
	v_mfma_f32_16x16x32_bf16 v[36:39], v[166:169], v[212:215], v[36:39]
	v_mfma_f32_16x16x32_bf16 v[32:35], v[174:177], v[212:215], v[32:35]
	v_mfma_f32_16x16x32_bf16 v[60:63], v[170:173], v[192:195], v[60:63]
	v_mfma_f32_16x16x32_bf16 v[56:59], v[184:187], v[192:195], v[56:59]
	v_mfma_f32_16x16x32_bf16 v[52:55], v[170:173], v[200:203], v[52:55]
	v_mfma_f32_16x16x32_bf16 v[48:51], v[184:187], v[200:203], v[48:51]
	v_mfma_f32_16x16x32_bf16 v[44:47], v[170:173], v[208:211], v[44:47]
	v_mfma_f32_16x16x32_bf16 v[40:43], v[184:187], v[208:211], v[40:43]
	v_mfma_f32_16x16x32_bf16 v[36:39], v[170:173], v[216:219], v[36:39]
	s_barrier
	v_mfma_f32_16x16x32_bf16 v[32:35], v[184:187], v[216:219], v[32:35]
	s_setprio 0
	s_add_i32 s59, s57, s44
	v_add_u32_e32 v147, s58, v181
	v_lshl_add_u64 v[178:179], s[36:37], 0, v[130:131]
	s_mov_b32 m0, s59
	ds_read_b128 v[222:225], v147
	ds_read_b128 v[226:229], v147 offset:1024
	ds_read_b128 v[230:233], v147 offset:2048
	ds_read_b128 v[234:237], v147 offset:3072
	global_load_lds_dwordx4 v[178:179], off
	v_lshl_add_u64 v[238:239], s[36:37], 0, v[134:135]
	s_add_i32 m0, s59, 0x2000
	s_nop 0
	global_load_lds_dwordx4 v[238:239], off
	s_waitcnt vmcnt(10)
	s_barrier
	s_waitcnt lgkmcnt(0)
	s_setprio 1
	s_waitcnt lgkmcnt(0)
	v_mfma_f32_16x16x32_bf16 v[124:127], v[222:225], v[188:191], v[124:127]
	v_mfma_f32_16x16x32_bf16 v[120:123], v[230:233], v[188:191], v[120:123]
	v_mfma_f32_16x16x32_bf16 v[116:119], v[222:225], v[196:199], v[116:119]
	v_mfma_f32_16x16x32_bf16 v[112:115], v[230:233], v[196:199], v[112:115]
	v_mfma_f32_16x16x32_bf16 v[108:111], v[222:225], v[204:207], v[108:111]
	v_mfma_f32_16x16x32_bf16 v[104:107], v[230:233], v[204:207], v[104:107]
	v_mfma_f32_16x16x32_bf16 v[100:103], v[222:225], v[212:215], v[100:103]
	v_mfma_f32_16x16x32_bf16 v[96:99], v[230:233], v[212:215], v[96:99]
	v_mfma_f32_16x16x32_bf16 v[124:127], v[226:229], v[192:195], v[124:127]
	v_mfma_f32_16x16x32_bf16 v[120:123], v[234:237], v[192:195], v[120:123]
	v_mfma_f32_16x16x32_bf16 v[116:119], v[226:229], v[200:203], v[116:119]
	v_mfma_f32_16x16x32_bf16 v[112:115], v[234:237], v[200:203], v[112:115]
	v_mfma_f32_16x16x32_bf16 v[108:111], v[226:229], v[208:211], v[108:111]
	v_mfma_f32_16x16x32_bf16 v[104:107], v[234:237], v[208:211], v[104:107]
	v_mfma_f32_16x16x32_bf16 v[100:103], v[226:229], v[216:219], v[100:103]
	s_barrier
	v_mfma_f32_16x16x32_bf16 v[96:99], v[234:237], v[216:219], v[96:99]
	s_setprio 0
	s_mov_b32 m0, s45
	v_lshl_add_u64 v[240:241], s[38:39], 0, v[128:129]
	ds_read_b128 v[188:191], v183 offset:16384
	ds_read_b128 v[192:195], v183 offset:17408
	ds_read_b128 v[196:199], v183 offset:18432
	ds_read_b128 v[200:203], v183 offset:19456
	ds_read_b128 v[204:207], v183 offset:20480
	ds_read_b128 v[208:211], v183 offset:21504
	ds_read_b128 v[212:215], v183 offset:22528
	ds_read_b128 v[216:219], v183 offset:23552
	global_load_lds_dwordx4 v[240:241], off
	v_lshl_add_u64 v[242:243], s[38:39], 0, v[132:133]
	s_mov_b32 m0, s46
	s_nop 0
	global_load_lds_dwordx4 v[242:243], off
	s_waitcnt vmcnt(10)
	s_barrier
	s_waitcnt lgkmcnt(0)
	s_setprio 1
	s_waitcnt lgkmcnt(0)
	v_mfma_f32_16x16x32_bf16 v[28:31], v[166:169], v[188:191], v[28:31]
	v_mfma_f32_16x16x32_bf16 v[24:27], v[174:177], v[188:191], v[24:27]
	v_mfma_f32_16x16x32_bf16 v[20:23], v[166:169], v[196:199], v[20:23]
	v_mfma_f32_16x16x32_bf16 v[16:19], v[174:177], v[196:199], v[16:19]
	v_mfma_f32_16x16x32_bf16 v[12:15], v[166:169], v[204:207], v[12:15]
	v_mfma_f32_16x16x32_bf16 v[8:11], v[174:177], v[204:207], v[8:11]
	v_mfma_f32_16x16x32_bf16 v[4:7], v[166:169], v[212:215], v[4:7]
	v_mfma_f32_16x16x32_bf16 v[0:3], v[174:177], v[212:215], v[0:3]
	v_mfma_f32_16x16x32_bf16 v[28:31], v[170:173], v[192:195], v[28:31]
	v_mfma_f32_16x16x32_bf16 v[24:27], v[184:187], v[192:195], v[24:27]
	v_mfma_f32_16x16x32_bf16 v[20:23], v[170:173], v[200:203], v[20:23]
	v_mfma_f32_16x16x32_bf16 v[16:19], v[184:187], v[200:203], v[16:19]
	v_mfma_f32_16x16x32_bf16 v[12:15], v[170:173], v[208:211], v[12:15]
	v_mfma_f32_16x16x32_bf16 v[8:11], v[184:187], v[208:211], v[8:11]
	v_mfma_f32_16x16x32_bf16 v[4:7], v[170:173], v[216:219], v[4:7]
	s_barrier
; #define PG8_STAGE(bufoff, gbase, voff) do { _Pragma("unroll") for (int _i = 0; _i < 2; ++_i) \
;         __builtin_amdgcn_global_load_lds((const unsigned*)((const char*)(gbase) + (voff)[_i]), (LAS unsigned*)(lds + (bufoff) + ldsw + _i * 8192), 16, 0, 0); } while (0)
; #define PG8_WAIT_V(n) asm volatile("s_waitcnt vmcnt(" #n ")" ::: "memory")
; template <class Epi>
; __device__ __forceinline__ void gemm_phase(ldsp lds, const Gemm g, const StaticOrder& S, const Epi& E) {
;     ...
;         for (int t = 0; t < nt; t += 2) {
;             const bool last = (t == nt - 2);
;             const char* a1 = cA + (size_t)(t + 1) * kstep;
;             const char* a2 = last ? nA : cA + (size_t)(t + 2) * kstep; const char* b2 = last ? nB : cB + (size_t)(t + 2) * kstep;
;             const char* a3 = a2 + kstep; const char* b3 = b2 + kstep;
;             if constexpr (Epi::NPRE > 0) { if (last) E.pre(pre, cur, wr, fr); }
;             if constexpr (Epi::MID_T > 0) { if (t == Epi::MID_T) E.mid(acc, cur, wr, wc, fr, fq); }
;             PG8_LDB(B0, 0, 0); PG8_SCHED; PG8_LDA(At, 0, 0); PG8_STAGE(PG8_SA(1, 1), a1 + hstep, voffA);
;             PG8_WAIT_L(8); PG8_WAIT_V(10); PG8_BAR; PG8_WAIT_L(0); PG8_MMA(0, 0, At, B0); PG8_BAR; PG8_SCHED;
;             PG8_LDB(B1, 0, 1); PG8_STAGE(PG8_SB(0, 0), b2, voffB);
;             PG8_WAIT_V(10); PG8_BAR; PG8_WAIT_L(0); PG8_MMA(0, 1, At, B1); PG8_BAR;
;             PG8_LDA(At, 0, 1); PG8_STAGE(PG8_SA(0, 0), a2, voffA);
;             PG8_WAIT_V(10); PG8_BAR; PG8_WAIT_L(0); PG8_MMA(1, 0, At, B0); PG8_BAR; PG8_SCHED;
;             PG8_STAGE(PG8_SB(0, 1), b2 + hstep, voffB);
;             PG8_WAIT_V(10); PG8_BAR; PG8_MMA(1, 1, At, B1); PG8_BAR;
;             PG8_LDB(B0, 1, 0); PG8_SCHED; PG8_LDA(At, 1, 0); PG8_STAGE(PG8_SA(0, 1), a2 + hstep, voffA);
;             PG8_WAIT_L(8); PG8_WAIT_V(10); PG8_BAR; PG8_WAIT_L(0); PG8_MMA(0, 0, At, B0); PG8_BAR; PG8_SCHED;
;             PG8_LDB(B1, 1, 1); PG8_STAGE(PG8_SB(1, 0), b3, voffB);
;             PG8_WAIT_V(10); PG8_BAR; PG8_WAIT_L(0); PG8_MMA(0, 1, At, B1); PG8_BAR;
;             PG8_LDA(At, 1, 1); PG8_STAGE(PG8_SA(1, 0), a3, voffA);
;             PG8_WAIT_V(10); PG8_BAR; PG8_WAIT_L(0); PG8_MMA(1, 0, At, B0); PG8_BAR; PG8_SCHED;
;             PG8_STAGE(PG8_SB(1, 1), b3 + hstep, voffB);
;             PG8_WAIT_V(10); PG8_BAR; PG8_MMA(1, 1, At, B1); PG8_BAR;
;         }
	v_mfma_f32_16x16x32_bf16 v[0:3], v[184:187], v[216:219], v[0:3]
	s_setprio 0
	s_add_u32 s60, s36, 0x80000
	s_addc_u32 s61, s37, 0
	s_add_i32 s59, s58, s44
	v_lshl_add_u64 v[166:167], s[60:61], 0, v[130:131]
	s_mov_b32 m0, s59
	s_nop 0
	global_load_lds_dwordx4 v[166:167], off
	v_lshl_add_u64 v[166:167], s[60:61], 0, v[134:135]
	s_add_i32 m0, s59, 0x2000
	s_nop 0
	global_load_lds_dwordx4 v[166:167], off
	s_waitcnt vmcnt(10)
	s_barrier
	s_setprio 1
	v_mfma_f32_16x16x32_bf16 v[92:95], v[222:225], v[188:191], v[92:95]
	v_mfma_f32_16x16x32_bf16 v[88:91], v[230:233], v[188:191], v[88:91]
	v_mfma_f32_16x16x32_bf16 v[84:87], v[222:225], v[196:199], v[84:87]
	v_mfma_f32_16x16x32_bf16 v[80:83], v[230:233], v[196:199], v[80:83]
	v_mfma_f32_16x16x32_bf16 v[76:79], v[222:225], v[204:207], v[76:79]
	v_mfma_f32_16x16x32_bf16 v[72:75], v[230:233], v[204:207], v[72:75]
	v_mfma_f32_16x16x32_bf16 v[68:71], v[222:225], v[212:215], v[68:71]
	v_mfma_f32_16x16x32_bf16 v[64:67], v[230:233], v[212:215], v[64:67]
	v_mfma_f32_16x16x32_bf16 v[92:95], v[226:229], v[192:195], v[92:95]
	v_mfma_f32_16x16x32_bf16 v[88:91], v[234:237], v[192:195], v[88:91]
	v_mfma_f32_16x16x32_bf16 v[84:87], v[226:229], v[200:203], v[84:87]
	v_mfma_f32_16x16x32_bf16 v[80:83], v[234:237], v[200:203], v[80:83]
	v_mfma_f32_16x16x32_bf16 v[76:79], v[226:229], v[208:211], v[76:79]
	v_mfma_f32_16x16x32_bf16 v[72:75], v[234:237], v[208:211], v[72:75]
	v_mfma_f32_16x16x32_bf16 v[68:71], v[226:229], v[216:219], v[68:71]
	s_barrier
	v_mfma_f32_16x16x32_bf16 v[64:67], v[234:237], v[216:219], v[64:67]
	s_setprio 0
	s_add_i32 s59, 0, 0x18000
	v_add_u32_e32 v147, s59, v181
	ds_read_b128 v[166:169], v147
	ds_read_b128 v[170:173], v147 offset:1024
	ds_read_b128 v[174:177], v147 offset:2048
	ds_read_b128 v[184:187], v147 offset:3072
	s_add_u32 s38, s38, 0x80000
	s_addc_u32 s39, s39, 0
	s_mov_b32 m0, s47
	v_lshl_add_u64 v[222:223], s[38:39], 0, v[128:129]
	ds_read_b128 v[188:191], v183 offset:32768
	ds_read_b128 v[192:195], v183 offset:33792
	ds_read_b128 v[196:199], v183 offset:34816
	ds_read_b128 v[200:203], v183 offset:35840
	ds_read_b128 v[204:207], v183 offset:36864
	ds_read_b128 v[208:211], v183 offset:37888
	ds_read_b128 v[212:215], v183 offset:38912
	ds_read_b128 v[216:219], v183 offset:39936
	global_load_lds_dwordx4 v[222:223], off
	v_lshl_add_u64 v[222:223], s[38:39], 0, v[132:133]
	s_mov_b32 m0, s50
	s_nop 0
	global_load_lds_dwordx4 v[222:223], off
	s_waitcnt lgkmcnt(8)
	s_waitcnt vmcnt(10)
	s_barrier
	s_waitcnt lgkmcnt(0)
	s_setprio 1
	s_waitcnt lgkmcnt(0)
	v_mfma_f32_16x16x32_bf16 v[60:63], v[166:169], v[188:191], v[60:63]
	v_mfma_f32_16x16x32_bf16 v[56:59], v[174:177], v[188:191], v[56:59]
	v_mfma_f32_16x16x32_bf16 v[52:55], v[166:169], v[196:199], v[52:55]
	v_mfma_f32_16x16x32_bf16 v[48:51], v[174:177], v[196:199], v[48:51]
	v_mfma_f32_16x16x32_bf16 v[44:47], v[166:169], v[204:207], v[44:47]
	v_mfma_f32_16x16x32_bf16 v[40:43], v[174:177], v[204:207], v[40:43]
	v_mfma_f32_16x16x32_bf16 v[36:39], v[166:169], v[212:215], v[36:39]
	v_mfma_f32_16x16x32_bf16 v[32:35], v[174:177], v[212:215], v[32:35]
	v_mfma_f32_16x16x32_bf16 v[60:63], v[170:173], v[192:195], v[60:63]
	v_mfma_f32_16x16x32_bf16 v[56:59], v[184:187], v[192:195], v[56:59]
	v_mfma_f32_16x16x32_bf16 v[52:55], v[170:173], v[200:203], v[52:55]
	v_mfma_f32_16x16x32_bf16 v[48:51], v[184:187], v[200:203], v[48:51]
	v_mfma_f32_16x16x32_bf16 v[44:47], v[170:173], v[208:211], v[44:47]
	v_mfma_f32_16x16x32_bf16 v[40:43], v[184:187], v[208:211], v[40:43]
	v_mfma_f32_16x16x32_bf16 v[36:39], v[170:173], v[216:219], v[36:39]
	s_barrier
	v_mfma_f32_16x16x32_bf16 v[32:35], v[184:187], v[216:219], v[32:35]
	s_setprio 0
	s_add_i32 s38, 0, 0x1c000
	s_add_i32 s39, s59, s44
	v_add_u32_e32 v147, s38, v181
	v_lshl_add_u64 v[178:179], v[178:179], 0, s[22:23]
	s_mov_b32 m0, s39
	ds_read_b128 v[222:225], v147
	ds_read_b128 v[226:229], v147 offset:1024
	ds_read_b128 v[230:233], v147 offset:2048
	ds_read_b128 v[234:237], v147 offset:3072
	global_load_lds_dwordx4 v[178:179], off
	v_lshl_add_u64 v[178:179], v[238:239], 0, s[22:23]
	s_add_i32 m0, s39, 0x2000
	s_nop 0
	global_load_lds_dwordx4 v[178:179], off
	s_waitcnt vmcnt(10)
	s_barrier
; #define PG8_STAGE(bufoff, gbase, voff) do { _Pragma("unroll") for (int _i = 0; _i < 2; ++_i) \
;         __builtin_amdgcn_global_load_lds((const unsigned*)((const char*)(gbase) + (voff)[_i]), (LAS unsigned*)(lds + (bufoff) + ldsw + _i * 8192), 16, 0, 0); } while (0)
; #define PG8_WAIT_V(n) asm volatile("s_waitcnt vmcnt(" #n ")" ::: "memory")
; template <class Epi>
; __device__ __forceinline__ void gemm_phase(ldsp lds, const Gemm g, const StaticOrder& S, const Epi& E) {
;     ...
;         for (int t = 0; t < nt; t += 2) {
;             const bool last = (t == nt - 2);
;             const char* a1 = cA + (size_t)(t + 1) * kstep;
;             const char* a2 = last ? nA : cA + (size_t)(t + 2) * kstep; const char* b2 = last ? nB : cB + (size_t)(t + 2) * kstep;
;             const char* a3 = a2 + kstep; const char* b3 = b2 + kstep;
;             if constexpr (Epi::NPRE > 0) { if (last) E.pre(pre, cur, wr, fr); }
;             if constexpr (Epi::MID_T > 0) { if (t == Epi::MID_T) E.mid(acc, cur, wr, wc, fr, fq); }
;             PG8_LDB(B0, 0, 0); PG8_SCHED; PG8_LDA(At, 0, 0); PG8_STAGE(PG8_SA(1, 1), a1 + hstep, voffA);
;             PG8_WAIT_L(8); PG8_WAIT_V(10); PG8_BAR; PG8_WAIT_L(0); PG8_MMA(0, 0, At, B0); PG8_BAR; PG8_SCHED;
;             PG8_LDB(B1, 0, 1); PG8_STAGE(PG8_SB(0, 0), b2, voffB);
;             PG8_WAIT_V(10); PG8_BAR; PG8_WAIT_L(0); PG8_MMA(0, 1, At, B1); PG8_BAR;
;             PG8_LDA(At, 0, 1); PG8_STAGE(PG8_SA(0, 0), a2, voffA);
;             PG8_WAIT_V(10); PG8_BAR; PG8_WAIT_L(0); PG8_MMA(1, 0, At, B0); PG8_BAR; PG8_SCHED;
;             PG8_STAGE(PG8_SB(0, 1), b2 + hstep, voffB);
;             PG8_WAIT_V(10); PG8_BAR; PG8_MMA(1, 1, At, B1); PG8_BAR;
;             PG8_LDB(B0, 1, 0); PG8_SCHED; PG8_LDA(At, 1, 0); PG8_STAGE(PG8_SA(0, 1), a2 + hstep, voffA);
;             PG8_WAIT_L(8); PG8_WAIT_V(10); PG8_BAR; PG8_WAIT_L(0); PG8_MMA(0, 0, At, B0); PG8_BAR; PG8_SCHED;
;             PG8_LDB(B1, 1, 1); PG8_STAGE(PG8_SB(1, 0), b3, voffB);
;             PG8_WAIT_V(10); PG8_BAR; PG8_WAIT_L(0); PG8_MMA(0, 1, At, B1); PG8_BAR;
;             PG8_LDA(At, 1, 1); PG8_STAGE(PG8_SA(1, 0), a3, voffA);
;             PG8_WAIT_V(10); PG8_BAR; PG8_WAIT_L(0); PG8_MMA(1, 0, At, B0); PG8_BAR; PG8_SCHED;
;             PG8_STAGE(PG8_SB(1, 1), b3 + hstep, voffB);
;             PG8_WAIT_V(10); PG8_BAR; PG8_MMA(1, 1, At, B1); PG8_BAR;
;         }
	s_waitcnt lgkmcnt(0)
	s_setprio 1
	s_waitcnt lgkmcnt(0)
	v_mfma_f32_16x16x32_bf16 v[124:127], v[222:225], v[188:191], v[124:127]
	v_mfma_f32_16x16x32_bf16 v[120:123], v[230:233], v[188:191], v[120:123]
	v_mfma_f32_16x16x32_bf16 v[116:119], v[222:225], v[196:199], v[116:119]
	v_mfma_f32_16x16x32_bf16 v[112:115], v[230:233], v[196:199], v[112:115]
	v_mfma_f32_16x16x32_bf16 v[108:111], v[222:225], v[204:207], v[108:111]
	v_mfma_f32_16x16x32_bf16 v[104:107], v[230:233], v[204:207], v[104:107]
	v_mfma_f32_16x16x32_bf16 v[100:103], v[222:225], v[212:215], v[100:103]
	v_mfma_f32_16x16x32_bf16 v[96:99], v[230:233], v[212:215], v[96:99]
	v_mfma_f32_16x16x32_bf16 v[124:127], v[226:229], v[192:195], v[124:127]
	v_mfma_f32_16x16x32_bf16 v[120:123], v[234:237], v[192:195], v[120:123]
	v_mfma_f32_16x16x32_bf16 v[116:119], v[226:229], v[200:203], v[116:119]
	v_mfma_f32_16x16x32_bf16 v[112:115], v[234:237], v[200:203], v[112:115]
	v_mfma_f32_16x16x32_bf16 v[108:111], v[226:229], v[208:211], v[108:111]
	v_mfma_f32_16x16x32_bf16 v[104:107], v[234:237], v[208:211], v[104:107]
	v_mfma_f32_16x16x32_bf16 v[100:103], v[226:229], v[216:219], v[100:103]
	s_barrier
	v_mfma_f32_16x16x32_bf16 v[96:99], v[234:237], v[216:219], v[96:99]
	s_setprio 0
	s_mov_b32 m0, s52
	v_lshl_add_u64 v[178:179], v[240:241], 0, s[22:23]
	ds_read_b128 v[188:191], v183 offset:49152
	ds_read_b128 v[192:195], v183 offset:50176
	ds_read_b128 v[196:199], v183 offset:51200
	ds_read_b128 v[200:203], v183 offset:52224
	ds_read_b128 v[204:207], v183 offset:53248
	ds_read_b128 v[208:211], v183 offset:54272
	ds_read_b128 v[212:215], v183 offset:55296
	ds_read_b128 v[216:219], v183 offset:56320
	global_load_lds_dwordx4 v[178:179], off
	v_lshl_add_u64 v[178:179], v[242:243], 0, s[22:23]
	s_mov_b32 m0, s53
	s_nop 0
	global_load_lds_dwordx4 v[178:179], off
	s_waitcnt vmcnt(10)
	s_barrier
	s_waitcnt lgkmcnt(0)
	s_setprio 1
	s_waitcnt lgkmcnt(0)
	v_mfma_f32_16x16x32_bf16 v[28:31], v[166:169], v[188:191], v[28:31]
	v_mfma_f32_16x16x32_bf16 v[24:27], v[174:177], v[188:191], v[24:27]
	v_mfma_f32_16x16x32_bf16 v[20:23], v[166:169], v[196:199], v[20:23]
	v_mfma_f32_16x16x32_bf16 v[16:19], v[174:177], v[196:199], v[16:19]
	v_mfma_f32_16x16x32_bf16 v[12:15], v[166:169], v[204:207], v[12:15]
	v_mfma_f32_16x16x32_bf16 v[8:11], v[174:177], v[204:207], v[8:11]
	v_mfma_f32_16x16x32_bf16 v[4:7], v[166:169], v[212:215], v[4:7]
	v_mfma_f32_16x16x32_bf16 v[0:3], v[174:177], v[212:215], v[0:3]
	v_mfma_f32_16x16x32_bf16 v[28:31], v[170:173], v[192:195], v[28:31]
	v_mfma_f32_16x16x32_bf16 v[24:27], v[184:187], v[192:195], v[24:27]
	v_mfma_f32_16x16x32_bf16 v[20:23], v[170:173], v[200:203], v[20:23]
	v_mfma_f32_16x16x32_bf16 v[16:19], v[184:187], v[200:203], v[16:19]
	v_mfma_f32_16x16x32_bf16 v[12:15], v[170:173], v[208:211], v[12:15]
	v_mfma_f32_16x16x32_bf16 v[8:11], v[184:187], v[208:211], v[8:11]
	v_mfma_f32_16x16x32_bf16 v[4:7], v[170:173], v[216:219], v[4:7]
	s_barrier
	v_mfma_f32_16x16x32_bf16 v[0:3], v[184:187], v[216:219], v[0:3]
	s_setprio 0
	s_add_u32 s36, s36, 0x80080
	s_addc_u32 s37, s37, 0
	s_add_i32 s38, s38, s44
	v_lshl_add_u64 v[166:167], s[36:37], 0, v[130:131]
	s_mov_b32 m0, s38
	s_nop 0
	global_load_lds_dwordx4 v[166:167], off
	v_lshl_add_u64 v[166:167], s[36:37], 0, v[134:135]
	s_add_i32 m0, s38, 0x2000
	s_nop 0
	global_load_lds_dwordx4 v[166:167], off
	s_waitcnt vmcnt(10)
	s_barrier
	s_setprio 1
	v_mfma_f32_16x16x32_bf16 v[92:95], v[222:225], v[188:191], v[92:95]
	v_mfma_f32_16x16x32_bf16 v[88:91], v[230:233], v[188:191], v[88:91]
	v_mfma_f32_16x16x32_bf16 v[84:87], v[222:225], v[196:199], v[84:87]
	v_mfma_f32_16x16x32_bf16 v[80:83], v[230:233], v[196:199], v[80:83]
	v_mfma_f32_16x16x32_bf16 v[76:79], v[222:225], v[204:207], v[76:79]
	v_mfma_f32_16x16x32_bf16 v[72:75], v[230:233], v[204:207], v[72:75]
	v_mfma_f32_16x16x32_bf16 v[68:71], v[222:225], v[212:215], v[68:71]
	v_mfma_f32_16x16x32_bf16 v[64:67], v[230:233], v[212:215], v[64:67]
	v_mfma_f32_16x16x32_bf16 v[92:95], v[226:229], v[192:195], v[92:95]
	v_mfma_f32_16x16x32_bf16 v[88:91], v[234:237], v[192:195], v[88:91]
	v_mfma_f32_16x16x32_bf16 v[84:87], v[226:229], v[200:203], v[84:87]
	v_mfma_f32_16x16x32_bf16 v[80:83], v[234:237], v[200:203], v[80:83]
	v_mfma_f32_16x16x32_bf16 v[76:79], v[226:229], v[208:211], v[76:79]
	v_mfma_f32_16x16x32_bf16 v[72:75], v[234:237], v[208:211], v[72:75]
	v_mfma_f32_16x16x32_bf16 v[68:71], v[226:229], v[216:219], v[68:71]
	s_barrier
	v_mfma_f32_16x16x32_bf16 v[64:67], v[234:237], v[216:219], v[64:67]
	s_setprio 0
	s_add_i32 s43, s43, 2
	s_add_u32 s4, s4, 0x100
	s_addc_u32 s5, s5, 0
	s_add_u32 s41, s41, 0x100
	s_addc_u32 s42, s42, 0
	s_cmp_gt_u32 s43, 29
	s_cbranch_scc1 .LBB0_136

; #define PG8_STAGE(bufoff, gbase, voff) do { _Pragma("unroll") for (int _i = 0; _i < 2; ++_i) \
;         __builtin_amdgcn_global_load_lds((const unsigned*)((const char*)(gbase) + (voff)[_i]), (LAS unsigned*)(lds + (bufoff) + ldsw + _i * 8192), 16, 0, 0); } while (0)
; #define PG8_WAIT_V(n) asm volatile("s_waitcnt vmcnt(" #n ")" ::: "memory")
; template <class Epi>
; __device__ __forceinline__ void gemm_phase(ldsp lds, const Gemm g, const StaticOrder& S, const Epi& E) {
;     ...
;         for (int t = 0; t < nt; t += 2) {
;             const bool last = (t == nt - 2);
;             const char* a1 = cA + (size_t)(t + 1) * kstep;
;             const char* a2 = last ? nA : cA + (size_t)(t + 2) * kstep; const char* b2 = last ? nB : cB + (size_t)(t + 2) * kstep;
;             const char* a3 = a2 + kstep; const char* b3 = b2 + kstep;
;             if constexpr (Epi::NPRE > 0) { if (last) E.pre(pre, cur, wr, fr); }
;             if constexpr (Epi::MID_T > 0) { if (t == Epi::MID_T) E.mid(acc, cur, wr, wc, fr, fq); }
;             PG8_LDB(B0, 0, 0); PG8_SCHED; PG8_LDA(At, 0, 0); PG8_STAGE(PG8_SA(1, 1), a1 + hstep, voffA);
;             PG8_WAIT_L(8); PG8_WAIT_V(10); PG8_BAR; PG8_WAIT_L(0); PG8_MMA(0, 0, At, B0); PG8_BAR; PG8_SCHED;
;             PG8_LDB(B1, 0, 1); PG8_STAGE(PG8_SB(0, 0), b2, voffB);
;             PG8_WAIT_V(10); PG8_BAR; PG8_WAIT_L(0); PG8_MMA(0, 1, At, B1); PG8_BAR;
;             PG8_LDA(At, 0, 1); PG8_STAGE(PG8_SA(0, 0), a2, voffA);
;             PG8_WAIT_V(10); PG8_BAR; PG8_WAIT_L(0); PG8_MMA(1, 0, At, B0); PG8_BAR; PG8_SCHED;
;             PG8_STAGE(PG8_SB(0, 1), b2 + hstep, voffB);
;             PG8_WAIT_V(10); PG8_BAR; PG8_MMA(1, 1, At, B1); PG8_BAR;
;             PG8_LDB(B0, 1, 0); PG8_SCHED; PG8_LDA(At, 1, 0); PG8_STAGE(PG8_SA(0, 1), a2 + hstep, voffA);
;             PG8_WAIT_L(8); PG8_WAIT_V(10); PG8_BAR; PG8_WAIT_L(0); PG8_MMA(0, 0, At, B0); PG8_BAR; PG8_SCHED;
;             PG8_LDB(B1, 1, 1); PG8_STAGE(PG8_SB(1, 0), b3, voffB);
;             PG8_WAIT_V(10); PG8_BAR; PG8_WAIT_L(0); PG8_MMA(0, 1, At, B1); PG8_BAR;
;             PG8_LDA(At, 1, 1); PG8_STAGE(PG8_SA(1, 0), a3, voffA);
;             PG8_WAIT_V(10); PG8_BAR; PG8_WAIT_L(0); PG8_MMA(1, 0, At, B0); PG8_BAR; PG8_SCHED;
;             PG8_STAGE(PG8_SB(1, 1), b3 + hstep, voffB);
;             PG8_WAIT_V(10); PG8_BAR; PG8_MMA(1, 1, At, B1); PG8_BAR;
;         }
.LBB0_574:
	ds_read_b128 v[128:131], v219
	ds_read_b128 v[132:135], v219 offset:1024
	ds_read_b128 v[136:139], v219 offset:2048
	ds_read_b128 v[140:143], v219 offset:3072
	s_add_u32 s22, s20, 0xfffe0080
	s_addc_u32 s23, s21, -1
	s_cmp_eq_u32 s46, 4
	s_cselect_b32 s25, s13, s23
	s_cselect_b32 s24, s42, s22
	s_cselect_b32 s23, s11, s45
	s_cselect_b32 s22, s43, s44
	v_lshl_add_u64 v[192:193], s[20:21], 0, v[184:185]
	s_add_i32 m0, s19, 0xc000
	ds_read_b128 v[144:147], v221
	ds_read_b128 v[148:151], v221 offset:1024
	ds_read_b128 v[152:155], v221 offset:2048
	ds_read_b128 v[156:159], v221 offset:3072
	ds_read_b128 v[160:163], v221 offset:4096
	ds_read_b128 v[164:167], v221 offset:5120
	ds_read_b128 v[168:171], v221 offset:6144
	ds_read_b128 v[172:175], v221 offset:7168
	global_load_lds_dwordx4 v[192:193], off
	v_lshl_add_u64 v[192:193], s[20:21], 0, v[186:187]
	s_add_i32 m0, s19, 0xe000
	s_nop 0
	global_load_lds_dwordx4 v[192:193], off
	s_waitcnt lgkmcnt(8)
	s_waitcnt vmcnt(10)
	s_barrier
	s_waitcnt lgkmcnt(0)
	s_setprio 1
	s_waitcnt lgkmcnt(0)
	v_mfma_f32_16x16x32_bf16 v[124:127], v[128:131], v[144:147], v[124:127]
	v_mfma_f32_16x16x32_bf16 v[120:123], v[136:139], v[144:147], v[120:123]
	v_mfma_f32_16x16x32_bf16 v[116:119], v[128:131], v[152:155], v[116:119]
	v_mfma_f32_16x16x32_bf16 v[112:115], v[136:139], v[152:155], v[112:115]
	v_mfma_f32_16x16x32_bf16 v[108:111], v[128:131], v[160:163], v[108:111]
	v_mfma_f32_16x16x32_bf16 v[104:107], v[136:139], v[160:163], v[104:107]
	v_mfma_f32_16x16x32_bf16 v[100:103], v[128:131], v[168:171], v[100:103]
	v_mfma_f32_16x16x32_bf16 v[96:99], v[136:139], v[168:171], v[96:99]
	v_mfma_f32_16x16x32_bf16 v[124:127], v[132:135], v[148:151], v[124:127]
	v_mfma_f32_16x16x32_bf16 v[120:123], v[140:143], v[148:151], v[120:123]
	v_mfma_f32_16x16x32_bf16 v[116:119], v[132:135], v[156:159], v[116:119]
	v_mfma_f32_16x16x32_bf16 v[112:115], v[140:143], v[156:159], v[112:115]
	v_mfma_f32_16x16x32_bf16 v[108:111], v[132:135], v[164:167], v[108:111]
	v_mfma_f32_16x16x32_bf16 v[104:107], v[140:143], v[164:167], v[104:107]
	v_mfma_f32_16x16x32_bf16 v[100:103], v[132:135], v[172:175], v[100:103]
	s_barrier
	v_mfma_f32_16x16x32_bf16 v[96:99], v[140:143], v[172:175], v[96:99]
	s_setprio 0
	s_add_i32 s47, s38, s28
	v_lshl_add_u64 v[208:209], s[22:23], 0, v[178:179]
	s_mov_b32 m0, s47
	ds_read_b128 v[192:195], v222
	ds_read_b128 v[196:199], v222 offset:1024
	ds_read_b128 v[200:203], v222 offset:2048
	ds_read_b128 v[204:207], v222 offset:3072
	global_load_lds_dwordx4 v[208:209], off
	v_lshl_add_u64 v[210:211], s[22:23], 0, v[182:183]
	s_add_i32 m0, s47, 0x2000
	s_nop 0
	global_load_lds_dwordx4 v[210:211], off
	s_waitcnt vmcnt(10)
	s_barrier
	s_waitcnt lgkmcnt(0)
	s_setprio 1
	s_waitcnt lgkmcnt(0)
	v_mfma_f32_16x16x32_bf16 v[60:63], v[192:195], v[144:147], v[60:63]
	v_mfma_f32_16x16x32_bf16 v[56:59], v[200:203], v[144:147], v[56:59]
	v_mfma_f32_16x16x32_bf16 v[52:55], v[192:195], v[152:155], v[52:55]
	v_mfma_f32_16x16x32_bf16 v[48:51], v[200:203], v[152:155], v[48:51]
	v_mfma_f32_16x16x32_bf16 v[44:47], v[192:195], v[160:163], v[44:47]
	v_mfma_f32_16x16x32_bf16 v[40:43], v[200:203], v[160:163], v[40:43]
	v_mfma_f32_16x16x32_bf16 v[36:39], v[192:195], v[168:171], v[36:39]
	v_mfma_f32_16x16x32_bf16 v[32:35], v[200:203], v[168:171], v[32:35]
	v_mfma_f32_16x16x32_bf16 v[60:63], v[196:199], v[148:151], v[60:63]
	v_mfma_f32_16x16x32_bf16 v[56:59], v[204:207], v[148:151], v[56:59]
	v_mfma_f32_16x16x32_bf16 v[52:55], v[196:199], v[156:159], v[52:55]
	v_mfma_f32_16x16x32_bf16 v[48:51], v[204:207], v[156:159], v[48:51]
	v_mfma_f32_16x16x32_bf16 v[44:47], v[196:199], v[164:167], v[44:47]
	v_mfma_f32_16x16x32_bf16 v[40:43], v[204:207], v[164:167], v[40:43]
	v_mfma_f32_16x16x32_bf16 v[36:39], v[196:199], v[172:175], v[36:39]
	s_barrier
	v_mfma_f32_16x16x32_bf16 v[32:35], v[204:207], v[172:175], v[32:35]
	s_setprio 0
	s_mov_b32 m0, s19
	v_lshl_add_u64 v[212:213], s[24:25], 0, v[176:177]
	ds_read_b128 v[144:147], v221 offset:16384
	ds_read_b128 v[148:151], v221 offset:17408
	ds_read_b128 v[152:155], v221 offset:18432
	ds_read_b128 v[156:159], v221 offset:19456
	ds_read_b128 v[160:163], v221 offset:20480
	ds_read_b128 v[164:167], v221 offset:21504
	ds_read_b128 v[168:171], v221 offset:22528
	ds_read_b128 v[172:175], v221 offset:23552
	global_load_lds_dwordx4 v[212:213], off
	v_lshl_add_u64 v[214:215], s[24:25], 0, v[180:181]
	s_mov_b32 m0, s29
	s_nop 0
	global_load_lds_dwordx4 v[214:215], off
	s_waitcnt vmcnt(10)
	s_barrier
	s_waitcnt lgkmcnt(0)
	s_setprio 1
	s_waitcnt lgkmcnt(0)
	v_mfma_f32_16x16x32_bf16 v[92:95], v[128:131], v[144:147], v[92:95]
	v_mfma_f32_16x16x32_bf16 v[88:91], v[136:139], v[144:147], v[88:91]
	v_mfma_f32_16x16x32_bf16 v[84:87], v[128:131], v[152:155], v[84:87]
	v_mfma_f32_16x16x32_bf16 v[80:83], v[136:139], v[152:155], v[80:83]
	v_mfma_f32_16x16x32_bf16 v[76:79], v[128:131], v[160:163], v[76:79]
	v_mfma_f32_16x16x32_bf16 v[72:75], v[136:139], v[160:163], v[72:75]
	v_mfma_f32_16x16x32_bf16 v[68:71], v[128:131], v[168:171], v[68:71]
	v_mfma_f32_16x16x32_bf16 v[64:67], v[136:139], v[168:171], v[64:67]
	v_mfma_f32_16x16x32_bf16 v[92:95], v[132:135], v[148:151], v[92:95]
	v_mfma_f32_16x16x32_bf16 v[88:91], v[140:143], v[148:151], v[88:91]
	v_mfma_f32_16x16x32_bf16 v[84:87], v[132:135], v[156:159], v[84:87]
	v_mfma_f32_16x16x32_bf16 v[80:83], v[140:143], v[156:159], v[80:83]
	v_mfma_f32_16x16x32_bf16 v[76:79], v[132:135], v[164:167], v[76:79]
	v_mfma_f32_16x16x32_bf16 v[72:75], v[140:143], v[164:167], v[72:75]
	v_mfma_f32_16x16x32_bf16 v[68:71], v[132:135], v[172:175], v[68:71]
	s_barrier
; #define PG8_STAGE(bufoff, gbase, voff) do { _Pragma("unroll") for (int _i = 0; _i < 2; ++_i) \
;         __builtin_amdgcn_global_load_lds((const unsigned*)((const char*)(gbase) + (voff)[_i]), (LAS unsigned*)(lds + (bufoff) + ldsw + _i * 8192), 16, 0, 0); } while (0)
; #define PG8_WAIT_V(n) asm volatile("s_waitcnt vmcnt(" #n ")" ::: "memory")
; template <class Epi>
; __device__ __forceinline__ void gemm_phase(ldsp lds, const Gemm g, const StaticOrder& S, const Epi& E) {
;     ...
;         for (int t = 0; t < nt; t += 2) {
;             const bool last = (t == nt - 2);
;             const char* a1 = cA + (size_t)(t + 1) * kstep;
;             const char* a2 = last ? nA : cA + (size_t)(t + 2) * kstep; const char* b2 = last ? nB : cB + (size_t)(t + 2) * kstep;
;             const char* a3 = a2 + kstep; const char* b3 = b2 + kstep;
;             if constexpr (Epi::NPRE > 0) { if (last) E.pre(pre, cur, wr, fr); }
;             if constexpr (Epi::MID_T > 0) { if (t == Epi::MID_T) E.mid(acc, cur, wr, wc, fr, fq); }
;             PG8_LDB(B0, 0, 0); PG8_SCHED; PG8_LDA(At, 0, 0); PG8_STAGE(PG8_SA(1, 1), a1 + hstep, voffA);
;             PG8_WAIT_L(8); PG8_WAIT_V(10); PG8_BAR; PG8_WAIT_L(0); PG8_MMA(0, 0, At, B0); PG8_BAR; PG8_SCHED;
;             PG8_LDB(B1, 0, 1); PG8_STAGE(PG8_SB(0, 0), b2, voffB);
;             PG8_WAIT_V(10); PG8_BAR; PG8_WAIT_L(0); PG8_MMA(0, 1, At, B1); PG8_BAR;
;             PG8_LDA(At, 0, 1); PG8_STAGE(PG8_SA(0, 0), a2, voffA);
;             PG8_WAIT_V(10); PG8_BAR; PG8_WAIT_L(0); PG8_MMA(1, 0, At, B0); PG8_BAR; PG8_SCHED;
;             PG8_STAGE(PG8_SB(0, 1), b2 + hstep, voffB);
;             PG8_WAIT_V(10); PG8_BAR; PG8_MMA(1, 1, At, B1); PG8_BAR;
;             PG8_LDB(B0, 1, 0); PG8_SCHED; PG8_LDA(At, 1, 0); PG8_STAGE(PG8_SA(0, 1), a2 + hstep, voffA);
;             PG8_WAIT_L(8); PG8_WAIT_V(10); PG8_BAR; PG8_WAIT_L(0); PG8_MMA(0, 0, At, B0); PG8_BAR; PG8_SCHED;
;             PG8_LDB(B1, 1, 1); PG8_STAGE(PG8_SB(1, 0), b3, voffB);
;             PG8_WAIT_V(10); PG8_BAR; PG8_WAIT_L(0); PG8_MMA(0, 1, At, B1); PG8_BAR;
;             PG8_LDA(At, 1, 1); PG8_STAGE(PG8_SA(1, 0), a3, voffA);
;             PG8_WAIT_V(10); PG8_BAR; PG8_WAIT_L(0); PG8_MMA(1, 0, At, B0); PG8_BAR; PG8_SCHED;
;             PG8_STAGE(PG8_SB(1, 1), b3 + hstep, voffB);
;             PG8_WAIT_V(10); PG8_BAR; PG8_MMA(1, 1, At, B1); PG8_BAR;
;         }
	v_mfma_f32_16x16x32_bf16 v[64:67], v[140:143], v[172:175], v[64:67]
	s_setprio 0
	s_add_u32 s50, s22, 0x20000
	s_addc_u32 s51, s23, 0
	s_add_i32 s47, s39, s28
	v_lshl_add_u64 v[128:129], s[50:51], 0, v[178:179]
	s_mov_b32 m0, s47
	s_nop 0
	global_load_lds_dwordx4 v[128:129], off
	v_lshl_add_u64 v[128:129], s[50:51], 0, v[182:183]
	s_add_i32 m0, s47, 0x2000
	s_nop 0
	global_load_lds_dwordx4 v[128:129], off
	s_waitcnt vmcnt(10)
	s_barrier
	s_setprio 1
	v_mfma_f32_16x16x32_bf16 v[28:31], v[192:195], v[144:147], v[28:31]
	v_mfma_f32_16x16x32_bf16 v[24:27], v[200:203], v[144:147], v[24:27]
	v_mfma_f32_16x16x32_bf16 v[20:23], v[192:195], v[152:155], v[20:23]
	v_mfma_f32_16x16x32_bf16 v[16:19], v[200:203], v[152:155], v[16:19]
	v_mfma_f32_16x16x32_bf16 v[12:15], v[192:195], v[160:163], v[12:15]
	v_mfma_f32_16x16x32_bf16 v[8:11], v[200:203], v[160:163], v[8:11]
	v_mfma_f32_16x16x32_bf16 v[4:7], v[192:195], v[168:171], v[4:7]
	v_mfma_f32_16x16x32_bf16 v[0:3], v[200:203], v[168:171], v[0:3]
	v_mfma_f32_16x16x32_bf16 v[28:31], v[196:199], v[148:151], v[28:31]
	v_mfma_f32_16x16x32_bf16 v[24:27], v[204:207], v[148:151], v[24:27]
	v_mfma_f32_16x16x32_bf16 v[20:23], v[196:199], v[156:159], v[20:23]
	v_mfma_f32_16x16x32_bf16 v[16:19], v[204:207], v[156:159], v[16:19]
	v_mfma_f32_16x16x32_bf16 v[12:15], v[196:199], v[164:167], v[12:15]
	v_mfma_f32_16x16x32_bf16 v[8:11], v[204:207], v[164:167], v[8:11]
	v_mfma_f32_16x16x32_bf16 v[4:7], v[196:199], v[172:175], v[4:7]
	s_barrier
	v_mfma_f32_16x16x32_bf16 v[0:3], v[204:207], v[172:175], v[0:3]
	s_setprio 0
	s_add_i32 s47, 0, 0x18000
	v_add_u32_e32 v140, s47, v217
	ds_read_b128 v[128:131], v140
	ds_read_b128 v[132:135], v140 offset:1024
	ds_read_b128 v[136:139], v140 offset:2048
	ds_read_b128 v[140:143], v140 offset:3072
	s_add_u32 s24, s24, 0x20000
	s_addc_u32 s25, s25, 0
	s_mov_b32 m0, s30
	v_lshl_add_u64 v[192:193], s[24:25], 0, v[176:177]
	ds_read_b128 v[144:147], v221 offset:32768
	ds_read_b128 v[148:151], v221 offset:33792
	ds_read_b128 v[152:155], v221 offset:34816
	ds_read_b128 v[156:159], v221 offset:35840
	ds_read_b128 v[160:163], v221 offset:36864
	ds_read_b128 v[164:167], v221 offset:37888
	ds_read_b128 v[168:171], v221 offset:38912
	ds_read_b128 v[172:175], v221 offset:39936
	global_load_lds_dwordx4 v[192:193], off
	v_lshl_add_u64 v[192:193], s[24:25], 0, v[180:181]
	s_mov_b32 m0, s31
	s_nop 0
	global_load_lds_dwordx4 v[192:193], off
	s_waitcnt lgkmcnt(8)
	s_waitcnt vmcnt(10)
	s_barrier
	s_waitcnt lgkmcnt(0)
	s_setprio 1
	s_waitcnt lgkmcnt(0)
	v_mfma_f32_16x16x32_bf16 v[124:127], v[128:131], v[144:147], v[124:127]
	v_mfma_f32_16x16x32_bf16 v[120:123], v[136:139], v[144:147], v[120:123]
	v_mfma_f32_16x16x32_bf16 v[116:119], v[128:131], v[152:155], v[116:119]
	v_mfma_f32_16x16x32_bf16 v[112:115], v[136:139], v[152:155], v[112:115]
	v_mfma_f32_16x16x32_bf16 v[108:111], v[128:131], v[160:163], v[108:111]
	v_mfma_f32_16x16x32_bf16 v[104:107], v[136:139], v[160:163], v[104:107]
	v_mfma_f32_16x16x32_bf16 v[100:103], v[128:131], v[168:171], v[100:103]
	v_mfma_f32_16x16x32_bf16 v[96:99], v[136:139], v[168:171], v[96:99]
	v_mfma_f32_16x16x32_bf16 v[124:127], v[132:135], v[148:151], v[124:127]
	v_mfma_f32_16x16x32_bf16 v[120:123], v[140:143], v[148:151], v[120:123]
	v_mfma_f32_16x16x32_bf16 v[116:119], v[132:135], v[156:159], v[116:119]
	v_mfma_f32_16x16x32_bf16 v[112:115], v[140:143], v[156:159], v[112:115]
	v_mfma_f32_16x16x32_bf16 v[108:111], v[132:135], v[164:167], v[108:111]
	v_mfma_f32_16x16x32_bf16 v[104:107], v[140:143], v[164:167], v[104:107]
	v_mfma_f32_16x16x32_bf16 v[100:103], v[132:135], v[172:175], v[100:103]
	s_barrier
	v_mfma_f32_16x16x32_bf16 v[96:99], v[140:143], v[172:175], v[96:99]
	s_setprio 0
	s_add_i32 s24, 0, 0x1c000
	s_add_i32 s25, s47, s28
	v_add_u32_e32 v204, s24, v217
	v_lshl_add_u64 v[208:209], v[208:209], 0, s[8:9]
	s_mov_b32 m0, s25
	ds_read_b128 v[192:195], v204
	ds_read_b128 v[196:199], v204 offset:1024
	ds_read_b128 v[200:203], v204 offset:2048
	ds_read_b128 v[204:207], v204 offset:3072
	global_load_lds_dwordx4 v[208:209], off
	v_lshl_add_u64 v[208:209], v[210:211], 0, s[8:9]
	s_add_i32 m0, s25, 0x2000
	s_nop 0
	global_load_lds_dwordx4 v[208:209], off
	s_waitcnt vmcnt(10)
	s_barrier
	s_waitcnt lgkmcnt(0)
	s_setprio 1
	s_waitcnt lgkmcnt(0)
	v_mfma_f32_16x16x32_bf16 v[60:63], v[192:195], v[144:147], v[60:63]
	v_mfma_f32_16x16x32_bf16 v[56:59], v[200:203], v[144:147], v[56:59]
	v_mfma_f32_16x16x32_bf16 v[52:55], v[192:195], v[152:155], v[52:55]
	v_mfma_f32_16x16x32_bf16 v[48:51], v[200:203], v[152:155], v[48:51]
	v_mfma_f32_16x16x32_bf16 v[44:47], v[192:195], v[160:163], v[44:47]
	v_mfma_f32_16x16x32_bf16 v[40:43], v[200:203], v[160:163], v[40:43]
	v_mfma_f32_16x16x32_bf16 v[36:39], v[192:195], v[168:171], v[36:39]
	v_mfma_f32_16x16x32_bf16 v[32:35], v[200:203], v[168:171], v[32:35]
	v_mfma_f32_16x16x32_bf16 v[60:63], v[196:199], v[148:151], v[60:63]
	v_mfma_f32_16x16x32_bf16 v[56:59], v[204:207], v[148:151], v[56:59]
	v_mfma_f32_16x16x32_bf16 v[52:55], v[196:199], v[156:159], v[52:55]
	v_mfma_f32_16x16x32_bf16 v[48:51], v[204:207], v[156:159], v[48:51]
	v_mfma_f32_16x16x32_bf16 v[44:47], v[196:199], v[164:167], v[44:47]
	v_mfma_f32_16x16x32_bf16 v[40:43], v[204:207], v[164:167], v[40:43]
	v_mfma_f32_16x16x32_bf16 v[36:39], v[196:199], v[172:175], v[36:39]
	s_barrier
; template <class Epi>
; __device__ __forceinline__ void gemm_phase(ldsp lds, const Gemm g, const StaticOrder& S, const Epi& E) {
;     ...
;         for (int t = 0; t < nt; t += 2) {
;             const bool last = (t == nt - 2);
;             const char* a1 = cA + (size_t)(t + 1) * kstep;
;             const char* a2 = last ? nA : cA + (size_t)(t + 2) * kstep; const char* b2 = last ? nB : cB + (size_t)(t + 2) * kstep;
;             const char* a3 = a2 + kstep; const char* b3 = b2 + kstep;
;             if constexpr (Epi::NPRE > 0) { if (last) E.pre(pre, cur, wr, fr); }
;             if constexpr (Epi::MID_T > 0) { if (t == Epi::MID_T) E.mid(acc, cur, wr, wc, fr, fq); }
;             PG8_LDB(B0, 0, 0); PG8_SCHED; PG8_LDA(At, 0, 0); PG8_STAGE(PG8_SA(1, 1), a1 + hstep, voffA);
;             PG8_WAIT_L(8); PG8_WAIT_V(10); PG8_BAR; PG8_WAIT_L(0); PG8_MMA(0, 0, At, B0); PG8_BAR; PG8_SCHED;
;             PG8_LDB(B1, 0, 1); PG8_STAGE(PG8_SB(0, 0), b2, voffB);
;             PG8_WAIT_V(10); PG8_BAR; PG8_WAIT_L(0); PG8_MMA(0, 1, At, B1); PG8_BAR;
;             PG8_LDA(At, 0, 1); PG8_STAGE(PG8_SA(0, 0), a2, voffA);
;             PG8_WAIT_V(10); PG8_BAR; PG8_WAIT_L(0); PG8_MMA(1, 0, At, B0); PG8_BAR; PG8_SCHED;
;             PG8_STAGE(PG8_SB(0, 1), b2 + hstep, voffB);
;             PG8_WAIT_V(10); PG8_BAR; PG8_MMA(1, 1, At, B1); PG8_BAR;
;             PG8_LDB(B0, 1, 0); PG8_SCHED; PG8_LDA(At, 1, 0); PG8_STAGE(PG8_SA(0, 1), a2 + hstep, voffA);
;             PG8_WAIT_L(8); PG8_WAIT_V(10); PG8_BAR; PG8_WAIT_L(0); PG8_MMA(0, 0, At, B0); PG8_BAR; PG8_SCHED;
;             PG8_LDB(B1, 1, 1); PG8_STAGE(PG8_SB(1, 0), b3, voffB);
;             PG8_WAIT_V(10); PG8_BAR; PG8_WAIT_L(0); PG8_MMA(0, 1, At, B1); PG8_BAR;
;             PG8_LDA(At, 1, 1); PG8_STAGE(PG8_SA(1, 0), a3, voffA);
;             PG8_WAIT_V(10); PG8_BAR; PG8_WAIT_L(0); PG8_MMA(1, 0, At, B0); PG8_BAR; PG8_SCHED;
;             PG8_STAGE(PG8_SB(1, 1), b3 + hstep, voffB);
;             PG8_WAIT_V(10); PG8_BAR; PG8_MMA(1, 1, At, B1); PG8_BAR;
;         }
;     __device__ __forceinline__ void operator()(EPI_ARGS) const {
;         const int row0 = u.pm * 256 + wr * 64 + fr, col0 = u.pn * 256 + wc * 32 + 8 * fq;
; #pragma unroll
;         for (int bj = 0; bj < 2; ++bj) { const f32x4 b0 = *(const f32x4*)(bias + col0 + bj * 128), b1 = *(const f32x4*)(bias + col0 + bj * 128 + 4);
;             u32x4 hw[2][4];
; #pragma unroll
	v_mfma_f32_16x16x32_bf16 v[32:35], v[204:207], v[172:175], v[32:35]
	s_setprio 0
	s_mov_b32 m0, s34
	v_lshl_add_u64 v[208:209], v[212:213], 0, s[8:9]
	ds_read_b128 v[144:147], v221 offset:49152
	ds_read_b128 v[148:151], v221 offset:50176
	ds_read_b128 v[152:155], v221 offset:51200
	ds_read_b128 v[156:159], v221 offset:52224
	ds_read_b128 v[160:163], v221 offset:53248
	ds_read_b128 v[164:167], v221 offset:54272
	ds_read_b128 v[168:171], v221 offset:55296
	ds_read_b128 v[172:175], v221 offset:56320
	global_load_lds_dwordx4 v[208:209], off
	v_lshl_add_u64 v[208:209], v[214:215], 0, s[8:9]
	s_mov_b32 m0, s35
	s_nop 0
	global_load_lds_dwordx4 v[208:209], off
	s_waitcnt vmcnt(10)
	s_barrier
	s_waitcnt lgkmcnt(0)
	s_setprio 1
	s_waitcnt lgkmcnt(0)
	v_mfma_f32_16x16x32_bf16 v[92:95], v[128:131], v[144:147], v[92:95]
	v_mfma_f32_16x16x32_bf16 v[88:91], v[136:139], v[144:147], v[88:91]
	v_mfma_f32_16x16x32_bf16 v[84:87], v[128:131], v[152:155], v[84:87]
	v_mfma_f32_16x16x32_bf16 v[80:83], v[136:139], v[152:155], v[80:83]
	v_mfma_f32_16x16x32_bf16 v[76:79], v[128:131], v[160:163], v[76:79]
	v_mfma_f32_16x16x32_bf16 v[72:75], v[136:139], v[160:163], v[72:75]
	v_mfma_f32_16x16x32_bf16 v[68:71], v[128:131], v[168:171], v[68:71]
	v_mfma_f32_16x16x32_bf16 v[64:67], v[136:139], v[168:171], v[64:67]
	v_mfma_f32_16x16x32_bf16 v[92:95], v[132:135], v[148:151], v[92:95]
	v_mfma_f32_16x16x32_bf16 v[88:91], v[140:143], v[148:151], v[88:91]
	v_mfma_f32_16x16x32_bf16 v[84:87], v[132:135], v[156:159], v[84:87]
	v_mfma_f32_16x16x32_bf16 v[80:83], v[140:143], v[156:159], v[80:83]
	v_mfma_f32_16x16x32_bf16 v[76:79], v[132:135], v[164:167], v[76:79]
	v_mfma_f32_16x16x32_bf16 v[72:75], v[140:143], v[164:167], v[72:75]
	v_mfma_f32_16x16x32_bf16 v[68:71], v[132:135], v[172:175], v[68:71]
	s_barrier
	v_mfma_f32_16x16x32_bf16 v[64:67], v[140:143], v[172:175], v[64:67]
	s_setprio 0
	s_add_u32 s22, s22, 0x20080
	s_addc_u32 s23, s23, 0
	s_add_i32 s24, s24, s28
	v_lshl_add_u64 v[128:129], s[22:23], 0, v[178:179]
	s_mov_b32 m0, s24
	s_nop 0
	global_load_lds_dwordx4 v[128:129], off
	v_lshl_add_u64 v[128:129], s[22:23], 0, v[182:183]
	s_add_i32 m0, s24, 0x2000
	s_nop 0
	global_load_lds_dwordx4 v[128:129], off
	s_waitcnt vmcnt(10)
	s_barrier
	s_setprio 1
	v_mfma_f32_16x16x32_bf16 v[28:31], v[192:195], v[144:147], v[28:31]
	v_mfma_f32_16x16x32_bf16 v[24:27], v[200:203], v[144:147], v[24:27]
	v_mfma_f32_16x16x32_bf16 v[20:23], v[192:195], v[152:155], v[20:23]
	v_mfma_f32_16x16x32_bf16 v[16:19], v[200:203], v[152:155], v[16:19]
	v_mfma_f32_16x16x32_bf16 v[12:15], v[192:195], v[160:163], v[12:15]
	v_mfma_f32_16x16x32_bf16 v[8:11], v[200:203], v[160:163], v[8:11]
	v_mfma_f32_16x16x32_bf16 v[4:7], v[192:195], v[168:171], v[4:7]
	v_mfma_f32_16x16x32_bf16 v[0:3], v[200:203], v[168:171], v[0:3]
	v_mfma_f32_16x16x32_bf16 v[28:31], v[196:199], v[148:151], v[28:31]
	v_mfma_f32_16x16x32_bf16 v[24:27], v[204:207], v[148:151], v[24:27]
	v_mfma_f32_16x16x32_bf16 v[20:23], v[196:199], v[156:159], v[20:23]
	v_mfma_f32_16x16x32_bf16 v[16:19], v[204:207], v[156:159], v[16:19]
	v_mfma_f32_16x16x32_bf16 v[12:15], v[196:199], v[164:167], v[12:15]
	v_mfma_f32_16x16x32_bf16 v[8:11], v[204:207], v[164:167], v[8:11]
	v_mfma_f32_16x16x32_bf16 v[4:7], v[196:199], v[172:175], v[4:7]
	s_barrier
	v_mfma_f32_16x16x32_bf16 v[0:3], v[204:207], v[172:175], v[0:3]
	s_setprio 0
	s_add_i32 s46, s46, 2
	s_add_u32 s20, s20, 0x100
	s_addc_u32 s21, s21, 0
	s_add_u32 s44, s44, 0x100
	s_addc_u32 s45, s45, 0
	s_cmp_gt_u32 s46, 5
	s_cbranch_scc0 .LBB0_574
	v_lshl_or_b32 v136, s41, 8, v218
	v_readlane_b32 s72, v246, 6
	v_ashrrev_i32_e32 v137, 31, v136
	v_readlane_b32 s86, v246, 20
	v_readlane_b32 s87, v246, 21
	v_lshl_add_u32 v140, s18, 8, v216
	v_ashrrev_i32_e32 v141, 31, v140
	v_lshl_add_u64 v[192:193], v[136:137], 2, s[86:87]
	v_lshlrev_b64 v[194:195], 1, v[136:137]
	global_load_dwordx4 v[132:135], v[192:193], off
	global_load_dwordx4 v[128:131], v[192:193], off offset:16
	v_lshlrev_b64 v[136:137], 10, v[140:141]
	v_lshl_add_u64 v[150:151], s[4:5], 0, v[194:195]
	v_lshl_add_u64 v[142:143], v[150:151], 0, v[136:137]
	global_load_dwordx4 v[136:139], v[142:143], off
	v_or_b32_e32 v210, 16, v140
	v_or_b32_e32 v206, 48, v140
	v_add_u32_e32 v204, 0x80, v140
	v_add_u32_e32 v198, 0xb0, v140
	v_ashrrev_i32_e32 v211, 31, v210
	v_ashrrev_i32_e32 v207, 31, v206
	v_ashrrev_i32_e32 v205, 31, v204
	v_ashrrev_i32_e32 v199, 31, v198
	v_lshlrev_b64 v[144:145], 10, v[210:211]
	v_lshlrev_b64 v[152:153], 10, v[206:207]
	v_lshlrev_b64 v[154:155], 10, v[204:205]
	v_lshlrev_b64 v[160:161], 10, v[198:199]
	v_lshl_add_u64 v[148:149], v[150:151], 0, v[144:145]
	v_lshl_add_u64 v[144:145], v[150:151], 0, v[152:153]
	v_lshl_add_u64 v[168:169], v[150:151], 0, v[154:155]
	v_lshl_add_u64 v[212:213], v[150:151], 0, v[160:161]
	global_load_dwordx4 v[152:155], v[148:149], off
	global_load_dwordx4 v[160:163], v[142:143], off offset:256
	v_or_b32_e32 v208, 32, v140
	v_add_u32_e32 v202, 0x90, v140
	v_add_u32_e32 v200, 0xa0, v140
	v_ashrrev_i32_e32 v209, 31, v208
	v_ashrrev_i32_e32 v203, 31, v202
	v_ashrrev_i32_e32 v201, 31, v200
	v_lshlrev_b64 v[146:147], 10, v[208:209]
	v_lshlrev_b64 v[156:157], 10, v[202:203]
	v_lshlrev_b64 v[158:159], 10, v[200:201]
	v_lshl_add_u64 v[146:147], v[150:151], 0, v[146:147]
	v_lshl_add_u64 v[166:167], v[150:151], 0, v[156:157]
	v_lshl_add_u64 v[164:165], v[150:151], 0, v[158:159]
	v_mov_b64_e32 v[196:197], s[6:7]
	s_and_b64 vcc, exec, s[2:3]
	s_mov_b32 s18, s12
	s_mov_b32 s41, s10
	s_mov_b64 s[22:23], s[16:17]
	v_readlane_b32 s73, v246, 7
	v_readlane_b32 s74, v246, 8
	v_readlane_b32 s75, v246, 9
	v_readlane_b32 s76, v246, 10
	v_readlane_b32 s77, v246, 11
	v_readlane_b32 s78, v246, 12
	v_readlane_b32 s79, v246, 13
	v_readlane_b32 s80, v246, 14
	v_readlane_b32 s81, v246, 15
	v_readlane_b32 s82, v246, 16
	v_readlane_b32 s83, v246, 17
	v_readlane_b32 s84, v246, 18
	v_readlane_b32 s85, v246, 19
	s_waitcnt vmcnt(0)
; __device__ __forceinline__ float sigm(float x) { return __builtin_amdgcn_rcpf(1.0f + __builtin_amdgcn_exp2f(-1.4426950408889634f * x)); }
;     __device__ __forceinline__ void operator()(EPI_ARGS) const {
;         const int row0 = u.pm * 256 + wr * 64 + fr, col0 = u.pn * 256 + wc * 32 + 8 * fq;
; #pragma unroll
;         for (int bj = 0; bj < 2; ++bj) { const f32x4 b0 = *(const f32x4*)(bias + col0 + bj * 128), b1 = *(const f32x4*)(bias + col0 + bj * 128 + 4);
;             u32x4 hw[2][4];
; #pragma unroll
;             for (int ai = 0; ai < 2; ++ai)
; #pragma unroll
;                 for (int m = 0; m < 4; ++m) hw[ai][m] = *(const u32x4*)(H + (size_t)(row0 + ai * 128 + m * 16) * 512 + col0 + bj * 128);
; #pragma unroll
;             for (int ai = 0; ai < 2; ++ai)
; #pragma unroll
;                 for (int m = 0; m < 4; ++m) { const size_t off = (size_t)(row0 + ai * 128 + m * 16) * 512 + col0 + bj * 128;
;                     f32x4 h0, h1; unpack8(hw[ai][m], h0, h1);
;                     f32x4 v0 = acc[ai][bj][m][0] + b0, v1 = acc[ai][bj][m][1] + b1;
; #pragma unroll
;                     for (int j = 0; j < 4; ++j) { v0[j] = h0[j] * sigm(v0[j]); v1[j] = h1[j] * sigm(v1[j]); }
;                     *(u32x4*)(O + (size_t)(row0 + ai * 128 + m * 16) * KAB + 1024 + col0 + bj * 128) = pack8(v0, v1); } }
;     }
	v_pk_add_f32 v[124:125], v[124:125], v[132:133]
	v_pk_add_f32 v[126:127], v[126:127], v[134:135]
	v_pk_add_f32 v[122:123], v[122:123], v[130:131]
	v_pk_add_f32 v[120:121], v[120:121], v[128:129]
	v_mul_f32_e32 v124, 0xbfb8aa3b, v124
	v_mul_f32_e32 v125, 0xbfb8aa3b, v125
	v_mul_f32_e32 v120, 0xbfb8aa3b, v120
	v_mul_f32_e32 v141, 0xbfb8aa3b, v121
	v_mul_f32_e32 v126, 0xbfb8aa3b, v126
	v_mul_f32_e32 v142, 0xbfb8aa3b, v122
	v_mul_f32_e32 v127, 0xbfb8aa3b, v127
	v_mul_f32_e32 v143, 0xbfb8aa3b, v123
	v_exp_f32_e32 v150, v124
	v_exp_f32_e32 v156, v125
	v_exp_f32_e32 v151, v120
	v_lshlrev_b32_e32 v120, 16, v136
	v_and_b32_e32 v121, 0xffff0000, v136
	v_exp_f32_e32 v136, v141
	v_lshlrev_b32_e32 v122, 16, v138
	v_and_b32_e32 v123, 0xffff0000, v138
	v_exp_f32_e32 v138, v126
	v_exp_f32_e32 v141, v142
	v_exp_f32_e32 v142, v127
	v_lshlrev_b32_e32 v124, 16, v137
	v_and_b32_e32 v125, 0xffff0000, v137
	v_exp_f32_e32 v137, v143
	v_lshlrev_b32_e32 v126, 16, v139
	v_and_b32_e32 v127, 0xffff0000, v139
	v_add_f32_e32 v139, 1.0, v150
	v_add_f32_e32 v150, 1.0, v156
	v_add_f32_e32 v143, 1.0, v151
	v_add_f32_e32 v151, 1.0, v136
	v_add_f32_e32 v156, 1.0, v138
	v_add_f32_e32 v141, 1.0, v141
	v_add_f32_e32 v157, 1.0, v142
	v_add_f32_e32 v158, 1.0, v137
	v_rcp_f32_e32 v136, v139
	v_rcp_f32_e32 v137, v150
	v_rcp_f32_e32 v138, v143
	v_rcp_f32_e32 v139, v151
	v_rcp_f32_e32 v142, v156
	v_rcp_f32_e32 v150, v141
	v_rcp_f32_e32 v143, v157
	v_rcp_f32_e32 v151, v158
	v_pk_mul_f32 v[120:121], v[136:137], v[120:121]
	v_pk_mul_f32 v[122:123], v[138:139], v[122:123]
	v_pk_mul_f32 v[124:125], v[142:143], v[124:125]
	v_pk_mul_f32 v[126:127], v[150:151], v[126:127]
	v_cvt_pk_bf16_f32 v224, v120, v121
	v_mad_i64_i32 v[120:121], s[20:21], v140, s40, v[196:197]
	v_cvt_pk_bf16_f32 v225, v124, v125
	v_cvt_pk_bf16_f32 v226, v122, v123
	v_cvt_pk_bf16_f32 v227, v126, v127
	v_lshl_add_u64 v[214:215], v[120:121], 0, v[194:195]
	global_load_dwordx4 v[156:159], v[148:149], off offset:256
	global_load_dwordx4 v[228:231], v[146:147], off
	s_nop 0
	global_load_dwordx4 v[148:151], v[146:147], off offset:256
	global_load_dwordx4 v[232:235], v[144:145], off
	s_nop 0
	global_load_dwordx4 v[144:147], v[144:145], off offset:256
	s_nop 0
	global_load_dwordx4 v[236:239], v[168:169], off
	global_load_dwordx4 v[140:143], v[168:169], off offset:256
	global_load_dwordx4 v[172:175], v[166:167], off
	global_load_dwordx4 v[136:139], v[166:167], off offset:256
	s_nop 0
	global_load_dwordx4 v[168:171], v[164:165], off
	global_load_dwordx4 v[124:127], v[164:165], off offset:256
	s_nop 0
	global_load_dwordx4 v[164:167], v[212:213], off
	global_load_dwordx4 v[120:123], v[212:213], off offset:256
	v_pk_add_f32 v[116:117], v[116:117], v[132:133]
	v_pk_add_f32 v[114:115], v[114:115], v[130:131]
	v_mul_f32_e32 v116, 0xbfb8aa3b, v116
	v_mul_f32_e32 v117, 0xbfb8aa3b, v117
	v_exp_f32_e32 v116, v116
	v_exp_f32_e32 v117, v117
	v_pk_add_f32 v[118:119], v[118:119], v[134:135]
	v_pk_add_f32 v[112:113], v[112:113], v[128:129]
	v_add_f32_e32 v116, 1.0, v116
	v_add_f32_e32 v117, 1.0, v117
	v_rcp_f32_e32 v116, v116
	v_rcp_f32_e32 v117, v117
	v_mul_f32_e32 v114, 0xbfb8aa3b, v114
	v_mul_f32_e32 v112, 0xbfb8aa3b, v112
	v_mul_f32_e32 v113, 0xbfb8aa3b, v113
	v_lshlrev_b32_e32 v212, 16, v152
	v_and_b32_e32 v213, 0xffff0000, v152
	v_mul_f32_e32 v118, 0xbfb8aa3b, v118
	v_exp_f32_e32 v152, v114
	v_mul_f32_e32 v114, 0xbfb8aa3b, v119
	v_exp_f32_e32 v112, v112
	v_exp_f32_e32 v113, v113
	v_exp_f32_e32 v118, v118
	v_exp_f32_e32 v119, v114
	v_mul_f32_e32 v115, 0xbfb8aa3b, v115
	v_pk_mul_f32 v[116:117], v[116:117], v[212:213]
	v_lshlrev_b32_e32 v212, 16, v154
	v_and_b32_e32 v213, 0xffff0000, v154
	v_exp_f32_e32 v154, v115
	v_pk_add_f32 v[108:109], v[108:109], v[132:133]
	v_pk_add_f32 v[104:105], v[104:105], v[128:129]
	v_mul_f32_e32 v108, 0xbfb8aa3b, v108
	v_mul_f32_e32 v109, 0xbfb8aa3b, v109
	v_add_f32_e32 v112, 1.0, v112
	v_add_f32_e32 v113, 1.0, v113
	v_add_f32_e32 v118, 1.0, v118
	v_add_f32_e32 v119, 1.0, v119
	v_exp_f32_e32 v108, v108
	v_mul_f32_e32 v104, 0xbfb8aa3b, v104
	v_exp_f32_e32 v109, v109
	v_mul_f32_e32 v105, 0xbfb8aa3b, v105
	v_rcp_f32_e32 v112, v112
	v_rcp_f32_e32 v113, v113
	v_rcp_f32_e32 v114, v118
	v_add_f32_e32 v118, 1.0, v152
	v_rcp_f32_e32 v115, v119
	v_add_f32_e32 v119, 1.0, v154
	v_exp_f32_e32 v104, v104
	v_exp_f32_e32 v105, v105
	v_rcp_f32_e32 v118, v118
	v_rcp_f32_e32 v119, v119
	v_lshlrev_b32_e32 v152, 16, v153
	v_and_b32_e32 v153, 0xffff0000, v153
	v_add_f32_e32 v108, 1.0, v108
	v_add_f32_e32 v109, 1.0, v109
	v_pk_mul_f32 v[112:113], v[112:113], v[212:213]
	v_pk_mul_f32 v[152:153], v[114:115], v[152:153]
	v_lshlrev_b32_e32 v114, 16, v155
	v_and_b32_e32 v115, 0xffff0000, v155
	v_rcp_f32_e32 v108, v108
	v_add_f32_e32 v104, 1.0, v104
	v_rcp_f32_e32 v109, v109
	v_add_f32_e32 v105, 1.0, v105
	v_pk_mul_f32 v[118:119], v[118:119], v[114:115]
	v_cvt_pk_bf16_f32 v114, v116, v117
	v_cvt_pk_bf16_f32 v116, v112, v113
	v_mad_i64_i32 v[112:113], s[20:21], v210, s40, v[196:197]
	v_rcp_f32_e32 v104, v104
	v_rcp_f32_e32 v105, v105
	v_cvt_pk_bf16_f32 v115, v152, v153
	v_cvt_pk_bf16_f32 v117, v118, v119
	v_lshl_add_u64 v[112:113], v[112:113], 0, v[194:195]
	global_store_dwordx4 v[112:113], v[114:117], off offset:2048
	v_pk_add_f32 v[106:107], v[106:107], v[130:131]
	v_pk_add_f32 v[110:111], v[110:111], v[134:135]
	s_waitcnt vmcnt(0)
; __device__ __forceinline__ float sigm(float x) { return __builtin_amdgcn_rcpf(1.0f + __builtin_amdgcn_exp2f(-1.4426950408889634f * x)); }
;     __device__ __forceinline__ void operator()(EPI_ARGS) const {
;         const int row0 = u.pm * 256 + wr * 64 + fr, col0 = u.pn * 256 + wc * 32 + 8 * fq;
; #pragma unroll
;         for (int bj = 0; bj < 2; ++bj) { const f32x4 b0 = *(const f32x4*)(bias + col0 + bj * 128), b1 = *(const f32x4*)(bias + col0 + bj * 128 + 4);
;             u32x4 hw[2][4];
; #pragma unroll
;             for (int ai = 0; ai < 2; ++ai)
; #pragma unroll
;                 for (int m = 0; m < 4; ++m) hw[ai][m] = *(const u32x4*)(H + (size_t)(row0 + ai * 128 + m * 16) * 512 + col0 + bj * 128);
; #pragma unroll
;             for (int ai = 0; ai < 2; ++ai)
; #pragma unroll
;                 for (int m = 0; m < 4; ++m) { const size_t off = (size_t)(row0 + ai * 128 + m * 16) * 512 + col0 + bj * 128;
;                     f32x4 h0, h1; unpack8(hw[ai][m], h0, h1);
;                     f32x4 v0 = acc[ai][bj][m][0] + b0, v1 = acc[ai][bj][m][1] + b1;
; #pragma unroll
;                     for (int j = 0; j < 4; ++j) { v0[j] = h0[j] * sigm(v0[j]); v1[j] = h1[j] * sigm(v1[j]); }
;                     *(u32x4*)(O + (size_t)(row0 + ai * 128 + m * 16) * KAB + 1024 + col0 + bj * 128) = pack8(v0, v1); } }
;     }
	v_lshlrev_b32_e32 v114, 16, v228
	v_and_b32_e32 v115, 0xffff0000, v228
	v_pk_mul_f32 v[108:109], v[108:109], v[114:115]
	v_lshlrev_b32_e32 v114, 16, v230
	v_and_b32_e32 v115, 0xffff0000, v230
	v_mul_f32_e32 v106, 0xbfb8aa3b, v106
	v_mul_f32_e32 v110, 0xbfb8aa3b, v110
	v_pk_mul_f32 v[104:105], v[104:105], v[114:115]
	v_exp_f32_e32 v114, v106
	v_mul_f32_e32 v106, 0xbfb8aa3b, v111
	v_exp_f32_e32 v110, v110
	v_exp_f32_e32 v111, v106
	v_mul_f32_e32 v107, 0xbfb8aa3b, v107
	v_exp_f32_e32 v116, v107
	v_pk_add_f32 v[100:101], v[100:101], v[132:133]
	v_pk_add_f32 v[96:97], v[96:97], v[128:129]
	v_mul_f32_e32 v100, 0xbfb8aa3b, v100
	v_mul_f32_e32 v101, 0xbfb8aa3b, v101
	v_add_f32_e32 v110, 1.0, v110
	v_add_f32_e32 v111, 1.0, v111
	v_exp_f32_e32 v100, v100
	v_mul_f32_e32 v96, 0xbfb8aa3b, v96
	v_exp_f32_e32 v101, v101
	v_mul_f32_e32 v97, 0xbfb8aa3b, v97
	v_rcp_f32_e32 v106, v110
	v_add_f32_e32 v110, 1.0, v114
	v_rcp_f32_e32 v107, v111
	v_add_f32_e32 v111, 1.0, v116
	v_exp_f32_e32 v96, v96
	v_exp_f32_e32 v97, v97
	v_rcp_f32_e32 v110, v110
	v_rcp_f32_e32 v111, v111
	v_lshlrev_b32_e32 v114, 16, v229
	v_and_b32_e32 v115, 0xffff0000, v229
	v_add_f32_e32 v100, 1.0, v100
	v_add_f32_e32 v101, 1.0, v101
	v_pk_mul_f32 v[114:115], v[106:107], v[114:115]
	v_lshlrev_b32_e32 v106, 16, v231
	v_and_b32_e32 v107, 0xffff0000, v231
	v_rcp_f32_e32 v100, v100
	v_add_f32_e32 v96, 1.0, v96
	v_rcp_f32_e32 v101, v101
	v_add_f32_e32 v97, 1.0, v97
	v_pk_mul_f32 v[110:111], v[110:111], v[106:107]
	v_cvt_pk_bf16_f32 v106, v108, v109
	v_cvt_pk_bf16_f32 v108, v104, v105
	v_mad_i64_i32 v[104:105], s[20:21], v208, s40, v[196:197]
	v_rcp_f32_e32 v96, v96
	v_rcp_f32_e32 v97, v97
	v_cvt_pk_bf16_f32 v107, v114, v115
	v_cvt_pk_bf16_f32 v109, v110, v111
	v_lshl_add_u64 v[104:105], v[104:105], 0, v[194:195]
	global_store_dwordx4 v[104:105], v[106:109], off offset:2048
	v_pk_add_f32 v[98:99], v[98:99], v[130:131]
	v_pk_add_f32 v[102:103], v[102:103], v[134:135]
	v_lshlrev_b32_e32 v106, 16, v232
	v_and_b32_e32 v107, 0xffff0000, v232
	v_pk_mul_f32 v[100:101], v[100:101], v[106:107]
	v_lshlrev_b32_e32 v106, 16, v234
	v_and_b32_e32 v107, 0xffff0000, v234
	v_mul_f32_e32 v98, 0xbfb8aa3b, v98
	v_mul_f32_e32 v102, 0xbfb8aa3b, v102
	v_pk_mul_f32 v[96:97], v[96:97], v[106:107]
	v_exp_f32_e32 v106, v98
	v_mul_f32_e32 v98, 0xbfb8aa3b, v103
	v_exp_f32_e32 v102, v102
	v_exp_f32_e32 v103, v98
	v_mul_f32_e32 v99, 0xbfb8aa3b, v99
	v_exp_f32_e32 v108, v99
	v_pk_add_f32 v[92:93], v[92:93], v[132:133]
	v_pk_add_f32 v[88:89], v[88:89], v[128:129]
	v_mul_f32_e32 v92, 0xbfb8aa3b, v92
	v_mul_f32_e32 v93, 0xbfb8aa3b, v93
	v_add_f32_e32 v102, 1.0, v102
	v_add_f32_e32 v103, 1.0, v103
	v_exp_f32_e32 v92, v92
	v_mul_f32_e32 v88, 0xbfb8aa3b, v88
	v_exp_f32_e32 v93, v93
	v_mul_f32_e32 v89, 0xbfb8aa3b, v89
	v_rcp_f32_e32 v98, v102
	v_add_f32_e32 v102, 1.0, v106
	v_rcp_f32_e32 v99, v103
	v_add_f32_e32 v103, 1.0, v108
	v_exp_f32_e32 v88, v88
	v_exp_f32_e32 v89, v89
	v_rcp_f32_e32 v102, v102
	v_rcp_f32_e32 v103, v103
	v_lshlrev_b32_e32 v106, 16, v233
	v_and_b32_e32 v107, 0xffff0000, v233
	v_add_f32_e32 v92, 1.0, v92
	v_add_f32_e32 v93, 1.0, v93
	v_pk_mul_f32 v[106:107], v[98:99], v[106:107]
	v_lshlrev_b32_e32 v98, 16, v235
	v_and_b32_e32 v99, 0xffff0000, v235
	v_rcp_f32_e32 v92, v92
	v_add_f32_e32 v88, 1.0, v88
	v_rcp_f32_e32 v93, v93
	v_add_f32_e32 v89, 1.0, v89
	v_pk_mul_f32 v[102:103], v[102:103], v[98:99]
	v_cvt_pk_bf16_f32 v98, v100, v101
	v_cvt_pk_bf16_f32 v100, v96, v97
	v_mad_i64_i32 v[96:97], s[20:21], v206, s40, v[196:197]
	v_rcp_f32_e32 v88, v88
	v_rcp_f32_e32 v89, v89
	v_cvt_pk_bf16_f32 v99, v106, v107
	v_cvt_pk_bf16_f32 v101, v102, v103
	v_lshl_add_u64 v[96:97], v[96:97], 0, v[194:195]
	global_store_dwordx4 v[96:97], v[98:101], off offset:2048
	v_pk_add_f32 v[90:91], v[90:91], v[130:131]
	v_pk_add_f32 v[94:95], v[94:95], v[134:135]
	v_lshlrev_b32_e32 v98, 16, v236
	v_and_b32_e32 v99, 0xffff0000, v236
	v_pk_mul_f32 v[92:93], v[92:93], v[98:99]
	v_lshlrev_b32_e32 v98, 16, v238
	v_and_b32_e32 v99, 0xffff0000, v238
	v_mul_f32_e32 v90, 0xbfb8aa3b, v90
	v_mul_f32_e32 v94, 0xbfb8aa3b, v94
	v_pk_mul_f32 v[88:89], v[88:89], v[98:99]
	v_exp_f32_e32 v98, v90
	v_mul_f32_e32 v90, 0xbfb8aa3b, v95
	v_exp_f32_e32 v94, v94
	v_exp_f32_e32 v95, v90
	v_mul_f32_e32 v91, 0xbfb8aa3b, v91
	v_exp_f32_e32 v100, v91
	v_pk_add_f32 v[84:85], v[84:85], v[132:133]
	v_pk_add_f32 v[80:81], v[80:81], v[128:129]
	v_mul_f32_e32 v84, 0xbfb8aa3b, v84
	v_mul_f32_e32 v85, 0xbfb8aa3b, v85
	v_add_f32_e32 v94, 1.0, v94
	v_add_f32_e32 v95, 1.0, v95
	v_exp_f32_e32 v84, v84
	v_mul_f32_e32 v80, 0xbfb8aa3b, v80
	v_exp_f32_e32 v85, v85
	v_mul_f32_e32 v81, 0xbfb8aa3b, v81
	v_rcp_f32_e32 v90, v94
	v_add_f32_e32 v94, 1.0, v98
	v_rcp_f32_e32 v91, v95
	v_add_f32_e32 v95, 1.0, v100
	v_exp_f32_e32 v80, v80
	v_exp_f32_e32 v81, v81
	v_rcp_f32_e32 v94, v94
	v_rcp_f32_e32 v95, v95
	v_lshlrev_b32_e32 v98, 16, v237
	v_and_b32_e32 v99, 0xffff0000, v237
	v_add_f32_e32 v84, 1.0, v84
	v_add_f32_e32 v85, 1.0, v85
	v_pk_mul_f32 v[98:99], v[90:91], v[98:99]
	v_lshlrev_b32_e32 v90, 16, v239
	v_and_b32_e32 v91, 0xffff0000, v239
	v_rcp_f32_e32 v84, v84
	v_add_f32_e32 v80, 1.0, v80
	v_rcp_f32_e32 v85, v85
	v_add_f32_e32 v81, 1.0, v81
	v_pk_mul_f32 v[94:95], v[94:95], v[90:91]
	v_cvt_pk_bf16_f32 v90, v92, v93
	v_cvt_pk_bf16_f32 v92, v88, v89
	v_mad_i64_i32 v[88:89], s[20:21], v204, s40, v[196:197]
	v_rcp_f32_e32 v80, v80
	v_rcp_f32_e32 v81, v81
	v_cvt_pk_bf16_f32 v91, v98, v99
	v_cvt_pk_bf16_f32 v93, v94, v95
	v_lshl_add_u64 v[88:89], v[88:89], 0, v[194:195]
	global_store_dwordx4 v[88:89], v[90:93], off offset:2048
	v_pk_add_f32 v[82:83], v[82:83], v[130:131]
; __device__ __forceinline__ float sigm(float x) { return __builtin_amdgcn_rcpf(1.0f + __builtin_amdgcn_exp2f(-1.4426950408889634f * x)); }
;     __device__ __forceinline__ void operator()(EPI_ARGS) const {
;         const int row0 = u.pm * 256 + wr * 64 + fr, col0 = u.pn * 256 + wc * 32 + 8 * fq;
; #pragma unroll
;         for (int bj = 0; bj < 2; ++bj) { const f32x4 b0 = *(const f32x4*)(bias + col0 + bj * 128), b1 = *(const f32x4*)(bias + col0 + bj * 128 + 4);
;             u32x4 hw[2][4];
; #pragma unroll
;             for (int ai = 0; ai < 2; ++ai)
; #pragma unroll
;                 for (int m = 0; m < 4; ++m) hw[ai][m] = *(const u32x4*)(H + (size_t)(row0 + ai * 128 + m * 16) * 512 + col0 + bj * 128);
; #pragma unroll
;             for (int ai = 0; ai < 2; ++ai)
; #pragma unroll
;                 for (int m = 0; m < 4; ++m) { const size_t off = (size_t)(row0 + ai * 128 + m * 16) * 512 + col0 + bj * 128;
;                     f32x4 h0, h1; unpack8(hw[ai][m], h0, h1);
;                     f32x4 v0 = acc[ai][bj][m][0] + b0, v1 = acc[ai][bj][m][1] + b1;
; #pragma unroll
;                     for (int j = 0; j < 4; ++j) { v0[j] = h0[j] * sigm(v0[j]); v1[j] = h1[j] * sigm(v1[j]); }
;                     *(u32x4*)(O + (size_t)(row0 + ai * 128 + m * 16) * KAB + 1024 + col0 + bj * 128) = pack8(v0, v1); } }
;     }
	v_pk_add_f32 v[86:87], v[86:87], v[134:135]
	v_lshlrev_b32_e32 v90, 16, v172
	v_and_b32_e32 v91, 0xffff0000, v172
	v_pk_mul_f32 v[84:85], v[84:85], v[90:91]
	v_lshlrev_b32_e32 v90, 16, v174
	v_and_b32_e32 v91, 0xffff0000, v174
	v_mul_f32_e32 v82, 0xbfb8aa3b, v82
	v_mul_f32_e32 v86, 0xbfb8aa3b, v86
	v_pk_mul_f32 v[80:81], v[80:81], v[90:91]
	v_exp_f32_e32 v90, v82
	v_mul_f32_e32 v82, 0xbfb8aa3b, v87
	v_exp_f32_e32 v86, v86
	v_exp_f32_e32 v87, v82
	v_mul_f32_e32 v83, 0xbfb8aa3b, v83
	v_exp_f32_e32 v92, v83
	v_pk_add_f32 v[76:77], v[76:77], v[132:133]
	v_pk_add_f32 v[72:73], v[72:73], v[128:129]
	v_mul_f32_e32 v76, 0xbfb8aa3b, v76
	v_mul_f32_e32 v77, 0xbfb8aa3b, v77
	v_add_f32_e32 v86, 1.0, v86
	v_add_f32_e32 v87, 1.0, v87
	v_exp_f32_e32 v76, v76
	v_mul_f32_e32 v72, 0xbfb8aa3b, v72
	v_exp_f32_e32 v77, v77
	v_mul_f32_e32 v73, 0xbfb8aa3b, v73
	v_rcp_f32_e32 v82, v86
	v_add_f32_e32 v86, 1.0, v90
	v_rcp_f32_e32 v83, v87
	v_add_f32_e32 v87, 1.0, v92
	v_exp_f32_e32 v72, v72
	v_exp_f32_e32 v73, v73
	v_rcp_f32_e32 v86, v86
	v_rcp_f32_e32 v87, v87
	v_lshlrev_b32_e32 v90, 16, v173
	v_and_b32_e32 v91, 0xffff0000, v173
	v_add_f32_e32 v76, 1.0, v76
	v_add_f32_e32 v77, 1.0, v77
	v_pk_mul_f32 v[90:91], v[82:83], v[90:91]
	v_lshlrev_b32_e32 v82, 16, v175
	v_and_b32_e32 v83, 0xffff0000, v175
	v_rcp_f32_e32 v76, v76
	v_add_f32_e32 v72, 1.0, v72
	v_rcp_f32_e32 v77, v77
	v_add_f32_e32 v73, 1.0, v73
	v_pk_mul_f32 v[86:87], v[86:87], v[82:83]
	v_cvt_pk_bf16_f32 v82, v84, v85
	v_cvt_pk_bf16_f32 v84, v80, v81
	v_mad_i64_i32 v[80:81], s[20:21], v202, s40, v[196:197]
	v_rcp_f32_e32 v72, v72
	v_rcp_f32_e32 v73, v73
	v_cvt_pk_bf16_f32 v83, v90, v91
	v_cvt_pk_bf16_f32 v85, v86, v87
	v_lshl_add_u64 v[80:81], v[80:81], 0, v[194:195]
	global_store_dwordx4 v[80:81], v[82:85], off offset:2048
	v_pk_add_f32 v[74:75], v[74:75], v[130:131]
	v_pk_add_f32 v[78:79], v[78:79], v[134:135]
	v_lshlrev_b32_e32 v82, 16, v168
	v_and_b32_e32 v83, 0xffff0000, v168
	v_pk_mul_f32 v[76:77], v[76:77], v[82:83]
	v_lshlrev_b32_e32 v82, 16, v170
	v_and_b32_e32 v83, 0xffff0000, v170
	v_mul_f32_e32 v74, 0xbfb8aa3b, v74
	v_mul_f32_e32 v78, 0xbfb8aa3b, v78
	v_pk_mul_f32 v[72:73], v[72:73], v[82:83]
	v_exp_f32_e32 v82, v74
	v_mul_f32_e32 v74, 0xbfb8aa3b, v79
	v_exp_f32_e32 v78, v78
	v_exp_f32_e32 v79, v74
	v_mul_f32_e32 v75, 0xbfb8aa3b, v75
	v_exp_f32_e32 v84, v75
	v_pk_add_f32 v[68:69], v[68:69], v[132:133]
	v_pk_add_f32 v[64:65], v[64:65], v[128:129]
	v_mul_f32_e32 v68, 0xbfb8aa3b, v68
	v_mul_f32_e32 v69, 0xbfb8aa3b, v69
	v_exp_f32_e32 v68, v68
	v_mul_f32_e32 v64, 0xbfb8aa3b, v64
	v_exp_f32_e32 v69, v69
	v_mul_f32_e32 v65, 0xbfb8aa3b, v65
	v_add_f32_e32 v78, 1.0, v78
	v_add_f32_e32 v79, 1.0, v79
	v_exp_f32_e32 v64, v64
	v_exp_f32_e32 v65, v65
	v_rcp_f32_e32 v74, v78
	v_add_f32_e32 v78, 1.0, v82
	v_rcp_f32_e32 v75, v79
	v_add_f32_e32 v79, 1.0, v84
	v_rcp_f32_e32 v78, v78
	v_rcp_f32_e32 v79, v79
	v_add_f32_e32 v68, 1.0, v68
	v_add_f32_e32 v69, 1.0, v69
	v_lshlrev_b32_e32 v82, 16, v169
	v_and_b32_e32 v83, 0xffff0000, v169
	v_rcp_f32_e32 v68, v68
	v_add_f32_e32 v64, 1.0, v64
	v_rcp_f32_e32 v69, v69
	v_add_f32_e32 v65, 1.0, v65
	v_pk_mul_f32 v[74:75], v[74:75], v[82:83]
	v_lshlrev_b32_e32 v82, 16, v171
	v_and_b32_e32 v83, 0xffff0000, v171
	v_pk_add_f32 v[70:71], v[70:71], v[134:135]
	v_rcp_f32_e32 v64, v64
	v_rcp_f32_e32 v65, v65
	v_pk_mul_f32 v[82:83], v[78:79], v[82:83]
	v_cvt_pk_bf16_f32 v78, v72, v73
	v_mad_i64_i32 v[72:73], s[20:21], v200, s40, v[196:197]
	v_mul_f32_e32 v70, 0xbfb8aa3b, v70
	v_cvt_pk_bf16_f32 v76, v76, v77
	v_cvt_pk_bf16_f32 v77, v74, v75
	v_lshl_add_u64 v[74:75], v[72:73], 0, v[194:195]
	v_lshlrev_b32_e32 v72, 16, v164
	v_and_b32_e32 v73, 0xffff0000, v164
	v_exp_f32_e32 v70, v70
	v_pk_add_f32 v[66:67], v[66:67], v[130:131]
	v_pk_mul_f32 v[68:69], v[68:69], v[72:73]
	v_lshlrev_b32_e32 v72, 16, v166
	v_and_b32_e32 v73, 0xffff0000, v166
	v_pk_mul_f32 v[72:73], v[64:65], v[72:73]
	v_mul_f32_e32 v65, 0xbfb8aa3b, v66
	v_exp_f32_e32 v65, v65
	v_mul_f32_e32 v66, 0xbfb8aa3b, v71
	v_add_f32_e32 v64, 1.0, v70
	v_exp_f32_e32 v70, v66
	v_mul_f32_e32 v67, 0xbfb8aa3b, v67
	v_exp_f32_e32 v67, v67
	v_add_f32_e32 v65, 1.0, v65
	v_rcp_f32_e32 v66, v65
	v_add_f32_e32 v65, 1.0, v70
	v_rcp_f32_e32 v64, v64
	v_rcp_f32_e32 v65, v65
	v_add_f32_e32 v67, 1.0, v67
	v_rcp_f32_e32 v67, v67
	v_lshlrev_b32_e32 v70, 16, v165
	v_and_b32_e32 v71, 0xffff0000, v165
	v_cvt_pk_bf16_f32 v79, v82, v83
	v_pk_mul_f32 v[70:71], v[64:65], v[70:71]
	v_lshlrev_b32_e32 v64, 16, v167
	v_and_b32_e32 v65, 0xffff0000, v167
	global_store_dwordx4 v[74:75], v[76:79], off offset:2048
	global_store_dwordx4 v[214:215], v[224:227], off offset:2048
	s_nop 0
	v_pk_mul_f32 v[76:77], v[66:67], v[64:65]
	v_cvt_pk_bf16_f32 v64, v68, v69
	v_mad_i64_i32 v[68:69], s[20:21], v198, s40, v[196:197]
	v_cvt_pk_bf16_f32 v65, v70, v71
	v_cvt_pk_bf16_f32 v66, v72, v73
	v_cvt_pk_bf16_f32 v67, v76, v77
	v_lshl_add_u64 v[72:73], v[68:69], 0, v[194:195]
	global_store_dwordx4 v[72:73], v[64:67], off offset:2048
	global_load_dwordx4 v[68:71], v[192:193], off offset:512
	s_nop 0
	global_load_dwordx4 v[64:67], v[192:193], off offset:528
	v_lshlrev_b32_e32 v76, 16, v160
	v_and_b32_e32 v77, 0xffff0000, v160
	s_mov_b64 s[20:21], s[14:15]
	s_waitcnt vmcnt(0)
; __device__ __forceinline__ float sigm(float x) { return __builtin_amdgcn_rcpf(1.0f + __builtin_amdgcn_exp2f(-1.4426950408889634f * x)); }
;     __device__ __forceinline__ void operator()(EPI_ARGS) const {
;         const int row0 = u.pm * 256 + wr * 64 + fr, col0 = u.pn * 256 + wc * 32 + 8 * fq;
; #pragma unroll
;         for (int bj = 0; bj < 2; ++bj) { const f32x4 b0 = *(const f32x4*)(bias + col0 + bj * 128), b1 = *(const f32x4*)(bias + col0 + bj * 128 + 4);
;             u32x4 hw[2][4];
; #pragma unroll
;             for (int ai = 0; ai < 2; ++ai)
; #pragma unroll
;                 for (int m = 0; m < 4; ++m) hw[ai][m] = *(const u32x4*)(H + (size_t)(row0 + ai * 128 + m * 16) * 512 + col0 + bj * 128);
; #pragma unroll
;             for (int ai = 0; ai < 2; ++ai)
; #pragma unroll
;                 for (int m = 0; m < 4; ++m) { const size_t off = (size_t)(row0 + ai * 128 + m * 16) * 512 + col0 + bj * 128;
;                     f32x4 h0, h1; unpack8(hw[ai][m], h0, h1);
;                     f32x4 v0 = acc[ai][bj][m][0] + b0, v1 = acc[ai][bj][m][1] + b1;
; #pragma unroll
;                     for (int j = 0; j < 4; ++j) { v0[j] = h0[j] * sigm(v0[j]); v1[j] = h1[j] * sigm(v1[j]); }
;                     *(u32x4*)(O + (size_t)(row0 + ai * 128 + m * 16) * KAB + 1024 + col0 + bj * 128) = pack8(v0, v1); } }
;     }
	v_pk_add_f32 v[60:61], v[60:61], v[68:69]
	s_nop 0
	v_mul_f32_e32 v60, 0xbfb8aa3b, v60
	v_pk_add_f32 v[56:57], v[56:57], v[64:65]
	v_mul_f32_e32 v61, 0xbfb8aa3b, v61
	v_exp_f32_e32 v60, v60
	v_mul_f32_e32 v56, 0xbfb8aa3b, v56
	v_exp_f32_e32 v61, v61
	v_mul_f32_e32 v57, 0xbfb8aa3b, v57
	v_exp_f32_e32 v56, v56
	v_exp_f32_e32 v57, v57
	v_add_f32_e32 v60, 1.0, v60
	v_add_f32_e32 v61, 1.0, v61
	v_rcp_f32_e32 v60, v60
	v_add_f32_e32 v56, 1.0, v56
	v_rcp_f32_e32 v61, v61
	v_add_f32_e32 v57, 1.0, v57
	v_pk_add_f32 v[62:63], v[62:63], v[70:71]
	v_rcp_f32_e32 v56, v56
	v_rcp_f32_e32 v57, v57
	v_mul_f32_e32 v62, 0xbfb8aa3b, v62
	v_exp_f32_e32 v62, v62
	v_pk_add_f32 v[58:59], v[58:59], v[66:67]
	v_pk_mul_f32 v[60:61], v[60:61], v[76:77]
	v_lshlrev_b32_e32 v76, 16, v162
	v_and_b32_e32 v77, 0xffff0000, v162
	v_pk_mul_f32 v[76:77], v[56:57], v[76:77]
	v_mul_f32_e32 v57, 0xbfb8aa3b, v58
	v_exp_f32_e32 v57, v57
	v_mul_f32_e32 v58, 0xbfb8aa3b, v63
	v_add_f32_e32 v56, 1.0, v62
	v_exp_f32_e32 v62, v58
	v_mul_f32_e32 v59, 0xbfb8aa3b, v59
	v_exp_f32_e32 v59, v59
	v_pk_add_f32 v[52:53], v[52:53], v[68:69]
	v_add_f32_e32 v57, 1.0, v57
	v_mul_f32_e32 v52, 0xbfb8aa3b, v52
	v_pk_add_f32 v[48:49], v[48:49], v[64:65]
	v_mul_f32_e32 v53, 0xbfb8aa3b, v53
	v_rcp_f32_e32 v58, v57
	v_add_f32_e32 v57, 1.0, v62
	v_exp_f32_e32 v52, v52
	v_mul_f32_e32 v48, 0xbfb8aa3b, v48
	v_exp_f32_e32 v53, v53
	v_mul_f32_e32 v49, 0xbfb8aa3b, v49
	v_rcp_f32_e32 v56, v56
	v_rcp_f32_e32 v57, v57
	v_add_f32_e32 v59, 1.0, v59
	v_exp_f32_e32 v48, v48
	v_exp_f32_e32 v49, v49
	v_rcp_f32_e32 v59, v59
	v_lshlrev_b32_e32 v62, 16, v161
	v_and_b32_e32 v63, 0xffff0000, v161
	v_add_f32_e32 v52, 1.0, v52
	v_add_f32_e32 v53, 1.0, v53
	v_pk_mul_f32 v[62:63], v[56:57], v[62:63]
	v_lshlrev_b32_e32 v56, 16, v163
	v_and_b32_e32 v57, 0xffff0000, v163
	v_rcp_f32_e32 v52, v52
	v_add_f32_e32 v48, 1.0, v48
	v_rcp_f32_e32 v53, v53
	v_add_f32_e32 v49, 1.0, v49
	v_pk_mul_f32 v[78:79], v[58:59], v[56:57]
	v_pk_add_f32 v[54:55], v[54:55], v[70:71]
	v_rcp_f32_e32 v48, v48
	v_rcp_f32_e32 v49, v49
	v_cvt_pk_bf16_f32 v56, v60, v61
	v_cvt_pk_bf16_f32 v57, v62, v63
	v_cvt_pk_bf16_f32 v58, v76, v77
	v_cvt_pk_bf16_f32 v59, v78, v79
	v_mul_f32_e32 v54, 0xbfb8aa3b, v54
	global_store_dwordx4 v[214:215], v[56:59], off offset:2304
	v_exp_f32_e32 v54, v54
	v_pk_add_f32 v[50:51], v[50:51], v[66:67]
	v_lshlrev_b32_e32 v56, 16, v156
	v_and_b32_e32 v57, 0xffff0000, v156
	v_pk_mul_f32 v[52:53], v[52:53], v[56:57]
	v_lshlrev_b32_e32 v56, 16, v158
	v_and_b32_e32 v57, 0xffff0000, v158
	v_pk_mul_f32 v[56:57], v[48:49], v[56:57]
	v_mul_f32_e32 v49, 0xbfb8aa3b, v50
	v_exp_f32_e32 v49, v49
	v_mul_f32_e32 v50, 0xbfb8aa3b, v55
	v_add_f32_e32 v48, 1.0, v54
	v_exp_f32_e32 v54, v50
	v_mul_f32_e32 v51, 0xbfb8aa3b, v51
	v_exp_f32_e32 v51, v51
	v_pk_add_f32 v[44:45], v[44:45], v[68:69]
	v_add_f32_e32 v49, 1.0, v49
	v_mul_f32_e32 v44, 0xbfb8aa3b, v44
	v_pk_add_f32 v[40:41], v[40:41], v[64:65]
	v_mul_f32_e32 v45, 0xbfb8aa3b, v45
	v_rcp_f32_e32 v50, v49
	v_add_f32_e32 v49, 1.0, v54
	v_exp_f32_e32 v44, v44
	v_mul_f32_e32 v40, 0xbfb8aa3b, v40
	v_exp_f32_e32 v45, v45
	v_mul_f32_e32 v41, 0xbfb8aa3b, v41
	v_rcp_f32_e32 v48, v48
	v_rcp_f32_e32 v49, v49
	v_add_f32_e32 v51, 1.0, v51
	v_exp_f32_e32 v40, v40
	v_exp_f32_e32 v41, v41
	v_rcp_f32_e32 v51, v51
	v_lshlrev_b32_e32 v54, 16, v157
	v_and_b32_e32 v55, 0xffff0000, v157
	v_add_f32_e32 v44, 1.0, v44
	v_add_f32_e32 v45, 1.0, v45
	v_pk_mul_f32 v[54:55], v[48:49], v[54:55]
	v_lshlrev_b32_e32 v48, 16, v159
	v_and_b32_e32 v49, 0xffff0000, v159
	v_rcp_f32_e32 v44, v44
	v_add_f32_e32 v40, 1.0, v40
	v_rcp_f32_e32 v45, v45
	v_add_f32_e32 v41, 1.0, v41
	v_pk_mul_f32 v[58:59], v[50:51], v[48:49]
	v_pk_add_f32 v[46:47], v[46:47], v[70:71]
	v_rcp_f32_e32 v40, v40
	v_rcp_f32_e32 v41, v41
	v_cvt_pk_bf16_f32 v48, v52, v53
	v_cvt_pk_bf16_f32 v49, v54, v55
	v_cvt_pk_bf16_f32 v50, v56, v57
	v_cvt_pk_bf16_f32 v51, v58, v59
	v_mul_f32_e32 v46, 0xbfb8aa3b, v46
	global_store_dwordx4 v[112:113], v[48:51], off offset:2304
	v_exp_f32_e32 v46, v46
	v_pk_add_f32 v[42:43], v[42:43], v[66:67]
	v_lshlrev_b32_e32 v48, 16, v148
	v_and_b32_e32 v49, 0xffff0000, v148
	v_pk_mul_f32 v[44:45], v[44:45], v[48:49]
	v_lshlrev_b32_e32 v48, 16, v150
	v_and_b32_e32 v49, 0xffff0000, v150
	v_pk_mul_f32 v[48:49], v[40:41], v[48:49]
	v_mul_f32_e32 v41, 0xbfb8aa3b, v42
	v_exp_f32_e32 v41, v41
	v_mul_f32_e32 v42, 0xbfb8aa3b, v47
	v_add_f32_e32 v40, 1.0, v46
	v_exp_f32_e32 v46, v42
	v_mul_f32_e32 v43, 0xbfb8aa3b, v43
	v_exp_f32_e32 v43, v43
	v_pk_add_f32 v[36:37], v[36:37], v[68:69]
	v_add_f32_e32 v41, 1.0, v41
	v_mul_f32_e32 v36, 0xbfb8aa3b, v36
	v_pk_add_f32 v[32:33], v[32:33], v[64:65]
	v_mul_f32_e32 v37, 0xbfb8aa3b, v37
	v_rcp_f32_e32 v42, v41
	v_add_f32_e32 v41, 1.0, v46
	v_exp_f32_e32 v36, v36
	v_mul_f32_e32 v32, 0xbfb8aa3b, v32
	v_exp_f32_e32 v37, v37
	v_mul_f32_e32 v33, 0xbfb8aa3b, v33
	v_rcp_f32_e32 v40, v40
	v_rcp_f32_e32 v41, v41
	v_add_f32_e32 v43, 1.0, v43
	v_exp_f32_e32 v32, v32
	v_exp_f32_e32 v33, v33
	v_rcp_f32_e32 v43, v43
	v_lshlrev_b32_e32 v46, 16, v149
	v_and_b32_e32 v47, 0xffff0000, v149
	v_add_f32_e32 v36, 1.0, v36
	v_add_f32_e32 v37, 1.0, v37
	v_pk_mul_f32 v[46:47], v[40:41], v[46:47]
	v_lshlrev_b32_e32 v40, 16, v151
	v_and_b32_e32 v41, 0xffff0000, v151
	v_rcp_f32_e32 v36, v36
	v_add_f32_e32 v32, 1.0, v32
	v_rcp_f32_e32 v37, v37
	v_add_f32_e32 v33, 1.0, v33
	v_pk_mul_f32 v[50:51], v[42:43], v[40:41]
	v_pk_add_f32 v[38:39], v[38:39], v[70:71]
	v_rcp_f32_e32 v32, v32
	v_rcp_f32_e32 v33, v33
	v_cvt_pk_bf16_f32 v40, v44, v45
	v_cvt_pk_bf16_f32 v41, v46, v47
	v_cvt_pk_bf16_f32 v42, v48, v49
	v_cvt_pk_bf16_f32 v43, v50, v51
	v_mul_f32_e32 v38, 0xbfb8aa3b, v38
; __device__ __forceinline__ float sigm(float x) { return __builtin_amdgcn_rcpf(1.0f + __builtin_amdgcn_exp2f(-1.4426950408889634f * x)); }
;     __device__ __forceinline__ void operator()(EPI_ARGS) const {
;         const int row0 = u.pm * 256 + wr * 64 + fr, col0 = u.pn * 256 + wc * 32 + 8 * fq;
; #pragma unroll
;         for (int bj = 0; bj < 2; ++bj) { const f32x4 b0 = *(const f32x4*)(bias + col0 + bj * 128), b1 = *(const f32x4*)(bias + col0 + bj * 128 + 4);
;             u32x4 hw[2][4];
; #pragma unroll
;             for (int ai = 0; ai < 2; ++ai)
; #pragma unroll
;                 for (int m = 0; m < 4; ++m) hw[ai][m] = *(const u32x4*)(H + (size_t)(row0 + ai * 128 + m * 16) * 512 + col0 + bj * 128);
; #pragma unroll
;             for (int ai = 0; ai < 2; ++ai)
; #pragma unroll
;                 for (int m = 0; m < 4; ++m) { const size_t off = (size_t)(row0 + ai * 128 + m * 16) * 512 + col0 + bj * 128;
;                     f32x4 h0, h1; unpack8(hw[ai][m], h0, h1);
;                     f32x4 v0 = acc[ai][bj][m][0] + b0, v1 = acc[ai][bj][m][1] + b1;
; #pragma unroll
;                     for (int j = 0; j < 4; ++j) { v0[j] = h0[j] * sigm(v0[j]); v1[j] = h1[j] * sigm(v1[j]); }
;                     *(u32x4*)(O + (size_t)(row0 + ai * 128 + m * 16) * KAB + 1024 + col0 + bj * 128) = pack8(v0, v1); } }
;     }
	global_store_dwordx4 v[104:105], v[40:43], off offset:2304
	v_exp_f32_e32 v38, v38
	v_pk_add_f32 v[34:35], v[34:35], v[66:67]
	v_lshlrev_b32_e32 v40, 16, v144
	v_and_b32_e32 v41, 0xffff0000, v144
	v_pk_mul_f32 v[36:37], v[36:37], v[40:41]
	v_lshlrev_b32_e32 v40, 16, v146
	v_and_b32_e32 v41, 0xffff0000, v146
	v_pk_mul_f32 v[40:41], v[32:33], v[40:41]
	v_mul_f32_e32 v33, 0xbfb8aa3b, v34
	v_exp_f32_e32 v33, v33
	v_mul_f32_e32 v34, 0xbfb8aa3b, v39
	v_add_f32_e32 v32, 1.0, v38
	v_exp_f32_e32 v38, v34
	v_mul_f32_e32 v35, 0xbfb8aa3b, v35
	v_exp_f32_e32 v35, v35
	v_pk_add_f32 v[28:29], v[28:29], v[68:69]
	v_add_f32_e32 v33, 1.0, v33
	v_mul_f32_e32 v28, 0xbfb8aa3b, v28
	v_pk_add_f32 v[24:25], v[24:25], v[64:65]
	v_mul_f32_e32 v29, 0xbfb8aa3b, v29
	v_rcp_f32_e32 v34, v33
	v_add_f32_e32 v33, 1.0, v38
	v_exp_f32_e32 v28, v28
	v_mul_f32_e32 v24, 0xbfb8aa3b, v24
	v_exp_f32_e32 v29, v29
	v_mul_f32_e32 v25, 0xbfb8aa3b, v25
	v_rcp_f32_e32 v32, v32
	v_rcp_f32_e32 v33, v33
	v_add_f32_e32 v35, 1.0, v35
	v_exp_f32_e32 v24, v24
	v_exp_f32_e32 v25, v25
	v_rcp_f32_e32 v35, v35
	v_lshlrev_b32_e32 v38, 16, v145
	v_and_b32_e32 v39, 0xffff0000, v145
	v_add_f32_e32 v28, 1.0, v28
	v_add_f32_e32 v29, 1.0, v29
	v_pk_mul_f32 v[38:39], v[32:33], v[38:39]
	v_lshlrev_b32_e32 v32, 16, v147
	v_and_b32_e32 v33, 0xffff0000, v147
	v_rcp_f32_e32 v28, v28
	v_add_f32_e32 v24, 1.0, v24
	v_rcp_f32_e32 v29, v29
	v_add_f32_e32 v25, 1.0, v25
	v_pk_mul_f32 v[42:43], v[34:35], v[32:33]
	v_pk_add_f32 v[30:31], v[30:31], v[70:71]
	v_rcp_f32_e32 v24, v24
	v_rcp_f32_e32 v25, v25
	v_cvt_pk_bf16_f32 v32, v36, v37
	v_cvt_pk_bf16_f32 v33, v38, v39
	v_cvt_pk_bf16_f32 v34, v40, v41
	v_cvt_pk_bf16_f32 v35, v42, v43
	v_mul_f32_e32 v30, 0xbfb8aa3b, v30
	global_store_dwordx4 v[96:97], v[32:35], off offset:2304
	v_exp_f32_e32 v30, v30
	v_pk_add_f32 v[26:27], v[26:27], v[66:67]
	v_lshlrev_b32_e32 v32, 16, v140
	v_and_b32_e32 v33, 0xffff0000, v140
	v_pk_mul_f32 v[28:29], v[28:29], v[32:33]
	v_lshlrev_b32_e32 v32, 16, v142
	v_and_b32_e32 v33, 0xffff0000, v142
	v_pk_mul_f32 v[32:33], v[24:25], v[32:33]
	v_mul_f32_e32 v25, 0xbfb8aa3b, v26
	v_exp_f32_e32 v25, v25
	v_mul_f32_e32 v26, 0xbfb8aa3b, v31
	v_add_f32_e32 v24, 1.0, v30
	v_exp_f32_e32 v30, v26
	v_mul_f32_e32 v27, 0xbfb8aa3b, v27
	v_exp_f32_e32 v27, v27
	v_pk_add_f32 v[20:21], v[20:21], v[68:69]
	v_add_f32_e32 v25, 1.0, v25
	v_mul_f32_e32 v20, 0xbfb8aa3b, v20
	v_pk_add_f32 v[16:17], v[16:17], v[64:65]
	v_mul_f32_e32 v21, 0xbfb8aa3b, v21
	v_rcp_f32_e32 v26, v25
	v_add_f32_e32 v25, 1.0, v30
	v_exp_f32_e32 v20, v20
	v_mul_f32_e32 v16, 0xbfb8aa3b, v16
	v_exp_f32_e32 v21, v21
	v_mul_f32_e32 v17, 0xbfb8aa3b, v17
	v_rcp_f32_e32 v24, v24
	v_rcp_f32_e32 v25, v25
	v_add_f32_e32 v27, 1.0, v27
	v_exp_f32_e32 v16, v16
	v_exp_f32_e32 v17, v17
	v_rcp_f32_e32 v27, v27
	v_lshlrev_b32_e32 v30, 16, v141
	v_and_b32_e32 v31, 0xffff0000, v141
	v_add_f32_e32 v20, 1.0, v20
	v_add_f32_e32 v21, 1.0, v21
	v_pk_mul_f32 v[30:31], v[24:25], v[30:31]
	v_lshlrev_b32_e32 v24, 16, v143
	v_and_b32_e32 v25, 0xffff0000, v143
	v_rcp_f32_e32 v20, v20
	v_add_f32_e32 v16, 1.0, v16
	v_rcp_f32_e32 v21, v21
	v_add_f32_e32 v17, 1.0, v17
	v_pk_mul_f32 v[34:35], v[26:27], v[24:25]
	v_pk_add_f32 v[22:23], v[22:23], v[70:71]
	v_rcp_f32_e32 v16, v16
	v_rcp_f32_e32 v17, v17
	v_cvt_pk_bf16_f32 v24, v28, v29
	v_cvt_pk_bf16_f32 v25, v30, v31
	v_cvt_pk_bf16_f32 v26, v32, v33
	v_cvt_pk_bf16_f32 v27, v34, v35
	v_mul_f32_e32 v22, 0xbfb8aa3b, v22
	global_store_dwordx4 v[88:89], v[24:27], off offset:2304
	v_exp_f32_e32 v22, v22
	v_pk_add_f32 v[18:19], v[18:19], v[66:67]
	v_lshlrev_b32_e32 v24, 16, v136
	v_and_b32_e32 v25, 0xffff0000, v136
	v_pk_mul_f32 v[20:21], v[20:21], v[24:25]
	v_lshlrev_b32_e32 v24, 16, v138
	v_and_b32_e32 v25, 0xffff0000, v138
	v_pk_mul_f32 v[24:25], v[16:17], v[24:25]
	v_mul_f32_e32 v17, 0xbfb8aa3b, v18
	v_exp_f32_e32 v17, v17
	v_mul_f32_e32 v18, 0xbfb8aa3b, v23
	v_add_f32_e32 v16, 1.0, v22
	v_exp_f32_e32 v22, v18
	v_mul_f32_e32 v19, 0xbfb8aa3b, v19
	v_exp_f32_e32 v19, v19
; __device__ __forceinline__ float sigm(float x) { return __builtin_amdgcn_rcpf(1.0f + __builtin_amdgcn_exp2f(-1.4426950408889634f * x)); }
; #define PG8_WAIT_V(n) asm volatile("s_waitcnt vmcnt(" #n ")" ::: "memory")
; #define PG8_BAR __builtin_amdgcn_s_barrier()
; template <class Epi>
; __device__ __forceinline__ void gemm_phase(ldsp lds, const Gemm g, const StaticOrder& S, const Epi& E) {
;     ...
;     PG8_WAIT_V(0);
;     if (wr == 0) PG8_BAR;
;     PG8_BAR;
;     __device__ __forceinline__ void operator()(EPI_ARGS) const {
;         const int row0 = u.pm * 256 + wr * 64 + fr, col0 = u.pn * 256 + wc * 32 + 8 * fq;
; #pragma unroll
;         for (int bj = 0; bj < 2; ++bj) { const f32x4 b0 = *(const f32x4*)(bias + col0 + bj * 128), b1 = *(const f32x4*)(bias + col0 + bj * 128 + 4);
;             u32x4 hw[2][4];
; #pragma unroll
;             for (int ai = 0; ai < 2; ++ai)
; #pragma unroll
;                 for (int m = 0; m < 4; ++m) hw[ai][m] = *(const u32x4*)(H + (size_t)(row0 + ai * 128 + m * 16) * 512 + col0 + bj * 128);
; #pragma unroll
;             for (int ai = 0; ai < 2; ++ai)
; #pragma unroll
;                 for (int m = 0; m < 4; ++m) { const size_t off = (size_t)(row0 + ai * 128 + m * 16) * 512 + col0 + bj * 128;
;                     f32x4 h0, h1; unpack8(hw[ai][m], h0, h1);
;                     f32x4 v0 = acc[ai][bj][m][0] + b0, v1 = acc[ai][bj][m][1] + b1;
; #pragma unroll
;                     for (int j = 0; j < 4; ++j) { v0[j] = h0[j] * sigm(v0[j]); v1[j] = h1[j] * sigm(v1[j]); }
;                     *(u32x4*)(O + (size_t)(row0 + ai * 128 + m * 16) * KAB + 1024 + col0 + bj * 128) = pack8(v0, v1); } }
;     }
	v_pk_add_f32 v[12:13], v[12:13], v[68:69]
	v_add_f32_e32 v17, 1.0, v17
	v_mul_f32_e32 v12, 0xbfb8aa3b, v12
	v_pk_add_f32 v[8:9], v[8:9], v[64:65]
	v_mul_f32_e32 v13, 0xbfb8aa3b, v13
	v_rcp_f32_e32 v18, v17
	v_add_f32_e32 v17, 1.0, v22
	v_exp_f32_e32 v12, v12
	v_mul_f32_e32 v8, 0xbfb8aa3b, v8
	v_exp_f32_e32 v13, v13
	v_mul_f32_e32 v9, 0xbfb8aa3b, v9
	v_rcp_f32_e32 v16, v16
	v_rcp_f32_e32 v17, v17
	v_add_f32_e32 v19, 1.0, v19
	v_exp_f32_e32 v8, v8
	v_exp_f32_e32 v9, v9
	v_rcp_f32_e32 v19, v19
	v_lshlrev_b32_e32 v22, 16, v137
	v_and_b32_e32 v23, 0xffff0000, v137
	v_add_f32_e32 v12, 1.0, v12
	v_add_f32_e32 v13, 1.0, v13
	v_pk_mul_f32 v[22:23], v[16:17], v[22:23]
	v_lshlrev_b32_e32 v16, 16, v139
	v_and_b32_e32 v17, 0xffff0000, v139
	v_rcp_f32_e32 v12, v12
	v_add_f32_e32 v8, 1.0, v8
	v_rcp_f32_e32 v13, v13
	v_add_f32_e32 v9, 1.0, v9
	v_pk_mul_f32 v[26:27], v[18:19], v[16:17]
	v_pk_add_f32 v[14:15], v[14:15], v[70:71]
	v_rcp_f32_e32 v8, v8
	v_rcp_f32_e32 v9, v9
	v_cvt_pk_bf16_f32 v16, v20, v21
	v_cvt_pk_bf16_f32 v17, v22, v23
	v_cvt_pk_bf16_f32 v18, v24, v25
	v_cvt_pk_bf16_f32 v19, v26, v27
	v_mul_f32_e32 v14, 0xbfb8aa3b, v14
	global_store_dwordx4 v[80:81], v[16:19], off offset:2304
	v_exp_f32_e32 v14, v14
	v_pk_add_f32 v[10:11], v[10:11], v[66:67]
	v_lshlrev_b32_e32 v16, 16, v124
	v_and_b32_e32 v17, 0xffff0000, v124
	v_pk_mul_f32 v[12:13], v[12:13], v[16:17]
	v_lshlrev_b32_e32 v16, 16, v126
	v_and_b32_e32 v17, 0xffff0000, v126
	v_pk_mul_f32 v[16:17], v[8:9], v[16:17]
	v_mul_f32_e32 v9, 0xbfb8aa3b, v10
	v_exp_f32_e32 v9, v9
	v_mul_f32_e32 v10, 0xbfb8aa3b, v15
	v_add_f32_e32 v8, 1.0, v14
	v_exp_f32_e32 v14, v10
	v_mul_f32_e32 v11, 0xbfb8aa3b, v11
	v_exp_f32_e32 v11, v11
	v_pk_add_f32 v[4:5], v[4:5], v[68:69]
	v_add_f32_e32 v9, 1.0, v9
	v_mul_f32_e32 v4, 0xbfb8aa3b, v4
	v_pk_add_f32 v[0:1], v[0:1], v[64:65]
	v_mul_f32_e32 v5, 0xbfb8aa3b, v5
	v_rcp_f32_e32 v10, v9
	v_add_f32_e32 v9, 1.0, v14
	v_exp_f32_e32 v4, v4
	v_mul_f32_e32 v0, 0xbfb8aa3b, v0
	v_exp_f32_e32 v5, v5
	v_mul_f32_e32 v1, 0xbfb8aa3b, v1
	v_rcp_f32_e32 v8, v8
	v_rcp_f32_e32 v9, v9
	v_add_f32_e32 v11, 1.0, v11
	v_exp_f32_e32 v0, v0
	v_exp_f32_e32 v1, v1
	v_rcp_f32_e32 v11, v11
	v_lshlrev_b32_e32 v14, 16, v125
	v_and_b32_e32 v15, 0xffff0000, v125
	v_add_f32_e32 v4, 1.0, v4
	v_add_f32_e32 v5, 1.0, v5
	v_pk_mul_f32 v[14:15], v[8:9], v[14:15]
	v_lshlrev_b32_e32 v8, 16, v127
	v_and_b32_e32 v9, 0xffff0000, v127
	v_rcp_f32_e32 v4, v4
	v_add_f32_e32 v0, 1.0, v0
	v_rcp_f32_e32 v5, v5
	v_add_f32_e32 v1, 1.0, v1
	v_pk_mul_f32 v[18:19], v[10:11], v[8:9]
	v_pk_add_f32 v[6:7], v[6:7], v[70:71]
	v_rcp_f32_e32 v0, v0
	v_rcp_f32_e32 v1, v1
	v_cvt_pk_bf16_f32 v8, v12, v13
	v_cvt_pk_bf16_f32 v9, v14, v15
	v_cvt_pk_bf16_f32 v10, v16, v17
	v_cvt_pk_bf16_f32 v11, v18, v19
	v_mul_f32_e32 v6, 0xbfb8aa3b, v6
	global_store_dwordx4 v[74:75], v[8:11], off offset:2304
	v_exp_f32_e32 v6, v6
	v_pk_add_f32 v[2:3], v[2:3], v[66:67]
	v_lshlrev_b32_e32 v8, 16, v120
	v_and_b32_e32 v9, 0xffff0000, v120
	v_pk_mul_f32 v[4:5], v[4:5], v[8:9]
	v_lshlrev_b32_e32 v8, 16, v122
	v_and_b32_e32 v9, 0xffff0000, v122
	v_pk_mul_f32 v[8:9], v[0:1], v[8:9]
	v_mul_f32_e32 v1, 0xbfb8aa3b, v2
	v_exp_f32_e32 v1, v1
	v_mul_f32_e32 v2, 0xbfb8aa3b, v7
	v_add_f32_e32 v0, 1.0, v6
	v_exp_f32_e32 v6, v2
	v_mul_f32_e32 v3, 0xbfb8aa3b, v3
	v_exp_f32_e32 v3, v3
	v_add_f32_e32 v1, 1.0, v1
	v_rcp_f32_e32 v2, v1
	v_add_f32_e32 v1, 1.0, v6
	v_rcp_f32_e32 v0, v0
	v_rcp_f32_e32 v1, v1
	v_add_f32_e32 v3, 1.0, v3
	v_rcp_f32_e32 v3, v3
	v_lshlrev_b32_e32 v6, 16, v121
	v_and_b32_e32 v7, 0xffff0000, v121
	v_pk_mul_f32 v[6:7], v[0:1], v[6:7]
	v_lshlrev_b32_e32 v0, 16, v123
	v_and_b32_e32 v1, 0xffff0000, v123
	v_pk_mul_f32 v[10:11], v[2:3], v[0:1]
	v_cvt_pk_bf16_f32 v0, v4, v5
	v_cvt_pk_bf16_f32 v1, v6, v7
	v_cvt_pk_bf16_f32 v2, v8, v9
	v_cvt_pk_bf16_f32 v3, v10, v11
	global_store_dwordx4 v[72:73], v[0:3], off offset:2304
	s_cbranch_vccz .LBB0_567
	s_waitcnt vmcnt(0)
	s_cmpk_gt_u32 s26, 0xff
	s_cbranch_scc1 .LBB0_578
	s_barrier

; #define PG8_STAGE(bufoff, gbase, voff) do { _Pragma("unroll") for (int _i = 0; _i < 2; ++_i) \
;         __builtin_amdgcn_global_load_lds((const unsigned*)((const char*)(gbase) + (voff)[_i]), (LAS unsigned*)(lds + (bufoff) + ldsw + _i * 8192), 16, 0, 0); } while (0)
; #define PG8_WAIT_V(n) asm volatile("s_waitcnt vmcnt(" #n ")" ::: "memory")
; template <class Epi>
; __device__ __forceinline__ void gemm_phase(ldsp lds, const Gemm g, const StaticOrder& S, const Epi& E) {
;     ...
;         for (int t = 0; t < nt; t += 2) {
;             const bool last = (t == nt - 2);
;             const char* a1 = cA + (size_t)(t + 1) * kstep;
;             const char* a2 = last ? nA : cA + (size_t)(t + 2) * kstep; const char* b2 = last ? nB : cB + (size_t)(t + 2) * kstep;
;             const char* a3 = a2 + kstep; const char* b3 = b2 + kstep;
;             if constexpr (Epi::NPRE > 0) { if (last) E.pre(pre, cur, wr, fr); }
;             if constexpr (Epi::MID_T > 0) { if (t == Epi::MID_T) E.mid(acc, cur, wr, wc, fr, fq); }
;             PG8_LDB(B0, 0, 0); PG8_SCHED; PG8_LDA(At, 0, 0); PG8_STAGE(PG8_SA(1, 1), a1 + hstep, voffA);
;             PG8_WAIT_L(8); PG8_WAIT_V(10); PG8_BAR; PG8_WAIT_L(0); PG8_MMA(0, 0, At, B0); PG8_BAR; PG8_SCHED;
;             PG8_LDB(B1, 0, 1); PG8_STAGE(PG8_SB(0, 0), b2, voffB);
;             PG8_WAIT_V(10); PG8_BAR; PG8_WAIT_L(0); PG8_MMA(0, 1, At, B1); PG8_BAR;
;             PG8_LDA(At, 0, 1); PG8_STAGE(PG8_SA(0, 0), a2, voffA);
;             PG8_WAIT_V(10); PG8_BAR; PG8_WAIT_L(0); PG8_MMA(1, 0, At, B0); PG8_BAR; PG8_SCHED;
;             PG8_STAGE(PG8_SB(0, 1), b2 + hstep, voffB);
;             PG8_WAIT_V(10); PG8_BAR; PG8_MMA(1, 1, At, B1); PG8_BAR;
;             PG8_LDB(B0, 1, 0); PG8_SCHED; PG8_LDA(At, 1, 0); PG8_STAGE(PG8_SA(0, 1), a2 + hstep, voffA);
;             PG8_WAIT_L(8); PG8_WAIT_V(10); PG8_BAR; PG8_WAIT_L(0); PG8_MMA(0, 0, At, B0); PG8_BAR; PG8_SCHED;
;             PG8_LDB(B1, 1, 1); PG8_STAGE(PG8_SB(1, 0), b3, voffB);
;             PG8_WAIT_V(10); PG8_BAR; PG8_WAIT_L(0); PG8_MMA(0, 1, At, B1); PG8_BAR;
;             PG8_LDA(At, 1, 1); PG8_STAGE(PG8_SA(1, 0), a3, voffA);
;             PG8_WAIT_V(10); PG8_BAR; PG8_WAIT_L(0); PG8_MMA(1, 0, At, B0); PG8_BAR; PG8_SCHED;
;             PG8_STAGE(PG8_SB(1, 1), b3 + hstep, voffB);
;             PG8_WAIT_V(10); PG8_BAR; PG8_MMA(1, 1, At, B1); PG8_BAR;
;         }
.LBB0_654:
	v_add_u32_e32 v140, s45, v222
	s_add_u32 s26, s22, s24
	ds_read_b128 v[128:131], v140
	ds_read_b128 v[132:135], v140 offset:1024
	ds_read_b128 v[136:139], v140 offset:2048
	ds_read_b128 v[140:143], v140 offset:3072
	s_addc_u32 s27, s23, s25
	s_add_u32 s26, s26, 0x100
	s_addc_u32 s27, s27, 0
	s_add_u32 s54, s51, s24
	s_addc_u32 s55, s52, s25
	s_cmpk_eq_i32 s24, 0xb00
	s_cselect_b32 s29, s1, s27
	s_cselect_b32 s28, s0, s26
	s_cselect_b32 s27, s5, s55
	s_cselect_b32 s26, s4, s54
	v_lshl_add_u64 v[176:177], v[212:213], 0, s[24:25]
	s_add_i32 m0, s36, 0xc000
	s_waitcnt vmcnt(0)
	ds_read_b128 v[144:147], v224
	ds_read_b128 v[148:151], v224 offset:1024
	ds_read_b128 v[152:155], v224 offset:2048
	ds_read_b128 v[156:159], v224 offset:3072
	ds_read_b128 v[160:163], v224 offset:4096
	ds_read_b128 v[164:167], v224 offset:5120
	ds_read_b128 v[168:171], v224 offset:6144
	ds_read_b128 v[172:175], v224 offset:7168
	global_load_lds_dwordx4 v[176:177], off
	v_lshl_add_u64 v[176:177], v[214:215], 0, s[24:25]
	s_add_i32 m0, s36, 0xe000
	s_nop 0
	global_load_lds_dwordx4 v[176:177], off
	s_waitcnt lgkmcnt(8)
	s_waitcnt vmcnt(10)
	s_barrier
	s_waitcnt lgkmcnt(0)
	s_setprio 1
	s_waitcnt lgkmcnt(0)
	v_mfma_f32_16x16x32_bf16 v[124:127], v[128:131], v[144:147], v[124:127]
	v_mfma_f32_16x16x32_bf16 v[120:123], v[136:139], v[144:147], v[120:123]
	v_mfma_f32_16x16x32_bf16 v[116:119], v[128:131], v[152:155], v[116:119]
	v_mfma_f32_16x16x32_bf16 v[104:107], v[136:139], v[152:155], v[104:107]
	v_mfma_f32_16x16x32_bf16 v[96:99], v[128:131], v[160:163], v[96:99]
	v_mfma_f32_16x16x32_bf16 v[88:91], v[136:139], v[160:163], v[88:91]
	v_mfma_f32_16x16x32_bf16 v[80:83], v[128:131], v[168:171], v[80:83]
	v_mfma_f32_16x16x32_bf16 v[72:75], v[136:139], v[168:171], v[72:75]
	v_mfma_f32_16x16x32_bf16 v[124:127], v[132:135], v[148:151], v[124:127]
	v_mfma_f32_16x16x32_bf16 v[120:123], v[140:143], v[148:151], v[120:123]
	v_mfma_f32_16x16x32_bf16 v[116:119], v[132:135], v[156:159], v[116:119]
	v_mfma_f32_16x16x32_bf16 v[104:107], v[140:143], v[156:159], v[104:107]
	v_mfma_f32_16x16x32_bf16 v[96:99], v[132:135], v[164:167], v[96:99]
	v_mfma_f32_16x16x32_bf16 v[88:91], v[140:143], v[164:167], v[88:91]
	v_mfma_f32_16x16x32_bf16 v[80:83], v[132:135], v[172:175], v[80:83]
	s_barrier
	v_mfma_f32_16x16x32_bf16 v[72:75], v[140:143], v[172:175], v[72:75]
	s_setprio 0
	s_add_i32 s54, s45, s35
	v_add_u32_e32 v188, s46, v222
	v_lshl_add_u64 v[216:217], s[26:27], 0, v[194:195]
	s_mov_b32 m0, s54
	ds_read_b128 v[176:179], v188
	ds_read_b128 v[180:183], v188 offset:1024
	ds_read_b128 v[184:187], v188 offset:2048
	ds_read_b128 v[188:191], v188 offset:3072
	global_load_lds_dwordx4 v[216:217], off
	v_lshl_add_u64 v[218:219], s[26:27], 0, v[198:199]
	s_add_i32 m0, s54, 0x2000
	s_nop 0
	global_load_lds_dwordx4 v[218:219], off
	s_waitcnt vmcnt(10)
	s_barrier
	s_waitcnt lgkmcnt(0)
	s_setprio 1
	s_waitcnt lgkmcnt(0)
	v_mfma_f32_16x16x32_bf16 v[112:115], v[176:179], v[144:147], v[112:115]
	v_mfma_f32_16x16x32_bf16 v[108:111], v[184:187], v[144:147], v[108:111]
	v_mfma_f32_16x16x32_bf16 v[100:103], v[176:179], v[152:155], v[100:103]
	v_mfma_f32_16x16x32_bf16 v[92:95], v[184:187], v[152:155], v[92:95]
	v_mfma_f32_16x16x32_bf16 v[84:87], v[176:179], v[160:163], v[84:87]
	v_mfma_f32_16x16x32_bf16 v[76:79], v[184:187], v[160:163], v[76:79]
	v_mfma_f32_16x16x32_bf16 v[68:71], v[176:179], v[168:171], v[68:71]
	v_mfma_f32_16x16x32_bf16 v[64:67], v[184:187], v[168:171], v[64:67]
	v_mfma_f32_16x16x32_bf16 v[112:115], v[180:183], v[148:151], v[112:115]
	v_mfma_f32_16x16x32_bf16 v[108:111], v[188:191], v[148:151], v[108:111]
	v_mfma_f32_16x16x32_bf16 v[100:103], v[180:183], v[156:159], v[100:103]
	v_mfma_f32_16x16x32_bf16 v[92:95], v[188:191], v[156:159], v[92:95]
	v_mfma_f32_16x16x32_bf16 v[84:87], v[180:183], v[164:167], v[84:87]
	v_mfma_f32_16x16x32_bf16 v[76:79], v[188:191], v[164:167], v[76:79]
	v_mfma_f32_16x16x32_bf16 v[68:71], v[180:183], v[172:175], v[68:71]
	s_barrier
	v_mfma_f32_16x16x32_bf16 v[64:67], v[188:191], v[172:175], v[64:67]
	s_setprio 0
	s_mov_b32 m0, s36
	v_lshl_add_u64 v[226:227], s[28:29], 0, v[192:193]
	ds_read_b128 v[144:147], v224 offset:16384
	ds_read_b128 v[148:151], v224 offset:17408
	ds_read_b128 v[152:155], v224 offset:18432
	ds_read_b128 v[156:159], v224 offset:19456
	ds_read_b128 v[160:163], v224 offset:20480
	ds_read_b128 v[164:167], v224 offset:21504
	ds_read_b128 v[168:171], v224 offset:22528
	ds_read_b128 v[172:175], v224 offset:23552
	global_load_lds_dwordx4 v[226:227], off
	v_lshl_add_u64 v[228:229], s[28:29], 0, v[196:197]
	s_mov_b32 m0, s37
	s_nop 0
	global_load_lds_dwordx4 v[228:229], off
	s_waitcnt vmcnt(10)
	s_barrier
	s_waitcnt lgkmcnt(0)
	s_setprio 1
	s_waitcnt lgkmcnt(0)
	v_mfma_f32_16x16x32_bf16 v[60:63], v[128:131], v[144:147], v[60:63]
	v_mfma_f32_16x16x32_bf16 v[56:59], v[136:139], v[144:147], v[56:59]
	v_mfma_f32_16x16x32_bf16 v[48:51], v[128:131], v[152:155], v[48:51]
	v_mfma_f32_16x16x32_bf16 v[40:43], v[136:139], v[152:155], v[40:43]
	v_mfma_f32_16x16x32_bf16 v[32:35], v[128:131], v[160:163], v[32:35]
	v_mfma_f32_16x16x32_bf16 v[24:27], v[136:139], v[160:163], v[24:27]
	v_mfma_f32_16x16x32_bf16 v[16:19], v[128:131], v[168:171], v[16:19]
	v_mfma_f32_16x16x32_bf16 v[8:11], v[136:139], v[168:171], v[8:11]
	v_mfma_f32_16x16x32_bf16 v[60:63], v[132:135], v[148:151], v[60:63]
	v_mfma_f32_16x16x32_bf16 v[56:59], v[140:143], v[148:151], v[56:59]
	v_mfma_f32_16x16x32_bf16 v[48:51], v[132:135], v[156:159], v[48:51]
	v_mfma_f32_16x16x32_bf16 v[40:43], v[140:143], v[156:159], v[40:43]
	v_mfma_f32_16x16x32_bf16 v[32:35], v[132:135], v[164:167], v[32:35]
	v_mfma_f32_16x16x32_bf16 v[24:27], v[140:143], v[164:167], v[24:27]
	v_mfma_f32_16x16x32_bf16 v[16:19], v[132:135], v[172:175], v[16:19]
	s_barrier
; #define PG8_STAGE(bufoff, gbase, voff) do { _Pragma("unroll") for (int _i = 0; _i < 2; ++_i) \
;         __builtin_amdgcn_global_load_lds((const unsigned*)((const char*)(gbase) + (voff)[_i]), (LAS unsigned*)(lds + (bufoff) + ldsw + _i * 8192), 16, 0, 0); } while (0)
; #define PG8_WAIT_V(n) asm volatile("s_waitcnt vmcnt(" #n ")" ::: "memory")
; template <class Epi>
; __device__ __forceinline__ void gemm_phase(ldsp lds, const Gemm g, const StaticOrder& S, const Epi& E) {
;     ...
;         for (int t = 0; t < nt; t += 2) {
;             const bool last = (t == nt - 2);
;             const char* a1 = cA + (size_t)(t + 1) * kstep;
;             const char* a2 = last ? nA : cA + (size_t)(t + 2) * kstep; const char* b2 = last ? nB : cB + (size_t)(t + 2) * kstep;
;             const char* a3 = a2 + kstep; const char* b3 = b2 + kstep;
;             if constexpr (Epi::NPRE > 0) { if (last) E.pre(pre, cur, wr, fr); }
;             if constexpr (Epi::MID_T > 0) { if (t == Epi::MID_T) E.mid(acc, cur, wr, wc, fr, fq); }
;             PG8_LDB(B0, 0, 0); PG8_SCHED; PG8_LDA(At, 0, 0); PG8_STAGE(PG8_SA(1, 1), a1 + hstep, voffA);
;             PG8_WAIT_L(8); PG8_WAIT_V(10); PG8_BAR; PG8_WAIT_L(0); PG8_MMA(0, 0, At, B0); PG8_BAR; PG8_SCHED;
;             PG8_LDB(B1, 0, 1); PG8_STAGE(PG8_SB(0, 0), b2, voffB);
;             PG8_WAIT_V(10); PG8_BAR; PG8_WAIT_L(0); PG8_MMA(0, 1, At, B1); PG8_BAR;
;             PG8_LDA(At, 0, 1); PG8_STAGE(PG8_SA(0, 0), a2, voffA);
;             PG8_WAIT_V(10); PG8_BAR; PG8_WAIT_L(0); PG8_MMA(1, 0, At, B0); PG8_BAR; PG8_SCHED;
;             PG8_STAGE(PG8_SB(0, 1), b2 + hstep, voffB);
;             PG8_WAIT_V(10); PG8_BAR; PG8_MMA(1, 1, At, B1); PG8_BAR;
;             PG8_LDB(B0, 1, 0); PG8_SCHED; PG8_LDA(At, 1, 0); PG8_STAGE(PG8_SA(0, 1), a2 + hstep, voffA);
;             PG8_WAIT_L(8); PG8_WAIT_V(10); PG8_BAR; PG8_WAIT_L(0); PG8_MMA(0, 0, At, B0); PG8_BAR; PG8_SCHED;
;             PG8_LDB(B1, 1, 1); PG8_STAGE(PG8_SB(1, 0), b3, voffB);
;             PG8_WAIT_V(10); PG8_BAR; PG8_WAIT_L(0); PG8_MMA(0, 1, At, B1); PG8_BAR;
;             PG8_LDA(At, 1, 1); PG8_STAGE(PG8_SA(1, 0), a3, voffA);
;             PG8_WAIT_V(10); PG8_BAR; PG8_WAIT_L(0); PG8_MMA(1, 0, At, B0); PG8_BAR; PG8_SCHED;
;             PG8_STAGE(PG8_SB(1, 1), b3 + hstep, voffB);
;             PG8_WAIT_V(10); PG8_BAR; PG8_MMA(1, 1, At, B1); PG8_BAR;
;         }
	v_mfma_f32_16x16x32_bf16 v[8:11], v[140:143], v[172:175], v[8:11]
	s_setprio 0
	s_add_u32 s54, s26, 0x60000
	s_addc_u32 s55, s27, 0
	s_add_i32 s56, s46, s35
	v_lshl_add_u64 v[128:129], s[54:55], 0, v[194:195]
	s_mov_b32 m0, s56
	s_nop 0
	global_load_lds_dwordx4 v[128:129], off
	v_lshl_add_u64 v[128:129], s[54:55], 0, v[198:199]
	s_add_i32 m0, s56, 0x2000
	s_nop 0
	global_load_lds_dwordx4 v[128:129], off
	s_waitcnt vmcnt(10)
	s_barrier
	s_setprio 1
	v_mfma_f32_16x16x32_bf16 v[52:55], v[176:179], v[144:147], v[52:55]
	v_mfma_f32_16x16x32_bf16 v[44:47], v[184:187], v[144:147], v[44:47]
	v_mfma_f32_16x16x32_bf16 v[36:39], v[176:179], v[152:155], v[36:39]
	v_mfma_f32_16x16x32_bf16 v[28:31], v[184:187], v[152:155], v[28:31]
	v_mfma_f32_16x16x32_bf16 v[20:23], v[176:179], v[160:163], v[20:23]
	v_mfma_f32_16x16x32_bf16 v[12:15], v[184:187], v[160:163], v[12:15]
	v_mfma_f32_16x16x32_bf16 v[4:7], v[176:179], v[168:171], v[4:7]
	v_mfma_f32_16x16x32_bf16 v[0:3], v[184:187], v[168:171], v[0:3]
	v_mfma_f32_16x16x32_bf16 v[52:55], v[180:183], v[148:151], v[52:55]
	v_mfma_f32_16x16x32_bf16 v[44:47], v[188:191], v[148:151], v[44:47]
	v_mfma_f32_16x16x32_bf16 v[36:39], v[180:183], v[156:159], v[36:39]
	v_mfma_f32_16x16x32_bf16 v[28:31], v[188:191], v[156:159], v[28:31]
	v_mfma_f32_16x16x32_bf16 v[20:23], v[180:183], v[164:167], v[20:23]
	v_mfma_f32_16x16x32_bf16 v[12:15], v[188:191], v[164:167], v[12:15]
	v_mfma_f32_16x16x32_bf16 v[4:7], v[180:183], v[172:175], v[4:7]
	s_barrier
	v_mfma_f32_16x16x32_bf16 v[0:3], v[188:191], v[172:175], v[0:3]
	s_setprio 0
	s_add_i32 s54, 0, 0x18000
	v_add_u32_e32 v140, s54, v222
	ds_read_b128 v[128:131], v140
	ds_read_b128 v[132:135], v140 offset:1024
	ds_read_b128 v[136:139], v140 offset:2048
	ds_read_b128 v[140:143], v140 offset:3072
	s_add_u32 s28, s28, 0x60000
	s_addc_u32 s29, s29, 0
	s_mov_b32 m0, s38
	v_lshl_add_u64 v[176:177], s[28:29], 0, v[192:193]
	ds_read_b128 v[144:147], v224 offset:32768
	ds_read_b128 v[148:151], v224 offset:33792
	ds_read_b128 v[152:155], v224 offset:34816
	ds_read_b128 v[156:159], v224 offset:35840
	ds_read_b128 v[160:163], v224 offset:36864
	ds_read_b128 v[164:167], v224 offset:37888
	ds_read_b128 v[168:171], v224 offset:38912
	ds_read_b128 v[172:175], v224 offset:39936
	global_load_lds_dwordx4 v[176:177], off
	v_lshl_add_u64 v[176:177], s[28:29], 0, v[196:197]
	s_mov_b32 m0, s39
	s_nop 0
	global_load_lds_dwordx4 v[176:177], off
	s_waitcnt lgkmcnt(8)
	s_waitcnt vmcnt(10)
	s_barrier
	s_waitcnt lgkmcnt(0)
	s_setprio 1
	s_waitcnt lgkmcnt(0)
	v_mfma_f32_16x16x32_bf16 v[124:127], v[128:131], v[144:147], v[124:127]
	v_mfma_f32_16x16x32_bf16 v[120:123], v[136:139], v[144:147], v[120:123]
	v_mfma_f32_16x16x32_bf16 v[116:119], v[128:131], v[152:155], v[116:119]
	v_mfma_f32_16x16x32_bf16 v[104:107], v[136:139], v[152:155], v[104:107]
	v_mfma_f32_16x16x32_bf16 v[96:99], v[128:131], v[160:163], v[96:99]
	v_mfma_f32_16x16x32_bf16 v[88:91], v[136:139], v[160:163], v[88:91]
	v_mfma_f32_16x16x32_bf16 v[80:83], v[128:131], v[168:171], v[80:83]
	v_mfma_f32_16x16x32_bf16 v[72:75], v[136:139], v[168:171], v[72:75]
	v_mfma_f32_16x16x32_bf16 v[124:127], v[132:135], v[148:151], v[124:127]
	v_mfma_f32_16x16x32_bf16 v[120:123], v[140:143], v[148:151], v[120:123]
	v_mfma_f32_16x16x32_bf16 v[116:119], v[132:135], v[156:159], v[116:119]
	v_mfma_f32_16x16x32_bf16 v[104:107], v[140:143], v[156:159], v[104:107]
	v_mfma_f32_16x16x32_bf16 v[96:99], v[132:135], v[164:167], v[96:99]
	v_mfma_f32_16x16x32_bf16 v[88:91], v[140:143], v[164:167], v[88:91]
	v_mfma_f32_16x16x32_bf16 v[80:83], v[132:135], v[172:175], v[80:83]
	s_barrier
	v_mfma_f32_16x16x32_bf16 v[72:75], v[140:143], v[172:175], v[72:75]
	s_setprio 0
	s_add_i32 s28, 0, 0x1c000
	s_add_i32 s29, s54, s35
	v_add_u32_e32 v188, s28, v222
	v_lshl_add_u64 v[216:217], v[216:217], 0, s[12:13]
	s_mov_b32 m0, s29
	ds_read_b128 v[176:179], v188
	ds_read_b128 v[180:183], v188 offset:1024
	ds_read_b128 v[184:187], v188 offset:2048
	ds_read_b128 v[188:191], v188 offset:3072
	global_load_lds_dwordx4 v[216:217], off
	v_lshl_add_u64 v[216:217], v[218:219], 0, s[12:13]
	s_add_i32 m0, s29, 0x2000
	s_nop 0
	global_load_lds_dwordx4 v[216:217], off
	s_waitcnt vmcnt(10)
	s_barrier
; #define PG8_STAGE(bufoff, gbase, voff) do { _Pragma("unroll") for (int _i = 0; _i < 2; ++_i) \
;         __builtin_amdgcn_global_load_lds((const unsigned*)((const char*)(gbase) + (voff)[_i]), (LAS unsigned*)(lds + (bufoff) + ldsw + _i * 8192), 16, 0, 0); } while (0)
; #define PG8_WAIT_V(n) asm volatile("s_waitcnt vmcnt(" #n ")" ::: "memory")
; template <class Epi>
; __device__ __forceinline__ void gemm_phase(ldsp lds, const Gemm g, const StaticOrder& S, const Epi& E) {
;     ...
;         for (int t = 0; t < nt; t += 2) {
;             const bool last = (t == nt - 2);
;             const char* a1 = cA + (size_t)(t + 1) * kstep;
;             const char* a2 = last ? nA : cA + (size_t)(t + 2) * kstep; const char* b2 = last ? nB : cB + (size_t)(t + 2) * kstep;
;             const char* a3 = a2 + kstep; const char* b3 = b2 + kstep;
;             if constexpr (Epi::NPRE > 0) { if (last) E.pre(pre, cur, wr, fr); }
;             if constexpr (Epi::MID_T > 0) { if (t == Epi::MID_T) E.mid(acc, cur, wr, wc, fr, fq); }
;             PG8_LDB(B0, 0, 0); PG8_SCHED; PG8_LDA(At, 0, 0); PG8_STAGE(PG8_SA(1, 1), a1 + hstep, voffA);
;             PG8_WAIT_L(8); PG8_WAIT_V(10); PG8_BAR; PG8_WAIT_L(0); PG8_MMA(0, 0, At, B0); PG8_BAR; PG8_SCHED;
;             PG8_LDB(B1, 0, 1); PG8_STAGE(PG8_SB(0, 0), b2, voffB);
;             PG8_WAIT_V(10); PG8_BAR; PG8_WAIT_L(0); PG8_MMA(0, 1, At, B1); PG8_BAR;
;             PG8_LDA(At, 0, 1); PG8_STAGE(PG8_SA(0, 0), a2, voffA);
;             PG8_WAIT_V(10); PG8_BAR; PG8_WAIT_L(0); PG8_MMA(1, 0, At, B0); PG8_BAR; PG8_SCHED;
;             PG8_STAGE(PG8_SB(0, 1), b2 + hstep, voffB);
;             PG8_WAIT_V(10); PG8_BAR; PG8_MMA(1, 1, At, B1); PG8_BAR;
;             PG8_LDB(B0, 1, 0); PG8_SCHED; PG8_LDA(At, 1, 0); PG8_STAGE(PG8_SA(0, 1), a2 + hstep, voffA);
;             PG8_WAIT_L(8); PG8_WAIT_V(10); PG8_BAR; PG8_WAIT_L(0); PG8_MMA(0, 0, At, B0); PG8_BAR; PG8_SCHED;
;             PG8_LDB(B1, 1, 1); PG8_STAGE(PG8_SB(1, 0), b3, voffB);
;             PG8_WAIT_V(10); PG8_BAR; PG8_WAIT_L(0); PG8_MMA(0, 1, At, B1); PG8_BAR;
;             PG8_LDA(At, 1, 1); PG8_STAGE(PG8_SA(1, 0), a3, voffA);
;             PG8_WAIT_V(10); PG8_BAR; PG8_WAIT_L(0); PG8_MMA(1, 0, At, B0); PG8_BAR; PG8_SCHED;
;             PG8_STAGE(PG8_SB(1, 1), b3 + hstep, voffB);
;             PG8_WAIT_V(10); PG8_BAR; PG8_MMA(1, 1, At, B1); PG8_BAR;
;         }
	s_waitcnt lgkmcnt(0)
	s_setprio 1
	s_waitcnt lgkmcnt(0)
	v_mfma_f32_16x16x32_bf16 v[112:115], v[176:179], v[144:147], v[112:115]
	v_mfma_f32_16x16x32_bf16 v[108:111], v[184:187], v[144:147], v[108:111]
	v_mfma_f32_16x16x32_bf16 v[100:103], v[176:179], v[152:155], v[100:103]
	v_mfma_f32_16x16x32_bf16 v[92:95], v[184:187], v[152:155], v[92:95]
	v_mfma_f32_16x16x32_bf16 v[84:87], v[176:179], v[160:163], v[84:87]
	v_mfma_f32_16x16x32_bf16 v[76:79], v[184:187], v[160:163], v[76:79]
	v_mfma_f32_16x16x32_bf16 v[68:71], v[176:179], v[168:171], v[68:71]
	v_mfma_f32_16x16x32_bf16 v[64:67], v[184:187], v[168:171], v[64:67]
	v_mfma_f32_16x16x32_bf16 v[112:115], v[180:183], v[148:151], v[112:115]
	v_mfma_f32_16x16x32_bf16 v[108:111], v[188:191], v[148:151], v[108:111]
	v_mfma_f32_16x16x32_bf16 v[100:103], v[180:183], v[156:159], v[100:103]
	v_mfma_f32_16x16x32_bf16 v[92:95], v[188:191], v[156:159], v[92:95]
	v_mfma_f32_16x16x32_bf16 v[84:87], v[180:183], v[164:167], v[84:87]
	v_mfma_f32_16x16x32_bf16 v[76:79], v[188:191], v[164:167], v[76:79]
	v_mfma_f32_16x16x32_bf16 v[68:71], v[180:183], v[172:175], v[68:71]
	s_barrier
	v_mfma_f32_16x16x32_bf16 v[64:67], v[188:191], v[172:175], v[64:67]
	s_setprio 0
	s_mov_b32 m0, s41
	v_lshl_add_u64 v[216:217], v[226:227], 0, s[12:13]
	ds_read_b128 v[144:147], v224 offset:49152
	ds_read_b128 v[148:151], v224 offset:50176
	ds_read_b128 v[152:155], v224 offset:51200
	ds_read_b128 v[156:159], v224 offset:52224
	ds_read_b128 v[160:163], v224 offset:53248
	ds_read_b128 v[164:167], v224 offset:54272
	ds_read_b128 v[168:171], v224 offset:55296
	ds_read_b128 v[172:175], v224 offset:56320
	global_load_lds_dwordx4 v[216:217], off
	v_lshl_add_u64 v[216:217], v[228:229], 0, s[12:13]
	s_mov_b32 m0, s42
	s_nop 0
	global_load_lds_dwordx4 v[216:217], off
	s_waitcnt vmcnt(10)
	s_barrier
	s_waitcnt lgkmcnt(0)
	s_setprio 1
	s_waitcnt lgkmcnt(0)
	v_mfma_f32_16x16x32_bf16 v[60:63], v[128:131], v[144:147], v[60:63]
	v_mfma_f32_16x16x32_bf16 v[56:59], v[136:139], v[144:147], v[56:59]
	v_mfma_f32_16x16x32_bf16 v[48:51], v[128:131], v[152:155], v[48:51]
	v_mfma_f32_16x16x32_bf16 v[40:43], v[136:139], v[152:155], v[40:43]
	v_mfma_f32_16x16x32_bf16 v[32:35], v[128:131], v[160:163], v[32:35]
	v_mfma_f32_16x16x32_bf16 v[24:27], v[136:139], v[160:163], v[24:27]
	v_mfma_f32_16x16x32_bf16 v[16:19], v[128:131], v[168:171], v[16:19]
	v_mfma_f32_16x16x32_bf16 v[8:11], v[136:139], v[168:171], v[8:11]
	v_mfma_f32_16x16x32_bf16 v[60:63], v[132:135], v[148:151], v[60:63]
	v_mfma_f32_16x16x32_bf16 v[56:59], v[140:143], v[148:151], v[56:59]
	v_mfma_f32_16x16x32_bf16 v[48:51], v[132:135], v[156:159], v[48:51]
	v_mfma_f32_16x16x32_bf16 v[40:43], v[140:143], v[156:159], v[40:43]
	v_mfma_f32_16x16x32_bf16 v[32:35], v[132:135], v[164:167], v[32:35]
	v_mfma_f32_16x16x32_bf16 v[24:27], v[140:143], v[164:167], v[24:27]
	v_mfma_f32_16x16x32_bf16 v[16:19], v[132:135], v[172:175], v[16:19]
	s_barrier
	v_mfma_f32_16x16x32_bf16 v[8:11], v[140:143], v[172:175], v[8:11]
	s_setprio 0
	s_add_u32 s26, s26, 0x60080
	s_addc_u32 s27, s27, 0
	s_add_i32 s28, s28, s35
	v_lshl_add_u64 v[128:129], s[26:27], 0, v[194:195]
	s_mov_b32 m0, s28
	s_nop 0
	global_load_lds_dwordx4 v[128:129], off
	v_lshl_add_u64 v[128:129], s[26:27], 0, v[198:199]
	s_add_i32 m0, s28, 0x2000
	s_nop 0
	global_load_lds_dwordx4 v[128:129], off
	s_waitcnt vmcnt(10)
	s_barrier
	s_setprio 1
	v_mfma_f32_16x16x32_bf16 v[52:55], v[176:179], v[144:147], v[52:55]
	v_mfma_f32_16x16x32_bf16 v[44:47], v[184:187], v[144:147], v[44:47]
	v_mfma_f32_16x16x32_bf16 v[36:39], v[176:179], v[152:155], v[36:39]
	v_mfma_f32_16x16x32_bf16 v[28:31], v[184:187], v[152:155], v[28:31]
	v_mfma_f32_16x16x32_bf16 v[20:23], v[176:179], v[160:163], v[20:23]
	v_mfma_f32_16x16x32_bf16 v[12:15], v[184:187], v[160:163], v[12:15]
	v_mfma_f32_16x16x32_bf16 v[4:7], v[176:179], v[168:171], v[4:7]
	v_mfma_f32_16x16x32_bf16 v[0:3], v[184:187], v[168:171], v[0:3]
	v_mfma_f32_16x16x32_bf16 v[52:55], v[180:183], v[148:151], v[52:55]
	v_mfma_f32_16x16x32_bf16 v[44:47], v[188:191], v[148:151], v[44:47]
	v_mfma_f32_16x16x32_bf16 v[36:39], v[180:183], v[156:159], v[36:39]
	v_mfma_f32_16x16x32_bf16 v[28:31], v[188:191], v[156:159], v[28:31]
	v_mfma_f32_16x16x32_bf16 v[20:23], v[180:183], v[164:167], v[20:23]
	v_mfma_f32_16x16x32_bf16 v[12:15], v[188:191], v[164:167], v[12:15]
	v_mfma_f32_16x16x32_bf16 v[4:7], v[180:183], v[172:175], v[4:7]
	s_barrier
	v_mfma_f32_16x16x32_bf16 v[0:3], v[188:191], v[172:175], v[0:3]
	s_setprio 0
	s_add_i32 s53, s53, 2
	s_add_u32 s24, s24, 0x100
	s_addc_u32 s25, s25, 0
	s_cmp_gt_u32 s53, 21
	s_cbranch_scc1 .LBB0_642

; #define PG8_STAGE(bufoff, gbase, voff) do { _Pragma("unroll") for (int _i = 0; _i < 2; ++_i) \
;         __builtin_amdgcn_global_load_lds((const unsigned*)((const char*)(gbase) + (voff)[_i]), (LAS unsigned*)(lds + (bufoff) + ldsw + _i * 8192), 16, 0, 0); } while (0)
; #define PG8_WAIT_V(n) asm volatile("s_waitcnt vmcnt(" #n ")" ::: "memory")
; template <class Epi>
; __device__ __forceinline__ void gemm_phase(ldsp lds, const Gemm g, const StaticOrder& S, const Epi& E) {
;     ...
;         for (int t = 0; t < nt; t += 2) {
;             const bool last = (t == nt - 2);
;             const char* a1 = cA + (size_t)(t + 1) * kstep;
;             const char* a2 = last ? nA : cA + (size_t)(t + 2) * kstep; const char* b2 = last ? nB : cB + (size_t)(t + 2) * kstep;
;             const char* a3 = a2 + kstep; const char* b3 = b2 + kstep;
;             if constexpr (Epi::NPRE > 0) { if (last) E.pre(pre, cur, wr, fr); }
;             if constexpr (Epi::MID_T > 0) { if (t == Epi::MID_T) E.mid(acc, cur, wr, wc, fr, fq); }
;             PG8_LDB(B0, 0, 0); PG8_SCHED; PG8_LDA(At, 0, 0); PG8_STAGE(PG8_SA(1, 1), a1 + hstep, voffA);
;             PG8_WAIT_L(8); PG8_WAIT_V(10); PG8_BAR; PG8_WAIT_L(0); PG8_MMA(0, 0, At, B0); PG8_BAR; PG8_SCHED;
;             PG8_LDB(B1, 0, 1); PG8_STAGE(PG8_SB(0, 0), b2, voffB);
;             PG8_WAIT_V(10); PG8_BAR; PG8_WAIT_L(0); PG8_MMA(0, 1, At, B1); PG8_BAR;
;             PG8_LDA(At, 0, 1); PG8_STAGE(PG8_SA(0, 0), a2, voffA);
;             PG8_WAIT_V(10); PG8_BAR; PG8_WAIT_L(0); PG8_MMA(1, 0, At, B0); PG8_BAR; PG8_SCHED;
;             PG8_STAGE(PG8_SB(0, 1), b2 + hstep, voffB);
;             PG8_WAIT_V(10); PG8_BAR; PG8_MMA(1, 1, At, B1); PG8_BAR;
;             PG8_LDB(B0, 1, 0); PG8_SCHED; PG8_LDA(At, 1, 0); PG8_STAGE(PG8_SA(0, 1), a2 + hstep, voffA);
;             PG8_WAIT_L(8); PG8_WAIT_V(10); PG8_BAR; PG8_WAIT_L(0); PG8_MMA(0, 0, At, B0); PG8_BAR; PG8_SCHED;
;             PG8_LDB(B1, 1, 1); PG8_STAGE(PG8_SB(1, 0), b3, voffB);
;             PG8_WAIT_V(10); PG8_BAR; PG8_WAIT_L(0); PG8_MMA(0, 1, At, B1); PG8_BAR;
;             PG8_LDA(At, 1, 1); PG8_STAGE(PG8_SA(1, 0), a3, voffA);
;             PG8_WAIT_V(10); PG8_BAR; PG8_WAIT_L(0); PG8_MMA(1, 0, At, B0); PG8_BAR; PG8_SCHED;
;             PG8_STAGE(PG8_SB(1, 1), b3 + hstep, voffB);
;             PG8_WAIT_V(10); PG8_BAR; PG8_MMA(1, 1, At, B1); PG8_BAR;
;         }
.LBB0_733:
	ds_read_b128 v[128:131], v211
	ds_read_b128 v[132:135], v211 offset:1024
	ds_read_b128 v[136:139], v211 offset:2048
	ds_read_b128 v[140:143], v211 offset:3072
	s_add_u32 s24, s22, 0xfff80080
	s_addc_u32 s25, s23, -1
	s_cmp_eq_u32 s46, 28
	s_cselect_b32 s27, s13, s25
	s_cselect_b32 s26, s19, s24
	s_cselect_b32 s25, s11, s45
	s_cselect_b32 s24, s43, s44
	v_lshl_add_u64 v[192:193], s[22:23], 0, v[184:185]
	s_add_i32 m0, s21, 0xc000
	ds_read_b128 v[144:147], v212
	ds_read_b128 v[148:151], v212 offset:1024
	ds_read_b128 v[152:155], v212 offset:2048
	ds_read_b128 v[156:159], v212 offset:3072
	ds_read_b128 v[160:163], v212 offset:4096
	ds_read_b128 v[164:167], v212 offset:5120
	ds_read_b128 v[168:171], v212 offset:6144
	ds_read_b128 v[172:175], v212 offset:7168
	global_load_lds_dwordx4 v[192:193], off
	v_lshl_add_u64 v[192:193], s[22:23], 0, v[186:187]
	s_add_i32 m0, s21, 0xe000
	s_nop 0
	global_load_lds_dwordx4 v[192:193], off
	s_waitcnt lgkmcnt(8)
	s_waitcnt vmcnt(10)
	s_barrier
	s_waitcnt lgkmcnt(0)
	s_setprio 1
	s_waitcnt lgkmcnt(0)
	v_mfma_f32_16x16x32_bf16 v[124:127], v[128:131], v[144:147], v[124:127]
	v_mfma_f32_16x16x32_bf16 v[120:123], v[136:139], v[144:147], v[120:123]
	v_mfma_f32_16x16x32_bf16 v[108:111], v[128:131], v[152:155], v[108:111]
	v_mfma_f32_16x16x32_bf16 v[104:107], v[136:139], v[152:155], v[104:107]
	v_mfma_f32_16x16x32_bf16 v[92:95], v[128:131], v[160:163], v[92:95]
	v_mfma_f32_16x16x32_bf16 v[88:91], v[136:139], v[160:163], v[88:91]
	v_mfma_f32_16x16x32_bf16 v[76:79], v[128:131], v[168:171], v[76:79]
	v_mfma_f32_16x16x32_bf16 v[72:75], v[136:139], v[168:171], v[72:75]
	v_mfma_f32_16x16x32_bf16 v[124:127], v[132:135], v[148:151], v[124:127]
	v_mfma_f32_16x16x32_bf16 v[120:123], v[140:143], v[148:151], v[120:123]
	v_mfma_f32_16x16x32_bf16 v[108:111], v[132:135], v[156:159], v[108:111]
	v_mfma_f32_16x16x32_bf16 v[104:107], v[140:143], v[156:159], v[104:107]
	v_mfma_f32_16x16x32_bf16 v[92:95], v[132:135], v[164:167], v[92:95]
	v_mfma_f32_16x16x32_bf16 v[88:91], v[140:143], v[164:167], v[88:91]
	v_mfma_f32_16x16x32_bf16 v[76:79], v[132:135], v[172:175], v[76:79]
	s_barrier
	v_mfma_f32_16x16x32_bf16 v[72:75], v[140:143], v[172:175], v[72:75]
	s_setprio 0
	s_add_i32 s47, s40, s29
	v_lshl_add_u64 v[216:217], s[24:25], 0, v[178:179]
	s_mov_b32 m0, s47
	ds_read_b128 v[192:195], v213
	ds_read_b128 v[196:199], v213 offset:1024
	ds_read_b128 v[200:203], v213 offset:2048
	ds_read_b128 v[204:207], v213 offset:3072
	global_load_lds_dwordx4 v[216:217], off
	v_lshl_add_u64 v[218:219], s[24:25], 0, v[182:183]
	s_add_i32 m0, s47, 0x2000
	s_nop 0
	global_load_lds_dwordx4 v[218:219], off
	s_waitcnt vmcnt(10)
	s_barrier
	s_waitcnt lgkmcnt(0)
	s_setprio 1
	s_waitcnt lgkmcnt(0)
	v_mfma_f32_16x16x32_bf16 v[116:119], v[192:195], v[144:147], v[116:119]
	v_mfma_f32_16x16x32_bf16 v[112:115], v[200:203], v[144:147], v[112:115]
	v_mfma_f32_16x16x32_bf16 v[100:103], v[192:195], v[152:155], v[100:103]
	v_mfma_f32_16x16x32_bf16 v[96:99], v[200:203], v[152:155], v[96:99]
	v_mfma_f32_16x16x32_bf16 v[84:87], v[192:195], v[160:163], v[84:87]
	v_mfma_f32_16x16x32_bf16 v[80:83], v[200:203], v[160:163], v[80:83]
	v_mfma_f32_16x16x32_bf16 v[68:71], v[192:195], v[168:171], v[68:71]
	v_mfma_f32_16x16x32_bf16 v[64:67], v[200:203], v[168:171], v[64:67]
	v_mfma_f32_16x16x32_bf16 v[116:119], v[196:199], v[148:151], v[116:119]
	v_mfma_f32_16x16x32_bf16 v[112:115], v[204:207], v[148:151], v[112:115]
	v_mfma_f32_16x16x32_bf16 v[100:103], v[196:199], v[156:159], v[100:103]
	v_mfma_f32_16x16x32_bf16 v[96:99], v[204:207], v[156:159], v[96:99]
	v_mfma_f32_16x16x32_bf16 v[84:87], v[196:199], v[164:167], v[84:87]
	v_mfma_f32_16x16x32_bf16 v[80:83], v[204:207], v[164:167], v[80:83]
	v_mfma_f32_16x16x32_bf16 v[68:71], v[196:199], v[172:175], v[68:71]
	s_barrier
	v_mfma_f32_16x16x32_bf16 v[64:67], v[204:207], v[172:175], v[64:67]
	s_setprio 0
	s_mov_b32 m0, s21
	v_lshl_add_u64 v[222:223], s[26:27], 0, v[176:177]
	ds_read_b128 v[144:147], v212 offset:16384
	ds_read_b128 v[148:151], v212 offset:17408
	ds_read_b128 v[152:155], v212 offset:18432
	ds_read_b128 v[156:159], v212 offset:19456
	ds_read_b128 v[160:163], v212 offset:20480
	ds_read_b128 v[164:167], v212 offset:21504
	ds_read_b128 v[168:171], v212 offset:22528
	ds_read_b128 v[172:175], v212 offset:23552
	global_load_lds_dwordx4 v[222:223], off
	v_lshl_add_u64 v[224:225], s[26:27], 0, v[180:181]
	s_mov_b32 m0, s30
	s_nop 0
	global_load_lds_dwordx4 v[224:225], off
	s_waitcnt vmcnt(10)
	s_barrier
	s_waitcnt lgkmcnt(0)
	s_setprio 1
	s_waitcnt lgkmcnt(0)
	v_mfma_f32_16x16x32_bf16 v[60:63], v[128:131], v[144:147], v[60:63]
	v_mfma_f32_16x16x32_bf16 v[56:59], v[136:139], v[144:147], v[56:59]
	v_mfma_f32_16x16x32_bf16 v[44:47], v[128:131], v[152:155], v[44:47]
	v_mfma_f32_16x16x32_bf16 v[40:43], v[136:139], v[152:155], v[40:43]
	v_mfma_f32_16x16x32_bf16 v[28:31], v[128:131], v[160:163], v[28:31]
	v_mfma_f32_16x16x32_bf16 v[24:27], v[136:139], v[160:163], v[24:27]
	v_mfma_f32_16x16x32_bf16 v[12:15], v[128:131], v[168:171], v[12:15]
	v_mfma_f32_16x16x32_bf16 v[8:11], v[136:139], v[168:171], v[8:11]
	v_mfma_f32_16x16x32_bf16 v[60:63], v[132:135], v[148:151], v[60:63]
	v_mfma_f32_16x16x32_bf16 v[56:59], v[140:143], v[148:151], v[56:59]
	v_mfma_f32_16x16x32_bf16 v[44:47], v[132:135], v[156:159], v[44:47]
	v_mfma_f32_16x16x32_bf16 v[40:43], v[140:143], v[156:159], v[40:43]
	v_mfma_f32_16x16x32_bf16 v[28:31], v[132:135], v[164:167], v[28:31]
	v_mfma_f32_16x16x32_bf16 v[24:27], v[140:143], v[164:167], v[24:27]
	v_mfma_f32_16x16x32_bf16 v[12:15], v[132:135], v[172:175], v[12:15]
	s_barrier
; #define PG8_STAGE(bufoff, gbase, voff) do { _Pragma("unroll") for (int _i = 0; _i < 2; ++_i) \
;         __builtin_amdgcn_global_load_lds((const unsigned*)((const char*)(gbase) + (voff)[_i]), (LAS unsigned*)(lds + (bufoff) + ldsw + _i * 8192), 16, 0, 0); } while (0)
; #define PG8_LDA(dst, b, h) do { _Pragma("unroll") for (int m = 0; m < 4; ++m) _Pragma("unroll") for (int k = 0; k < 2; ++k) dst[m][k] = *(const LAS bf16x8*)(lds + PG8_SA(b, h) + aoff + m * 2048 + k * 1024); } while (0)
; #define PG8_LDB(dst, b, h) do { _Pragma("unroll") for (int n = 0; n < 2; ++n) _Pragma("unroll") for (int k = 0; k < 2; ++k) dst[n][k] = *(const LAS bf16x8*)(lds + PG8_SB(b, h) + boff + n * 2048 + k * 1024); } while (0)
; #define PG8_MMA(ai, bj, At, Bt) do { __builtin_amdgcn_s_setprio(1); _Pragma("unroll") for (int m = 0; m < 4; ++m) _Pragma("unroll") for (int n = 0; n < 2; ++n) _Pragma("unroll") for (int k = 0; k < 2; ++k) \
;         acc[ai][bj][m][n] = __builtin_amdgcn_mfma_f32_16x16x32_bf16(Bt[n][k], At[m][k], acc[ai][bj][m][n], 0, 0, 0); __builtin_amdgcn_s_setprio(0); } while (0)
; #define PG8_WAIT_V(n) asm volatile("s_waitcnt vmcnt(" #n ")" ::: "memory")
; #define PG8_WAIT_L(n) asm volatile("s_waitcnt lgkmcnt(" #n ")" ::: "memory")
; #define PG8_BAR __builtin_amdgcn_s_barrier()
; #define PG8_SCHED __builtin_amdgcn_sched_barrier(0)
; template <class Epi>
; __device__ __forceinline__ void gemm_phase(ldsp lds, const Gemm g, const StaticOrder& S, const Epi& E) {
;     ...
;             PG8_WAIT_V(10); PG8_BAR; PG8_WAIT_L(0); PG8_MMA(1, 0, At, B0); PG8_BAR; PG8_SCHED;
;             PG8_STAGE(PG8_SB(0, 1), b2 + hstep, voffB);
;             PG8_WAIT_V(10); PG8_BAR; PG8_MMA(1, 1, At, B1); PG8_BAR;
;             PG8_LDB(B0, 1, 0); PG8_SCHED; PG8_LDA(At, 1, 0); PG8_STAGE(PG8_SA(0, 1), a2 + hstep, voffA);
;             PG8_WAIT_L(8); PG8_WAIT_V(10); PG8_BAR; PG8_WAIT_L(0); PG8_MMA(0, 0, At, B0); PG8_BAR; PG8_SCHED;
;             PG8_LDB(B1, 1, 1); PG8_STAGE(PG8_SB(1, 0), b3, voffB);
;             PG8_WAIT_V(10); PG8_BAR; PG8_WAIT_L(0); PG8_MMA(0, 1, At, B1); PG8_BAR;
	v_mfma_f32_16x16x32_bf16 v[8:11], v[140:143], v[172:175], v[8:11]
	s_setprio 0
	s_add_u32 s50, s24, 0x80000
	s_addc_u32 s51, s25, 0
	s_add_i32 s47, s41, s29
	v_lshl_add_u64 v[128:129], s[50:51], 0, v[178:179]
	s_mov_b32 m0, s47
	s_nop 0
	global_load_lds_dwordx4 v[128:129], off
	v_lshl_add_u64 v[128:129], s[50:51], 0, v[182:183]
	s_add_i32 m0, s47, 0x2000
	s_nop 0
	global_load_lds_dwordx4 v[128:129], off
	s_waitcnt vmcnt(10)
	s_barrier
	s_setprio 1
	v_mfma_f32_16x16x32_bf16 v[52:55], v[192:195], v[144:147], v[52:55]
	v_mfma_f32_16x16x32_bf16 v[48:51], v[200:203], v[144:147], v[48:51]
	v_mfma_f32_16x16x32_bf16 v[36:39], v[192:195], v[152:155], v[36:39]
	v_mfma_f32_16x16x32_bf16 v[32:35], v[200:203], v[152:155], v[32:35]
	v_mfma_f32_16x16x32_bf16 v[20:23], v[192:195], v[160:163], v[20:23]
	v_mfma_f32_16x16x32_bf16 v[16:19], v[200:203], v[160:163], v[16:19]
	v_mfma_f32_16x16x32_bf16 v[4:7], v[192:195], v[168:171], v[4:7]
	v_mfma_f32_16x16x32_bf16 v[0:3], v[200:203], v[168:171], v[0:3]
	v_mfma_f32_16x16x32_bf16 v[52:55], v[196:199], v[148:151], v[52:55]
	v_mfma_f32_16x16x32_bf16 v[48:51], v[204:207], v[148:151], v[48:51]
	v_mfma_f32_16x16x32_bf16 v[36:39], v[196:199], v[156:159], v[36:39]
	v_mfma_f32_16x16x32_bf16 v[32:35], v[204:207], v[156:159], v[32:35]
	v_mfma_f32_16x16x32_bf16 v[20:23], v[196:199], v[164:167], v[20:23]
	v_mfma_f32_16x16x32_bf16 v[16:19], v[204:207], v[164:167], v[16:19]
	v_mfma_f32_16x16x32_bf16 v[4:7], v[196:199], v[172:175], v[4:7]
	s_barrier
	v_mfma_f32_16x16x32_bf16 v[0:3], v[204:207], v[172:175], v[0:3]
	s_setprio 0
	s_add_i32 s47, 0, 0x18000
	v_add_u32_e32 v140, s47, v209
	ds_read_b128 v[128:131], v140
	ds_read_b128 v[132:135], v140 offset:1024
	ds_read_b128 v[136:139], v140 offset:2048
	ds_read_b128 v[140:143], v140 offset:3072
	s_add_u32 s26, s26, 0x80000
	s_addc_u32 s27, s27, 0
	s_mov_b32 m0, s31
	v_lshl_add_u64 v[192:193], s[26:27], 0, v[176:177]
	ds_read_b128 v[144:147], v212 offset:32768
	ds_read_b128 v[148:151], v212 offset:33792
	ds_read_b128 v[152:155], v212 offset:34816
	ds_read_b128 v[156:159], v212 offset:35840
	ds_read_b128 v[160:163], v212 offset:36864
	ds_read_b128 v[164:167], v212 offset:37888
	ds_read_b128 v[168:171], v212 offset:38912
	ds_read_b128 v[172:175], v212 offset:39936
	global_load_lds_dwordx4 v[192:193], off
	v_lshl_add_u64 v[192:193], s[26:27], 0, v[180:181]
	s_mov_b32 m0, s33
	s_nop 0
	global_load_lds_dwordx4 v[192:193], off
	s_waitcnt lgkmcnt(8)
	s_waitcnt vmcnt(10)
	s_barrier
	s_waitcnt lgkmcnt(0)
	s_setprio 1
	s_waitcnt lgkmcnt(0)
	v_mfma_f32_16x16x32_bf16 v[124:127], v[128:131], v[144:147], v[124:127]
	v_mfma_f32_16x16x32_bf16 v[120:123], v[136:139], v[144:147], v[120:123]
	v_mfma_f32_16x16x32_bf16 v[108:111], v[128:131], v[152:155], v[108:111]
	v_mfma_f32_16x16x32_bf16 v[104:107], v[136:139], v[152:155], v[104:107]
	v_mfma_f32_16x16x32_bf16 v[92:95], v[128:131], v[160:163], v[92:95]
	v_mfma_f32_16x16x32_bf16 v[88:91], v[136:139], v[160:163], v[88:91]
	v_mfma_f32_16x16x32_bf16 v[76:79], v[128:131], v[168:171], v[76:79]
	v_mfma_f32_16x16x32_bf16 v[72:75], v[136:139], v[168:171], v[72:75]
	v_mfma_f32_16x16x32_bf16 v[124:127], v[132:135], v[148:151], v[124:127]
	v_mfma_f32_16x16x32_bf16 v[120:123], v[140:143], v[148:151], v[120:123]
	v_mfma_f32_16x16x32_bf16 v[108:111], v[132:135], v[156:159], v[108:111]
	v_mfma_f32_16x16x32_bf16 v[104:107], v[140:143], v[156:159], v[104:107]
	v_mfma_f32_16x16x32_bf16 v[92:95], v[132:135], v[164:167], v[92:95]
	v_mfma_f32_16x16x32_bf16 v[88:91], v[140:143], v[164:167], v[88:91]
	v_mfma_f32_16x16x32_bf16 v[76:79], v[132:135], v[172:175], v[76:79]
	s_barrier
	v_mfma_f32_16x16x32_bf16 v[72:75], v[140:143], v[172:175], v[72:75]
	s_setprio 0
	s_add_i32 s26, 0, 0x1c000
	s_add_i32 s27, s47, s29
	v_add_u32_e32 v204, s26, v209
	v_lshl_add_u64 v[216:217], v[216:217], 0, s[8:9]
	s_mov_b32 m0, s27
	ds_read_b128 v[192:195], v204
	ds_read_b128 v[196:199], v204 offset:1024
	ds_read_b128 v[200:203], v204 offset:2048
	ds_read_b128 v[204:207], v204 offset:3072
	global_load_lds_dwordx4 v[216:217], off
	v_lshl_add_u64 v[216:217], v[218:219], 0, s[8:9]
	s_add_i32 m0, s27, 0x2000
	s_nop 0
	global_load_lds_dwordx4 v[216:217], off
	s_waitcnt vmcnt(10)
	s_barrier
	s_waitcnt lgkmcnt(0)
	s_setprio 1
	s_waitcnt lgkmcnt(0)
	v_mfma_f32_16x16x32_bf16 v[116:119], v[192:195], v[144:147], v[116:119]
	v_mfma_f32_16x16x32_bf16 v[112:115], v[200:203], v[144:147], v[112:115]
	v_mfma_f32_16x16x32_bf16 v[100:103], v[192:195], v[152:155], v[100:103]
	v_mfma_f32_16x16x32_bf16 v[96:99], v[200:203], v[152:155], v[96:99]
	v_mfma_f32_16x16x32_bf16 v[84:87], v[192:195], v[160:163], v[84:87]
	v_mfma_f32_16x16x32_bf16 v[80:83], v[200:203], v[160:163], v[80:83]
	v_mfma_f32_16x16x32_bf16 v[68:71], v[192:195], v[168:171], v[68:71]
	v_mfma_f32_16x16x32_bf16 v[64:67], v[200:203], v[168:171], v[64:67]
	v_mfma_f32_16x16x32_bf16 v[116:119], v[196:199], v[148:151], v[116:119]
	v_mfma_f32_16x16x32_bf16 v[112:115], v[204:207], v[148:151], v[112:115]
	v_mfma_f32_16x16x32_bf16 v[100:103], v[196:199], v[156:159], v[100:103]
	v_mfma_f32_16x16x32_bf16 v[96:99], v[204:207], v[156:159], v[96:99]
	v_mfma_f32_16x16x32_bf16 v[84:87], v[196:199], v[164:167], v[84:87]
	v_mfma_f32_16x16x32_bf16 v[80:83], v[204:207], v[164:167], v[80:83]
	v_mfma_f32_16x16x32_bf16 v[68:71], v[196:199], v[172:175], v[68:71]
	s_barrier
; #define PG8_STAGE(bufoff, gbase, voff) do { _Pragma("unroll") for (int _i = 0; _i < 2; ++_i) \
;         __builtin_amdgcn_global_load_lds((const unsigned*)((const char*)(gbase) + (voff)[_i]), (LAS unsigned*)(lds + (bufoff) + ldsw + _i * 8192), 16, 0, 0); } while (0)
; #define PG8_LDA(dst, b, h) do { _Pragma("unroll") for (int m = 0; m < 4; ++m) _Pragma("unroll") for (int k = 0; k < 2; ++k) dst[m][k] = *(const LAS bf16x8*)(lds + PG8_SA(b, h) + aoff + m * 2048 + k * 1024); } while (0)
; #define PG8_MMA(ai, bj, At, Bt) do { __builtin_amdgcn_s_setprio(1); _Pragma("unroll") for (int m = 0; m < 4; ++m) _Pragma("unroll") for (int n = 0; n < 2; ++n) _Pragma("unroll") for (int k = 0; k < 2; ++k) \
;         acc[ai][bj][m][n] = __builtin_amdgcn_mfma_f32_16x16x32_bf16(Bt[n][k], At[m][k], acc[ai][bj][m][n], 0, 0, 0); __builtin_amdgcn_s_setprio(0); } while (0)
; #define PG8_WAIT_V(n) asm volatile("s_waitcnt vmcnt(" #n ")" ::: "memory")
; #define PG8_WAIT_L(n) asm volatile("s_waitcnt lgkmcnt(" #n ")" ::: "memory")
; #define PG8_BAR __builtin_amdgcn_s_barrier()
; #define PG8_SCHED __builtin_amdgcn_sched_barrier(0)
; template <class Epi>
; __device__ __forceinline__ void gemm_phase(ldsp lds, const Gemm g, const StaticOrder& S, const Epi& E) {
;     ...
;             PG8_WAIT_V(10); PG8_BAR; PG8_WAIT_L(0); PG8_MMA(0, 1, At, B1); PG8_BAR;
;             PG8_LDA(At, 1, 1); PG8_STAGE(PG8_SA(1, 0), a3, voffA);
;             PG8_WAIT_V(10); PG8_BAR; PG8_WAIT_L(0); PG8_MMA(1, 0, At, B0); PG8_BAR; PG8_SCHED;
;             PG8_STAGE(PG8_SB(1, 1), b3 + hstep, voffB);
;             PG8_WAIT_V(10); PG8_BAR; PG8_MMA(1, 1, At, B1); PG8_BAR;
;         }
	v_mfma_f32_16x16x32_bf16 v[64:67], v[204:207], v[172:175], v[64:67]
	s_setprio 0
	s_mov_b32 m0, s35
	v_lshl_add_u64 v[216:217], v[222:223], 0, s[8:9]
	ds_read_b128 v[144:147], v212 offset:49152
	ds_read_b128 v[148:151], v212 offset:50176
	ds_read_b128 v[152:155], v212 offset:51200
	ds_read_b128 v[156:159], v212 offset:52224
	ds_read_b128 v[160:163], v212 offset:53248
	ds_read_b128 v[164:167], v212 offset:54272
	ds_read_b128 v[168:171], v212 offset:55296
	ds_read_b128 v[172:175], v212 offset:56320
	global_load_lds_dwordx4 v[216:217], off
	v_lshl_add_u64 v[216:217], v[224:225], 0, s[8:9]
	s_mov_b32 m0, s36
	s_nop 0
	global_load_lds_dwordx4 v[216:217], off
	s_waitcnt vmcnt(10)
	s_barrier
	s_waitcnt lgkmcnt(0)
	s_setprio 1
	s_waitcnt lgkmcnt(0)
	v_mfma_f32_16x16x32_bf16 v[60:63], v[128:131], v[144:147], v[60:63]
	v_mfma_f32_16x16x32_bf16 v[56:59], v[136:139], v[144:147], v[56:59]
	v_mfma_f32_16x16x32_bf16 v[44:47], v[128:131], v[152:155], v[44:47]
	v_mfma_f32_16x16x32_bf16 v[40:43], v[136:139], v[152:155], v[40:43]
	v_mfma_f32_16x16x32_bf16 v[28:31], v[128:131], v[160:163], v[28:31]
	v_mfma_f32_16x16x32_bf16 v[24:27], v[136:139], v[160:163], v[24:27]
	v_mfma_f32_16x16x32_bf16 v[12:15], v[128:131], v[168:171], v[12:15]
	v_mfma_f32_16x16x32_bf16 v[8:11], v[136:139], v[168:171], v[8:11]
	v_mfma_f32_16x16x32_bf16 v[60:63], v[132:135], v[148:151], v[60:63]
	v_mfma_f32_16x16x32_bf16 v[56:59], v[140:143], v[148:151], v[56:59]
	v_mfma_f32_16x16x32_bf16 v[44:47], v[132:135], v[156:159], v[44:47]
	v_mfma_f32_16x16x32_bf16 v[40:43], v[140:143], v[156:159], v[40:43]
	v_mfma_f32_16x16x32_bf16 v[28:31], v[132:135], v[164:167], v[28:31]
	v_mfma_f32_16x16x32_bf16 v[24:27], v[140:143], v[164:167], v[24:27]
	v_mfma_f32_16x16x32_bf16 v[12:15], v[132:135], v[172:175], v[12:15]
	s_barrier
	v_mfma_f32_16x16x32_bf16 v[8:11], v[140:143], v[172:175], v[8:11]
	s_setprio 0
	s_add_u32 s24, s24, 0x80080
	s_addc_u32 s25, s25, 0
	s_add_i32 s26, s26, s29
	v_lshl_add_u64 v[128:129], s[24:25], 0, v[178:179]
	s_mov_b32 m0, s26
	s_nop 0
	global_load_lds_dwordx4 v[128:129], off
	v_lshl_add_u64 v[128:129], s[24:25], 0, v[182:183]
	s_add_i32 m0, s26, 0x2000
	s_nop 0
	global_load_lds_dwordx4 v[128:129], off
	s_waitcnt vmcnt(10)
	s_barrier
	s_setprio 1
	v_mfma_f32_16x16x32_bf16 v[52:55], v[192:195], v[144:147], v[52:55]
	v_mfma_f32_16x16x32_bf16 v[48:51], v[200:203], v[144:147], v[48:51]
	v_mfma_f32_16x16x32_bf16 v[36:39], v[192:195], v[152:155], v[36:39]
	v_mfma_f32_16x16x32_bf16 v[32:35], v[200:203], v[152:155], v[32:35]
	v_mfma_f32_16x16x32_bf16 v[20:23], v[192:195], v[160:163], v[20:23]
	v_mfma_f32_16x16x32_bf16 v[16:19], v[200:203], v[160:163], v[16:19]
	v_mfma_f32_16x16x32_bf16 v[4:7], v[192:195], v[168:171], v[4:7]
	v_mfma_f32_16x16x32_bf16 v[0:3], v[200:203], v[168:171], v[0:3]
	v_mfma_f32_16x16x32_bf16 v[52:55], v[196:199], v[148:151], v[52:55]
	v_mfma_f32_16x16x32_bf16 v[48:51], v[204:207], v[148:151], v[48:51]
	v_mfma_f32_16x16x32_bf16 v[36:39], v[196:199], v[156:159], v[36:39]
	v_mfma_f32_16x16x32_bf16 v[32:35], v[204:207], v[156:159], v[32:35]
	v_mfma_f32_16x16x32_bf16 v[20:23], v[196:199], v[164:167], v[20:23]
	v_mfma_f32_16x16x32_bf16 v[16:19], v[204:207], v[164:167], v[16:19]
	v_mfma_f32_16x16x32_bf16 v[4:7], v[196:199], v[172:175], v[4:7]
	s_barrier
	v_mfma_f32_16x16x32_bf16 v[0:3], v[204:207], v[172:175], v[0:3]
	s_setprio 0
	s_add_i32 s46, s46, 2
	s_add_u32 s22, s22, 0x100
	s_addc_u32 s23, s23, 0
	s_add_u32 s44, s44, 0x100
	s_addc_u32 s45, s45, 0
	s_cmp_gt_u32 s46, 29
	s_cbranch_scc0 .LBB0_733
;     __device__ __forceinline__ void ld(f32x4 (&xv)[2][2][2], int row0, int col0, int ai, int mh) const {
; #pragma unroll
;         for (int mm = 0; mm < 2; ++mm)
; #pragma unroll
;             for (int bj = 0; bj < 2; ++bj) { const size_t off = (size_t)(row0 + ai * 128 + (2 * mh + mm) * 16) * 2048 + col0 + bj * 128;
;                 xv[mm][bj][0] = *(const f32x4*)(base + off); xv[mm][bj][1] = *(const f32x4*)(base + off + 4); }
;     }
;     __device__ __forceinline__ void fin(const f32x4 (&acc)[2][2][4][2], const f32x4 (&xv)[2][2][2], int row0, int col0, int fq, int ai, int mh) const {
; #pragma unroll
;         for (int mm = 0; mm < 2; ++mm) { const int m = 2 * mh + mm; const int row = row0 + ai * 128 + m * 16; float sq = 0.f;
; #pragma unroll
;             for (int bj = 0; bj < 2; ++bj) { const size_t off = (size_t)row * 2048 + col0 + bj * 128;
;                 const f32x4 y0 = xv[mm][bj][0] + acc[ai][bj][m][0], y1 = xv[mm][bj][1] + acc[ai][bj][m][1];
;                 *(f32x4*)(out + off) = y0; *(f32x4*)(out + off + 4) = y1;
;                 if (ob) *(u32x4*)(ob + off) = pack8(y0, y1);
;                 sq += (y0[0] * y0[0] + y0[1] * y0[1]) + (y0[2] * y0[2] + y0[3] * y0[3]) + (y1[0] * y1[0] + y1[1] * y1[1]) + (y1[2] * y1[2] + y1[3] * y1[3]); }
;             sq += __shfl_xor(sq, 16); sq += __shfl_xor(sq, 32);
;             if (fq == 0) atomicAdd(ssq + row, (unsigned long long)(sq * 16777216.0f + 0.5f)); }
	v_lshl_add_u32 v194, s18, 8, v208
	v_lshl_or_b32 v192, s20, 8, v210
	v_ashrrev_i32_e32 v195, 31, v194
	v_ashrrev_i32_e32 v193, 31, v192
	v_lshlrev_b64 v[128:129], 11, v[194:195]
	v_lshl_add_u64 v[218:219], v[128:129], 0, v[192:193]
	v_lshlrev_b64 v[238:239], 2, v[218:219]
	v_lshl_add_u64 v[128:129], s[64:65], 0, v[238:239]
	global_load_dwordx4 v[222:225], v[128:129], off
	global_load_dwordx4 v[226:229], v[128:129], off offset:16
	global_load_dwordx4 v[230:233], v[128:129], off offset:512
	global_load_dwordx4 v[234:237], v[128:129], off offset:528
	v_or_b32_e32 v204, 16, v194
	v_or_b32_e32 v200, 32, v194
	v_or_b32_e32 v196, 48, v194
	v_ashrrev_i32_e32 v205, 31, v204
	v_ashrrev_i32_e32 v201, 31, v200
	v_ashrrev_i32_e32 v197, 31, v196
	v_lshlrev_b64 v[128:129], 11, v[204:205]
	v_lshlrev_b64 v[130:131], 11, v[200:201]
	v_lshlrev_b64 v[132:133], 11, v[196:197]
	v_lshl_add_u64 v[206:207], v[128:129], 0, v[192:193]
	v_lshl_add_u64 v[202:203], v[130:131], 0, v[192:193]
	v_lshl_add_u64 v[198:199], v[132:133], 0, v[192:193]
	v_lshl_add_u64 v[128:129], v[206:207], 2, s[64:65]
	v_lshl_add_u64 v[130:131], v[202:203], 2, s[64:65]
	v_lshl_add_u64 v[132:133], v[198:199], 2, s[64:65]
	global_load_dwordx4 v[168:171], v[128:129], off offset:16
	global_load_dwordx4 v[172:175], v[128:129], off
	global_load_dwordx4 v[160:163], v[128:129], off offset:528
	global_load_dwordx4 v[164:167], v[128:129], off offset:512
	global_load_dwordx4 v[152:155], v[130:131], off offset:16
	global_load_dwordx4 v[156:159], v[130:131], off
	global_load_dwordx4 v[144:147], v[130:131], off offset:528
	global_load_dwordx4 v[148:151], v[130:131], off offset:512
	global_load_dwordx4 v[136:139], v[132:133], off offset:16
	global_load_dwordx4 v[140:143], v[132:133], off
	s_nop 0
	global_load_dwordx4 v[128:131], v[132:133], off offset:528
	s_nop 0
	global_load_dwordx4 v[132:135], v[132:133], off offset:512
	v_and_b32_e32 v216, 64, v214
	v_xor_b32_e32 v215, 16, v214
	v_add_u32_e32 v216, 64, v216
	v_xor_b32_e32 v217, 32, v214
	v_cmp_lt_i32_e32 vcc, v215, v216
	v_lshl_add_u64 v[238:239], s[70:71], 0, v[238:239]
	v_lshlrev_b64 v[218:219], 1, v[218:219]
	v_cndmask_b32_e32 v215, v214, v215, vcc
	v_cmp_lt_i32_e32 vcc, v217, v216
	v_lshlrev_b32_e32 v216, 2, v215
	v_lshl_add_u64 v[240:241], s[58:59], 0, v[218:219]
	v_cndmask_b32_e32 v217, v214, v217, vcc
	v_lshlrev_b32_e32 v215, 2, v217
	v_or_b32_e32 v218, 0x100, v218
	s_waitcnt vmcnt(0)
	v_pk_add_f32 v[126:127], v[126:127], v[224:225]
	v_pk_add_f32 v[124:125], v[124:125], v[222:223]
	v_pk_add_f32 v[118:119], v[118:119], v[232:233]
	v_pk_add_f32 v[116:117], v[116:117], v[230:231]
	v_pk_add_f32 v[122:123], v[122:123], v[228:229]
	v_pk_add_f32 v[120:121], v[120:121], v[226:227]
	v_pk_add_f32 v[112:113], v[112:113], v[234:235]
	global_store_dwordx4 v[238:239], v[124:127], off
	global_store_dwordx4 v[238:239], v[120:123], off offset:16
	v_cvt_pk_bf16_f32 v222, v124, v125
	v_cvt_pk_bf16_f32 v223, v126, v127
	v_mul_f32_e32 v125, v125, v125
	v_mul_f32_e32 v127, v127, v127
	v_mul_f32_e32 v217, v117, v117
	v_mul_f32_e32 v221, v119, v119
	v_pk_add_f32 v[114:115], v[114:115], v[236:237]
	v_cvt_pk_bf16_f32 v224, v120, v121
	v_cvt_pk_bf16_f32 v225, v122, v123
	v_mul_f32_e32 v121, v121, v121
	v_mul_f32_e32 v123, v123, v123
	v_mul_f32_e32 v226, v113, v113
	v_fmac_f32_e32 v125, v124, v124
	v_fmac_f32_e32 v127, v126, v126
	v_fmac_f32_e32 v217, v116, v116
	v_fmac_f32_e32 v221, v118, v118
	v_mul_f32_e32 v227, v115, v115
	v_fmac_f32_e32 v121, v120, v120
	v_fmac_f32_e32 v123, v122, v122
	v_fmac_f32_e32 v226, v112, v112
	v_add_f32_e32 v120, v125, v127
	v_add_f32_e32 v122, v217, v221
	v_fmac_f32_e32 v227, v114, v114
	v_add_f32_e32 v120, v120, v121
	v_add_f32_e32 v121, v122, v226
	v_add_f32_e32 v120, v123, v120
	v_add_f32_e32 v121, v227, v121
	v_add_f32_e32 v120, v120, v121
	ds_bpermute_b32 v121, v216, v120
	global_store_dwordx4 v[240:241], v[222:225], off
	global_store_dwordx4 v[238:239], v[116:119], off offset:512
	global_store_dwordx4 v[238:239], v[112:115], off offset:528
	s_nop 0
	v_cvt_pk_bf16_f32 v116, v116, v117
	v_cvt_pk_bf16_f32 v117, v118, v119
	v_cvt_pk_bf16_f32 v118, v112, v113
	s_waitcnt lgkmcnt(0)
	v_add_f32_e32 v112, v120, v121
	ds_bpermute_b32 v113, v215, v112
	v_cvt_pk_bf16_f32 v119, v114, v115
	v_lshl_add_u64 v[114:115], s[58:59], 0, v[218:219]
	global_store_dwordx4 v[114:115], v[116:119], off
	s_and_saveexec_b64 s[18:19], s[2:3]
	s_cbranch_execz .LBB0_736
	s_waitcnt lgkmcnt(0)
	v_add_f32_e32 v112, v112, v113
	v_fma_f32 v112, v112, s42, 0.5
	v_trunc_f32_e32 v112, v112
	v_mul_f32_e32 v113, 0x2f800000, v112
	v_floor_f32_e32 v113, v113
	v_fmac_f32_e32 v112, 0xcf800000, v113
	v_cvt_u32_f32_e32 v112, v112
	v_cvt_u32_f32_e32 v113, v113
	v_lshl_add_u64 v[114:115], v[194:195], 3, s[0:1]
	global_atomic_add_x2 v[114:115], v[112:113], off

; #define PG8_STAGE(bufoff, gbase, voff) do { _Pragma("unroll") for (int _i = 0; _i < 2; ++_i) \
;         __builtin_amdgcn_global_load_lds((const unsigned*)((const char*)(gbase) + (voff)[_i]), (LAS unsigned*)(lds + (bufoff) + ldsw + _i * 8192), 16, 0, 0); } while (0)
; #define PG8_LDA(dst, b, h) do { _Pragma("unroll") for (int m = 0; m < 4; ++m) _Pragma("unroll") for (int k = 0; k < 2; ++k) dst[m][k] = *(const LAS bf16x8*)(lds + PG8_SA(b, h) + aoff + m * 2048 + k * 1024); } while (0)
; #define PG8_LDB(dst, b, h) do { _Pragma("unroll") for (int n = 0; n < 2; ++n) _Pragma("unroll") for (int k = 0; k < 2; ++k) dst[n][k] = *(const LAS bf16x8*)(lds + PG8_SB(b, h) + boff + n * 2048 + k * 1024); } while (0)
; #define PG8_MMA(ai, bj, At, Bt) do { __builtin_amdgcn_s_setprio(1); _Pragma("unroll") for (int m = 0; m < 4; ++m) _Pragma("unroll") for (int n = 0; n < 2; ++n) _Pragma("unroll") for (int k = 0; k < 2; ++k) \
;         acc[ai][bj][m][n] = __builtin_amdgcn_mfma_f32_16x16x32_bf16(Bt[n][k], At[m][k], acc[ai][bj][m][n], 0, 0, 0); __builtin_amdgcn_s_setprio(0); } while (0)
; #define PG8_WAIT_V(n) asm volatile("s_waitcnt vmcnt(" #n ")" ::: "memory")
; template <class Epi>
; __device__ __forceinline__ void gemm_phase(ldsp lds, const Gemm g, const StaticOrder& S, const Epi& E) {
;     ...
;         for (int t = 0; t < nt; t += 2) {
;             const bool last = (t == nt - 2);
;             const char* a1 = cA + (size_t)(t + 1) * kstep;
;             const char* a2 = last ? nA : cA + (size_t)(t + 2) * kstep; const char* b2 = last ? nB : cB + (size_t)(t + 2) * kstep;
;             const char* a3 = a2 + kstep; const char* b3 = b2 + kstep;
;             if constexpr (Epi::NPRE > 0) { if (last) E.pre(pre, cur, wr, fr); }
;             if constexpr (Epi::MID_T > 0) { if (t == Epi::MID_T) E.mid(acc, cur, wr, wc, fr, fq); }
;             PG8_LDB(B0, 0, 0); PG8_SCHED; PG8_LDA(At, 0, 0); PG8_STAGE(PG8_SA(1, 1), a1 + hstep, voffA);
;             PG8_WAIT_L(8); PG8_WAIT_V(10); PG8_BAR; PG8_WAIT_L(0); PG8_MMA(0, 0, At, B0); PG8_BAR; PG8_SCHED;
;             PG8_LDB(B1, 0, 1); PG8_STAGE(PG8_SB(0, 0), b2, voffB);
;             PG8_WAIT_V(10); PG8_BAR; PG8_WAIT_L(0); PG8_MMA(0, 1, At, B1); PG8_BAR;
;             PG8_LDA(At, 0, 1); PG8_STAGE(PG8_SA(0, 0), a2, voffA);
;             PG8_WAIT_V(10); PG8_BAR; PG8_WAIT_L(0); PG8_MMA(1, 0, At, B0); PG8_BAR; PG8_SCHED;
.LBB0_816:
	v_add_u32_e32 v161, s39, v175
	ds_read_b128 v[164:167], v161
	ds_read_b128 v[168:171], v161 offset:1024
	ds_read_b128 v[178:181], v161 offset:2048
	ds_read_b128 v[182:185], v161 offset:3072
	s_add_u32 s26, s22, 0xfff80080
	s_addc_u32 s27, s23, -1
	s_and_b64 s[24:25], s[24:25], exec
	s_cselect_b32 s27, s17, s27
	s_cselect_b32 s26, s44, s26
	s_cselect_b32 s25, s15, s47
	s_cselect_b32 s24, s45, s46
	v_lshl_add_u64 v[172:173], s[22:23], 0, v[136:137]
	s_add_i32 m0, s29, 0xc000
	ds_read_b128 v[186:189], v177
	ds_read_b128 v[190:193], v177 offset:1024
	ds_read_b128 v[194:197], v177 offset:2048
	ds_read_b128 v[198:201], v177 offset:3072
	ds_read_b128 v[202:205], v177 offset:4096
	ds_read_b128 v[206:209], v177 offset:5120
	ds_read_b128 v[210:213], v177 offset:6144
	ds_read_b128 v[214:217], v177 offset:7168
	global_load_lds_dwordx4 v[172:173], off
	v_lshl_add_u64 v[172:173], s[22:23], 0, v[138:139]
	s_add_i32 m0, s29, 0xe000
	s_nop 0
	global_load_lds_dwordx4 v[172:173], off
	s_waitcnt lgkmcnt(8)
	s_waitcnt vmcnt(10)
	s_barrier
	s_waitcnt lgkmcnt(0)
	s_setprio 1
	s_waitcnt lgkmcnt(0)
	v_mfma_f32_16x16x32_bf16 v[124:127], v[164:167], v[186:189], v[124:127]
	v_mfma_f32_16x16x32_bf16 v[120:123], v[178:181], v[186:189], v[120:123]
	v_mfma_f32_16x16x32_bf16 v[112:115], v[164:167], v[194:197], v[112:115]
	v_mfma_f32_16x16x32_bf16 v[104:107], v[178:181], v[194:197], v[104:107]
	v_mfma_f32_16x16x32_bf16 v[92:95], v[164:167], v[202:205], v[92:95]
	v_mfma_f32_16x16x32_bf16 v[88:91], v[178:181], v[202:205], v[88:91]
	v_mfma_f32_16x16x32_bf16 v[80:83], v[164:167], v[210:213], v[80:83]
	v_mfma_f32_16x16x32_bf16 v[72:75], v[178:181], v[210:213], v[72:75]
	v_mfma_f32_16x16x32_bf16 v[124:127], v[168:171], v[190:193], v[124:127]
	v_mfma_f32_16x16x32_bf16 v[120:123], v[182:185], v[190:193], v[120:123]
	v_mfma_f32_16x16x32_bf16 v[112:115], v[168:171], v[198:201], v[112:115]
	v_mfma_f32_16x16x32_bf16 v[104:107], v[182:185], v[198:201], v[104:107]
	v_mfma_f32_16x16x32_bf16 v[92:95], v[168:171], v[206:209], v[92:95]
	v_mfma_f32_16x16x32_bf16 v[88:91], v[182:185], v[206:209], v[88:91]
	v_mfma_f32_16x16x32_bf16 v[80:83], v[168:171], v[214:217], v[80:83]
	s_barrier
	v_mfma_f32_16x16x32_bf16 v[72:75], v[182:185], v[214:217], v[72:75]
	s_setprio 0
	s_add_i32 s51, s39, s11
	v_add_u32_e32 v161, s40, v175
	v_lshl_add_u64 v[172:173], s[24:25], 0, v[132:133]
	s_mov_b32 m0, s51
	ds_read_b128 v[222:225], v161
	ds_read_b128 v[226:229], v161 offset:1024
	ds_read_b128 v[230:233], v161 offset:2048
	ds_read_b128 v[234:237], v161 offset:3072
	global_load_lds_dwordx4 v[172:173], off
	v_lshl_add_u64 v[218:219], s[24:25], 0, v[128:129]
	s_add_i32 m0, s51, 0x2000
	s_nop 0
	global_load_lds_dwordx4 v[218:219], off
	s_waitcnt vmcnt(10)
	s_barrier
	s_waitcnt lgkmcnt(0)
	s_setprio 1
	s_waitcnt lgkmcnt(0)
	v_mfma_f32_16x16x32_bf16 v[116:119], v[222:225], v[186:189], v[116:119]
	v_mfma_f32_16x16x32_bf16 v[108:111], v[230:233], v[186:189], v[108:111]
	v_mfma_f32_16x16x32_bf16 v[100:103], v[222:225], v[194:197], v[100:103]
	v_mfma_f32_16x16x32_bf16 v[96:99], v[230:233], v[194:197], v[96:99]
	v_mfma_f32_16x16x32_bf16 v[84:87], v[222:225], v[202:205], v[84:87]
	v_mfma_f32_16x16x32_bf16 v[76:79], v[230:233], v[202:205], v[76:79]
	v_mfma_f32_16x16x32_bf16 v[68:71], v[222:225], v[210:213], v[68:71]
	v_mfma_f32_16x16x32_bf16 v[64:67], v[230:233], v[210:213], v[64:67]
	v_mfma_f32_16x16x32_bf16 v[116:119], v[226:229], v[190:193], v[116:119]
	v_mfma_f32_16x16x32_bf16 v[108:111], v[234:237], v[190:193], v[108:111]
	v_mfma_f32_16x16x32_bf16 v[100:103], v[226:229], v[198:201], v[100:103]
	v_mfma_f32_16x16x32_bf16 v[96:99], v[234:237], v[198:201], v[96:99]
	v_mfma_f32_16x16x32_bf16 v[84:87], v[226:229], v[206:209], v[84:87]
	v_mfma_f32_16x16x32_bf16 v[76:79], v[234:237], v[206:209], v[76:79]
	v_mfma_f32_16x16x32_bf16 v[68:71], v[226:229], v[214:217], v[68:71]
	s_barrier
	v_mfma_f32_16x16x32_bf16 v[64:67], v[234:237], v[214:217], v[64:67]
	s_setprio 0
	s_mov_b32 m0, s29
	v_lshl_add_u64 v[238:239], s[26:27], 0, v[134:135]
	ds_read_b128 v[186:189], v177 offset:16384
	ds_read_b128 v[190:193], v177 offset:17408
	ds_read_b128 v[194:197], v177 offset:18432
	ds_read_b128 v[198:201], v177 offset:19456
	ds_read_b128 v[202:205], v177 offset:20480
	ds_read_b128 v[206:209], v177 offset:21504
	ds_read_b128 v[210:213], v177 offset:22528
	ds_read_b128 v[214:217], v177 offset:23552
	global_load_lds_dwordx4 v[238:239], off
	v_lshl_add_u64 v[240:241], s[26:27], 0, v[130:131]
	s_mov_b32 m0, s30
	s_nop 0
	global_load_lds_dwordx4 v[240:241], off
	s_waitcnt vmcnt(10)
	s_barrier
	s_waitcnt lgkmcnt(0)
	s_setprio 1
	s_waitcnt lgkmcnt(0)
	v_mfma_f32_16x16x32_bf16 v[60:63], v[164:167], v[186:189], v[60:63]
	v_mfma_f32_16x16x32_bf16 v[56:59], v[178:181], v[186:189], v[56:59]
	v_mfma_f32_16x16x32_bf16 v[48:51], v[164:167], v[194:197], v[48:51]
	v_mfma_f32_16x16x32_bf16 v[40:43], v[178:181], v[194:197], v[40:43]
	v_mfma_f32_16x16x32_bf16 v[28:31], v[164:167], v[202:205], v[28:31]
	v_mfma_f32_16x16x32_bf16 v[24:27], v[178:181], v[202:205], v[24:27]
	v_mfma_f32_16x16x32_bf16 v[16:19], v[164:167], v[210:213], v[16:19]
	v_mfma_f32_16x16x32_bf16 v[8:11], v[178:181], v[210:213], v[8:11]
	v_mfma_f32_16x16x32_bf16 v[60:63], v[168:171], v[190:193], v[60:63]
	v_mfma_f32_16x16x32_bf16 v[56:59], v[182:185], v[190:193], v[56:59]
	v_mfma_f32_16x16x32_bf16 v[48:51], v[168:171], v[198:201], v[48:51]
	v_mfma_f32_16x16x32_bf16 v[40:43], v[182:185], v[198:201], v[40:43]
	v_mfma_f32_16x16x32_bf16 v[28:31], v[168:171], v[206:209], v[28:31]
	v_mfma_f32_16x16x32_bf16 v[24:27], v[182:185], v[206:209], v[24:27]
	v_mfma_f32_16x16x32_bf16 v[16:19], v[168:171], v[214:217], v[16:19]
	s_barrier
; #define PG8_STAGE(bufoff, gbase, voff) do { _Pragma("unroll") for (int _i = 0; _i < 2; ++_i) \
;         __builtin_amdgcn_global_load_lds((const unsigned*)((const char*)(gbase) + (voff)[_i]), (LAS unsigned*)(lds + (bufoff) + ldsw + _i * 8192), 16, 0, 0); } while (0)
; #define PG8_LDA(dst, b, h) do { _Pragma("unroll") for (int m = 0; m < 4; ++m) _Pragma("unroll") for (int k = 0; k < 2; ++k) dst[m][k] = *(const LAS bf16x8*)(lds + PG8_SA(b, h) + aoff + m * 2048 + k * 1024); } while (0)
; #define PG8_LDB(dst, b, h) do { _Pragma("unroll") for (int n = 0; n < 2; ++n) _Pragma("unroll") for (int k = 0; k < 2; ++k) dst[n][k] = *(const LAS bf16x8*)(lds + PG8_SB(b, h) + boff + n * 2048 + k * 1024); } while (0)
; #define PG8_MMA(ai, bj, At, Bt) do { __builtin_amdgcn_s_setprio(1); _Pragma("unroll") for (int m = 0; m < 4; ++m) _Pragma("unroll") for (int n = 0; n < 2; ++n) _Pragma("unroll") for (int k = 0; k < 2; ++k) \
;         acc[ai][bj][m][n] = __builtin_amdgcn_mfma_f32_16x16x32_bf16(Bt[n][k], At[m][k], acc[ai][bj][m][n], 0, 0, 0); __builtin_amdgcn_s_setprio(0); } while (0)
; #define PG8_WAIT_V(n) asm volatile("s_waitcnt vmcnt(" #n ")" ::: "memory")
; #define PG8_WAIT_L(n) asm volatile("s_waitcnt lgkmcnt(" #n ")" ::: "memory")
; #define PG8_BAR __builtin_amdgcn_s_barrier()
; #define PG8_SCHED __builtin_amdgcn_sched_barrier(0)
; template <class Epi>
; __device__ __forceinline__ void gemm_phase(ldsp lds, const Gemm g, const StaticOrder& S, const Epi& E) {
;     ...
;             PG8_WAIT_V(10); PG8_BAR; PG8_WAIT_L(0); PG8_MMA(1, 0, At, B0); PG8_BAR; PG8_SCHED;
;             PG8_STAGE(PG8_SB(0, 1), b2 + hstep, voffB);
;             PG8_WAIT_V(10); PG8_BAR; PG8_MMA(1, 1, At, B1); PG8_BAR;
;             PG8_LDB(B0, 1, 0); PG8_SCHED; PG8_LDA(At, 1, 0); PG8_STAGE(PG8_SA(0, 1), a2 + hstep, voffA);
;             PG8_WAIT_L(8); PG8_WAIT_V(10); PG8_BAR; PG8_WAIT_L(0); PG8_MMA(0, 0, At, B0); PG8_BAR; PG8_SCHED;
;             PG8_LDB(B1, 1, 1); PG8_STAGE(PG8_SB(1, 0), b3, voffB);
	v_mfma_f32_16x16x32_bf16 v[8:11], v[182:185], v[214:217], v[8:11]
	s_setprio 0
	s_add_u32 s52, s24, 0x80000
	s_addc_u32 s53, s25, 0
	s_add_i32 s51, s40, s11
	v_lshl_add_u64 v[164:165], s[52:53], 0, v[132:133]
	s_mov_b32 m0, s51
	s_nop 0
	global_load_lds_dwordx4 v[164:165], off
	v_lshl_add_u64 v[164:165], s[52:53], 0, v[128:129]
	s_add_i32 m0, s51, 0x2000
	s_nop 0
	global_load_lds_dwordx4 v[164:165], off
	s_waitcnt vmcnt(10)
	s_barrier
	s_setprio 1
	v_mfma_f32_16x16x32_bf16 v[52:55], v[222:225], v[186:189], v[52:55]
	v_mfma_f32_16x16x32_bf16 v[44:47], v[230:233], v[186:189], v[44:47]
	v_mfma_f32_16x16x32_bf16 v[36:39], v[222:225], v[194:197], v[36:39]
	v_mfma_f32_16x16x32_bf16 v[32:35], v[230:233], v[194:197], v[32:35]
	v_mfma_f32_16x16x32_bf16 v[20:23], v[222:225], v[202:205], v[20:23]
	v_mfma_f32_16x16x32_bf16 v[12:15], v[230:233], v[202:205], v[12:15]
	v_mfma_f32_16x16x32_bf16 v[4:7], v[222:225], v[210:213], v[4:7]
	v_mfma_f32_16x16x32_bf16 v[0:3], v[230:233], v[210:213], v[0:3]
	v_mfma_f32_16x16x32_bf16 v[52:55], v[226:229], v[190:193], v[52:55]
	v_mfma_f32_16x16x32_bf16 v[44:47], v[234:237], v[190:193], v[44:47]
	v_mfma_f32_16x16x32_bf16 v[36:39], v[226:229], v[198:201], v[36:39]
	v_mfma_f32_16x16x32_bf16 v[32:35], v[234:237], v[198:201], v[32:35]
	v_mfma_f32_16x16x32_bf16 v[20:23], v[226:229], v[206:209], v[20:23]
	v_mfma_f32_16x16x32_bf16 v[12:15], v[234:237], v[206:209], v[12:15]
	v_mfma_f32_16x16x32_bf16 v[4:7], v[226:229], v[214:217], v[4:7]
	s_barrier
	v_mfma_f32_16x16x32_bf16 v[0:3], v[234:237], v[214:217], v[0:3]
	s_setprio 0
	s_add_i32 s51, 0, 0x18000
	v_add_u32_e32 v161, s51, v175
	ds_read_b128 v[164:167], v161
	ds_read_b128 v[168:171], v161 offset:1024
	ds_read_b128 v[178:181], v161 offset:2048
	ds_read_b128 v[182:185], v161 offset:3072
	s_add_u32 s26, s26, 0x80000
	s_addc_u32 s27, s27, 0
	s_mov_b32 m0, s31
	v_lshl_add_u64 v[222:223], s[26:27], 0, v[134:135]
	ds_read_b128 v[186:189], v177 offset:32768
	ds_read_b128 v[190:193], v177 offset:33792
	ds_read_b128 v[194:197], v177 offset:34816
	ds_read_b128 v[198:201], v177 offset:35840
	ds_read_b128 v[202:205], v177 offset:36864
	ds_read_b128 v[206:209], v177 offset:37888
	ds_read_b128 v[210:213], v177 offset:38912
	ds_read_b128 v[214:217], v177 offset:39936
	global_load_lds_dwordx4 v[222:223], off
	v_lshl_add_u64 v[222:223], s[26:27], 0, v[130:131]
	s_mov_b32 m0, s33
	s_nop 0
	global_load_lds_dwordx4 v[222:223], off
	s_waitcnt lgkmcnt(8)
	s_waitcnt vmcnt(10)
	s_barrier
	s_waitcnt lgkmcnt(0)
	s_setprio 1
	s_waitcnt lgkmcnt(0)
	v_mfma_f32_16x16x32_bf16 v[124:127], v[164:167], v[186:189], v[124:127]
	v_mfma_f32_16x16x32_bf16 v[120:123], v[178:181], v[186:189], v[120:123]
	v_mfma_f32_16x16x32_bf16 v[112:115], v[164:167], v[194:197], v[112:115]
	v_mfma_f32_16x16x32_bf16 v[104:107], v[178:181], v[194:197], v[104:107]
	v_mfma_f32_16x16x32_bf16 v[92:95], v[164:167], v[202:205], v[92:95]
	v_mfma_f32_16x16x32_bf16 v[88:91], v[178:181], v[202:205], v[88:91]
	v_mfma_f32_16x16x32_bf16 v[80:83], v[164:167], v[210:213], v[80:83]
	v_mfma_f32_16x16x32_bf16 v[72:75], v[178:181], v[210:213], v[72:75]
	v_mfma_f32_16x16x32_bf16 v[124:127], v[168:171], v[190:193], v[124:127]
	v_mfma_f32_16x16x32_bf16 v[120:123], v[182:185], v[190:193], v[120:123]
	v_mfma_f32_16x16x32_bf16 v[112:115], v[168:171], v[198:201], v[112:115]
	v_mfma_f32_16x16x32_bf16 v[104:107], v[182:185], v[198:201], v[104:107]
	v_mfma_f32_16x16x32_bf16 v[92:95], v[168:171], v[206:209], v[92:95]
	v_mfma_f32_16x16x32_bf16 v[88:91], v[182:185], v[206:209], v[88:91]
	v_mfma_f32_16x16x32_bf16 v[80:83], v[168:171], v[214:217], v[80:83]
	s_barrier
	v_mfma_f32_16x16x32_bf16 v[72:75], v[182:185], v[214:217], v[72:75]
	s_setprio 0
	s_add_i32 s26, 0, 0x1c000
	s_add_i32 s27, s51, s11
	v_add_u32_e32 v161, s26, v175
	v_lshl_add_u64 v[172:173], v[172:173], 0, s[6:7]
	s_mov_b32 m0, s27
	ds_read_b128 v[222:225], v161
	ds_read_b128 v[226:229], v161 offset:1024
	ds_read_b128 v[230:233], v161 offset:2048
	ds_read_b128 v[234:237], v161 offset:3072
	global_load_lds_dwordx4 v[172:173], off
	v_lshl_add_u64 v[172:173], v[218:219], 0, s[6:7]
	s_add_i32 m0, s27, 0x2000
	s_nop 0
	global_load_lds_dwordx4 v[172:173], off
	s_waitcnt vmcnt(10)
	s_barrier
; #define PG8_STAGE(bufoff, gbase, voff) do { _Pragma("unroll") for (int _i = 0; _i < 2; ++_i) \
;         __builtin_amdgcn_global_load_lds((const unsigned*)((const char*)(gbase) + (voff)[_i]), (LAS unsigned*)(lds + (bufoff) + ldsw + _i * 8192), 16, 0, 0); } while (0)
; #define PG8_LDA(dst, b, h) do { _Pragma("unroll") for (int m = 0; m < 4; ++m) _Pragma("unroll") for (int k = 0; k < 2; ++k) dst[m][k] = *(const LAS bf16x8*)(lds + PG8_SA(b, h) + aoff + m * 2048 + k * 1024); } while (0)
; #define PG8_MMA(ai, bj, At, Bt) do { __builtin_amdgcn_s_setprio(1); _Pragma("unroll") for (int m = 0; m < 4; ++m) _Pragma("unroll") for (int n = 0; n < 2; ++n) _Pragma("unroll") for (int k = 0; k < 2; ++k) \
;         acc[ai][bj][m][n] = __builtin_amdgcn_mfma_f32_16x16x32_bf16(Bt[n][k], At[m][k], acc[ai][bj][m][n], 0, 0, 0); __builtin_amdgcn_s_setprio(0); } while (0)
; #define PG8_WAIT_V(n) asm volatile("s_waitcnt vmcnt(" #n ")" ::: "memory")
; #define PG8_WAIT_L(n) asm volatile("s_waitcnt lgkmcnt(" #n ")" ::: "memory")
; #define PG8_BAR __builtin_amdgcn_s_barrier()
; #define PG8_SCHED __builtin_amdgcn_sched_barrier(0)
; template <class Epi>
; __device__ __forceinline__ void gemm_phase(ldsp lds, const Gemm g, const StaticOrder& S, const Epi& E) {
;     ...
;             PG8_WAIT_V(10); PG8_BAR; PG8_WAIT_L(0); PG8_MMA(0, 1, At, B1); PG8_BAR;
;             PG8_LDA(At, 1, 1); PG8_STAGE(PG8_SA(1, 0), a3, voffA);
;             PG8_WAIT_V(10); PG8_BAR; PG8_WAIT_L(0); PG8_MMA(1, 0, At, B0); PG8_BAR; PG8_SCHED;
;             PG8_STAGE(PG8_SB(1, 1), b3 + hstep, voffB);
;             PG8_WAIT_V(10); PG8_BAR; PG8_MMA(1, 1, At, B1); PG8_BAR;
;         }
	s_waitcnt lgkmcnt(0)
	s_setprio 1
	s_waitcnt lgkmcnt(0)
	v_mfma_f32_16x16x32_bf16 v[116:119], v[222:225], v[186:189], v[116:119]
	v_mfma_f32_16x16x32_bf16 v[108:111], v[230:233], v[186:189], v[108:111]
	v_mfma_f32_16x16x32_bf16 v[100:103], v[222:225], v[194:197], v[100:103]
	v_mfma_f32_16x16x32_bf16 v[96:99], v[230:233], v[194:197], v[96:99]
	v_mfma_f32_16x16x32_bf16 v[84:87], v[222:225], v[202:205], v[84:87]
	v_mfma_f32_16x16x32_bf16 v[76:79], v[230:233], v[202:205], v[76:79]
	v_mfma_f32_16x16x32_bf16 v[68:71], v[222:225], v[210:213], v[68:71]
	v_mfma_f32_16x16x32_bf16 v[64:67], v[230:233], v[210:213], v[64:67]
	v_mfma_f32_16x16x32_bf16 v[116:119], v[226:229], v[190:193], v[116:119]
	v_mfma_f32_16x16x32_bf16 v[108:111], v[234:237], v[190:193], v[108:111]
	v_mfma_f32_16x16x32_bf16 v[100:103], v[226:229], v[198:201], v[100:103]
	v_mfma_f32_16x16x32_bf16 v[96:99], v[234:237], v[198:201], v[96:99]
	v_mfma_f32_16x16x32_bf16 v[84:87], v[226:229], v[206:209], v[84:87]
	v_mfma_f32_16x16x32_bf16 v[76:79], v[234:237], v[206:209], v[76:79]
	v_mfma_f32_16x16x32_bf16 v[68:71], v[226:229], v[214:217], v[68:71]
	s_barrier
	v_mfma_f32_16x16x32_bf16 v[64:67], v[234:237], v[214:217], v[64:67]
	s_setprio 0
	s_mov_b32 m0, s35
	v_lshl_add_u64 v[172:173], v[238:239], 0, s[6:7]
	ds_read_b128 v[186:189], v177 offset:49152
	ds_read_b128 v[190:193], v177 offset:50176
	ds_read_b128 v[194:197], v177 offset:51200
	ds_read_b128 v[198:201], v177 offset:52224
	ds_read_b128 v[202:205], v177 offset:53248
	ds_read_b128 v[206:209], v177 offset:54272
	ds_read_b128 v[210:213], v177 offset:55296
	ds_read_b128 v[214:217], v177 offset:56320
	global_load_lds_dwordx4 v[172:173], off
	v_lshl_add_u64 v[172:173], v[240:241], 0, s[6:7]
	s_mov_b32 m0, s36
	s_nop 0
	global_load_lds_dwordx4 v[172:173], off
	s_waitcnt vmcnt(10)
	s_barrier
	s_waitcnt lgkmcnt(0)
	s_setprio 1
	s_waitcnt lgkmcnt(0)
	v_mfma_f32_16x16x32_bf16 v[60:63], v[164:167], v[186:189], v[60:63]
	v_mfma_f32_16x16x32_bf16 v[56:59], v[178:181], v[186:189], v[56:59]
	v_mfma_f32_16x16x32_bf16 v[48:51], v[164:167], v[194:197], v[48:51]
	v_mfma_f32_16x16x32_bf16 v[40:43], v[178:181], v[194:197], v[40:43]
	v_mfma_f32_16x16x32_bf16 v[28:31], v[164:167], v[202:205], v[28:31]
	v_mfma_f32_16x16x32_bf16 v[24:27], v[178:181], v[202:205], v[24:27]
	v_mfma_f32_16x16x32_bf16 v[16:19], v[164:167], v[210:213], v[16:19]
	v_mfma_f32_16x16x32_bf16 v[8:11], v[178:181], v[210:213], v[8:11]
	v_mfma_f32_16x16x32_bf16 v[60:63], v[168:171], v[190:193], v[60:63]
	v_mfma_f32_16x16x32_bf16 v[56:59], v[182:185], v[190:193], v[56:59]
	v_mfma_f32_16x16x32_bf16 v[48:51], v[168:171], v[198:201], v[48:51]
	v_mfma_f32_16x16x32_bf16 v[40:43], v[182:185], v[198:201], v[40:43]
	v_mfma_f32_16x16x32_bf16 v[28:31], v[168:171], v[206:209], v[28:31]
	v_mfma_f32_16x16x32_bf16 v[24:27], v[182:185], v[206:209], v[24:27]
	v_mfma_f32_16x16x32_bf16 v[16:19], v[168:171], v[214:217], v[16:19]
	s_barrier
	v_mfma_f32_16x16x32_bf16 v[8:11], v[182:185], v[214:217], v[8:11]
	s_setprio 0
	s_add_u32 s24, s24, 0x80080
	s_addc_u32 s25, s25, 0
	s_add_i32 s26, s26, s11
	v_lshl_add_u64 v[164:165], s[24:25], 0, v[132:133]
	s_mov_b32 m0, s26
	s_nop 0
	global_load_lds_dwordx4 v[164:165], off
	v_lshl_add_u64 v[164:165], s[24:25], 0, v[128:129]
	s_add_i32 m0, s26, 0x2000
	s_nop 0
	global_load_lds_dwordx4 v[164:165], off
	s_waitcnt vmcnt(10)
	s_barrier
	s_setprio 1
	v_mfma_f32_16x16x32_bf16 v[52:55], v[222:225], v[186:189], v[52:55]
	v_mfma_f32_16x16x32_bf16 v[44:47], v[230:233], v[186:189], v[44:47]
	v_mfma_f32_16x16x32_bf16 v[36:39], v[222:225], v[194:197], v[36:39]
	v_mfma_f32_16x16x32_bf16 v[32:35], v[230:233], v[194:197], v[32:35]
	v_mfma_f32_16x16x32_bf16 v[20:23], v[222:225], v[202:205], v[20:23]
	v_mfma_f32_16x16x32_bf16 v[12:15], v[230:233], v[202:205], v[12:15]
	v_mfma_f32_16x16x32_bf16 v[4:7], v[222:225], v[210:213], v[4:7]
	v_mfma_f32_16x16x32_bf16 v[0:3], v[230:233], v[210:213], v[0:3]
	v_mfma_f32_16x16x32_bf16 v[52:55], v[226:229], v[190:193], v[52:55]
	v_mfma_f32_16x16x32_bf16 v[44:47], v[234:237], v[190:193], v[44:47]
	v_mfma_f32_16x16x32_bf16 v[36:39], v[226:229], v[198:201], v[36:39]
	v_mfma_f32_16x16x32_bf16 v[32:35], v[234:237], v[198:201], v[32:35]
	v_mfma_f32_16x16x32_bf16 v[20:23], v[226:229], v[206:209], v[20:23]
	v_mfma_f32_16x16x32_bf16 v[12:15], v[234:237], v[206:209], v[12:15]
	v_mfma_f32_16x16x32_bf16 v[4:7], v[226:229], v[214:217], v[4:7]
	s_barrier
	v_mfma_f32_16x16x32_bf16 v[0:3], v[234:237], v[214:217], v[0:3]
	s_setprio 0
	s_add_i32 s50, s50, 2
	s_add_u32 s22, s22, 0x100
	s_addc_u32 s23, s23, 0
	s_add_u32 s46, s46, 0x100
	s_addc_u32 s47, s47, 0
	s_cmp_gt_u32 s50, 29
	s_cbranch_scc1 .LBB0_812

; #define PG8_STAGE(bufoff, gbase, voff) do { _Pragma("unroll") for (int _i = 0; _i < 2; ++_i) \
;         __builtin_amdgcn_global_load_lds((const unsigned*)((const char*)(gbase) + (voff)[_i]), (LAS unsigned*)(lds + (bufoff) + ldsw + _i * 8192), 16, 0, 0); } while (0)
; #define PG8_LDA(dst, b, h) do { _Pragma("unroll") for (int m = 0; m < 4; ++m) _Pragma("unroll") for (int k = 0; k < 2; ++k) dst[m][k] = *(const LAS bf16x8*)(lds + PG8_SA(b, h) + aoff + m * 2048 + k * 1024); } while (0)
; #define PG8_LDB(dst, b, h) do { _Pragma("unroll") for (int n = 0; n < 2; ++n) _Pragma("unroll") for (int k = 0; k < 2; ++k) dst[n][k] = *(const LAS bf16x8*)(lds + PG8_SB(b, h) + boff + n * 2048 + k * 1024); } while (0)
; #define PG8_MMA(ai, bj, At, Bt) do { __builtin_amdgcn_s_setprio(1); _Pragma("unroll") for (int m = 0; m < 4; ++m) _Pragma("unroll") for (int n = 0; n < 2; ++n) _Pragma("unroll") for (int k = 0; k < 2; ++k) \
;         acc[ai][bj][m][n] = __builtin_amdgcn_mfma_f32_16x16x32_bf16(Bt[n][k], At[m][k], acc[ai][bj][m][n], 0, 0, 0); __builtin_amdgcn_s_setprio(0); } while (0)
; #define PG8_WAIT_V(n) asm volatile("s_waitcnt vmcnt(" #n ")" ::: "memory")
; template <class Epi>
; __device__ __forceinline__ void gemm_phase(ldsp lds, const Gemm g, const StaticOrder& S, const Epi& E) {
;     ...
;         for (int t = 0; t < nt; t += 2) {
;             const bool last = (t == nt - 2);
;             const char* a1 = cA + (size_t)(t + 1) * kstep;
;             const char* a2 = last ? nA : cA + (size_t)(t + 2) * kstep; const char* b2 = last ? nB : cB + (size_t)(t + 2) * kstep;
;             const char* a3 = a2 + kstep; const char* b3 = b2 + kstep;
;             if constexpr (Epi::NPRE > 0) { if (last) E.pre(pre, cur, wr, fr); }
;             if constexpr (Epi::MID_T > 0) { if (t == Epi::MID_T) E.mid(acc, cur, wr, wc, fr, fq); }
;             PG8_LDB(B0, 0, 0); PG8_SCHED; PG8_LDA(At, 0, 0); PG8_STAGE(PG8_SA(1, 1), a1 + hstep, voffA);
;             PG8_WAIT_L(8); PG8_WAIT_V(10); PG8_BAR; PG8_WAIT_L(0); PG8_MMA(0, 0, At, B0); PG8_BAR; PG8_SCHED;
;             PG8_LDB(B1, 0, 1); PG8_STAGE(PG8_SB(0, 0), b2, voffB);
;             PG8_WAIT_V(10); PG8_BAR; PG8_WAIT_L(0); PG8_MMA(0, 1, At, B1); PG8_BAR;
;             PG8_LDA(At, 0, 1); PG8_STAGE(PG8_SA(0, 0), a2, voffA);
;             PG8_WAIT_V(10); PG8_BAR; PG8_WAIT_L(0); PG8_MMA(1, 0, At, B0); PG8_BAR; PG8_SCHED;
.LBB0_899:
	ds_read_b128 v[128:131], v211
	ds_read_b128 v[132:135], v211 offset:1024
	ds_read_b128 v[136:139], v211 offset:2048
	ds_read_b128 v[140:143], v211 offset:3072
	s_add_u32 s16, s14, 0xffea0080
	s_addc_u32 s17, s15, -1
	s_cmpk_eq_i32 s42, 0x54
	s_cselect_b32 s19, s1, s17
	s_cselect_b32 s18, s0, s16
	s_cselect_b32 s17, s7, s41
	s_cselect_b32 s16, s6, s40
	v_lshl_add_u64 v[192:193], s[14:15], 0, v[184:185]
	s_add_i32 m0, s22, 0xc000
	ds_read_b128 v[144:147], v212
	ds_read_b128 v[148:151], v212 offset:1024
	ds_read_b128 v[152:155], v212 offset:2048
	ds_read_b128 v[156:159], v212 offset:3072
	ds_read_b128 v[160:163], v212 offset:4096
	ds_read_b128 v[164:167], v212 offset:5120
	ds_read_b128 v[168:171], v212 offset:6144
	ds_read_b128 v[172:175], v212 offset:7168
	global_load_lds_dwordx4 v[192:193], off
	v_lshl_add_u64 v[192:193], s[14:15], 0, v[186:187]
	s_add_i32 m0, s22, 0xe000
	s_nop 0
	global_load_lds_dwordx4 v[192:193], off
	s_waitcnt lgkmcnt(8)
	s_waitcnt vmcnt(10)
	s_barrier
	s_waitcnt lgkmcnt(0)
	s_setprio 1
	s_waitcnt lgkmcnt(0)
	v_mfma_f32_16x16x32_bf16 v[124:127], v[128:131], v[144:147], v[124:127]
	v_mfma_f32_16x16x32_bf16 v[120:123], v[136:139], v[144:147], v[120:123]
	v_mfma_f32_16x16x32_bf16 v[108:111], v[128:131], v[152:155], v[108:111]
	v_mfma_f32_16x16x32_bf16 v[104:107], v[136:139], v[152:155], v[104:107]
	v_mfma_f32_16x16x32_bf16 v[92:95], v[128:131], v[160:163], v[92:95]
	v_mfma_f32_16x16x32_bf16 v[88:91], v[136:139], v[160:163], v[88:91]
	v_mfma_f32_16x16x32_bf16 v[76:79], v[128:131], v[168:171], v[76:79]
	v_mfma_f32_16x16x32_bf16 v[72:75], v[136:139], v[168:171], v[72:75]
	v_mfma_f32_16x16x32_bf16 v[124:127], v[132:135], v[148:151], v[124:127]
	v_mfma_f32_16x16x32_bf16 v[120:123], v[140:143], v[148:151], v[120:123]
	v_mfma_f32_16x16x32_bf16 v[108:111], v[132:135], v[156:159], v[108:111]
	v_mfma_f32_16x16x32_bf16 v[104:107], v[140:143], v[156:159], v[104:107]
	v_mfma_f32_16x16x32_bf16 v[92:95], v[132:135], v[164:167], v[92:95]
	v_mfma_f32_16x16x32_bf16 v[88:91], v[140:143], v[164:167], v[88:91]
	v_mfma_f32_16x16x32_bf16 v[76:79], v[132:135], v[172:175], v[76:79]
	s_barrier
	v_mfma_f32_16x16x32_bf16 v[72:75], v[140:143], v[172:175], v[72:75]
	s_setprio 0
	s_add_i32 s43, s33, s21
	v_lshl_add_u64 v[216:217], s[16:17], 0, v[178:179]
	s_mov_b32 m0, s43
	ds_read_b128 v[192:195], v213
	ds_read_b128 v[196:199], v213 offset:1024
	ds_read_b128 v[200:203], v213 offset:2048
	ds_read_b128 v[204:207], v213 offset:3072
	global_load_lds_dwordx4 v[216:217], off
	v_lshl_add_u64 v[218:219], s[16:17], 0, v[182:183]
	s_add_i32 m0, s43, 0x2000
	s_nop 0
	global_load_lds_dwordx4 v[218:219], off
	s_waitcnt vmcnt(10)
	s_barrier
	s_waitcnt lgkmcnt(0)
	s_setprio 1
	s_waitcnt lgkmcnt(0)
	v_mfma_f32_16x16x32_bf16 v[116:119], v[192:195], v[144:147], v[116:119]
	v_mfma_f32_16x16x32_bf16 v[112:115], v[200:203], v[144:147], v[112:115]
	v_mfma_f32_16x16x32_bf16 v[100:103], v[192:195], v[152:155], v[100:103]
	v_mfma_f32_16x16x32_bf16 v[96:99], v[200:203], v[152:155], v[96:99]
	v_mfma_f32_16x16x32_bf16 v[84:87], v[192:195], v[160:163], v[84:87]
	v_mfma_f32_16x16x32_bf16 v[80:83], v[200:203], v[160:163], v[80:83]
	v_mfma_f32_16x16x32_bf16 v[68:71], v[192:195], v[168:171], v[68:71]
	v_mfma_f32_16x16x32_bf16 v[64:67], v[200:203], v[168:171], v[64:67]
	v_mfma_f32_16x16x32_bf16 v[116:119], v[196:199], v[148:151], v[116:119]
	v_mfma_f32_16x16x32_bf16 v[112:115], v[204:207], v[148:151], v[112:115]
	v_mfma_f32_16x16x32_bf16 v[100:103], v[196:199], v[156:159], v[100:103]
	v_mfma_f32_16x16x32_bf16 v[96:99], v[204:207], v[156:159], v[96:99]
	v_mfma_f32_16x16x32_bf16 v[84:87], v[196:199], v[164:167], v[84:87]
	v_mfma_f32_16x16x32_bf16 v[80:83], v[204:207], v[164:167], v[80:83]
	v_mfma_f32_16x16x32_bf16 v[68:71], v[196:199], v[172:175], v[68:71]
	s_barrier
	v_mfma_f32_16x16x32_bf16 v[64:67], v[204:207], v[172:175], v[64:67]
	s_setprio 0
	s_mov_b32 m0, s22
	v_lshl_add_u64 v[222:223], s[18:19], 0, v[176:177]
	ds_read_b128 v[144:147], v212 offset:16384
	ds_read_b128 v[148:151], v212 offset:17408
	ds_read_b128 v[152:155], v212 offset:18432
	ds_read_b128 v[156:159], v212 offset:19456
	ds_read_b128 v[160:163], v212 offset:20480
	ds_read_b128 v[164:167], v212 offset:21504
	ds_read_b128 v[168:171], v212 offset:22528
	ds_read_b128 v[172:175], v212 offset:23552
	global_load_lds_dwordx4 v[222:223], off
	v_lshl_add_u64 v[224:225], s[18:19], 0, v[180:181]
	s_mov_b32 m0, s23
	s_nop 0
	global_load_lds_dwordx4 v[224:225], off
	s_waitcnt vmcnt(10)
	s_barrier
	s_waitcnt lgkmcnt(0)
	s_setprio 1
	s_waitcnt lgkmcnt(0)
	v_mfma_f32_16x16x32_bf16 v[60:63], v[128:131], v[144:147], v[60:63]
	v_mfma_f32_16x16x32_bf16 v[56:59], v[136:139], v[144:147], v[56:59]
	v_mfma_f32_16x16x32_bf16 v[44:47], v[128:131], v[152:155], v[44:47]
	v_mfma_f32_16x16x32_bf16 v[40:43], v[136:139], v[152:155], v[40:43]
	v_mfma_f32_16x16x32_bf16 v[28:31], v[128:131], v[160:163], v[28:31]
	v_mfma_f32_16x16x32_bf16 v[24:27], v[136:139], v[160:163], v[24:27]
	v_mfma_f32_16x16x32_bf16 v[12:15], v[128:131], v[168:171], v[12:15]
	v_mfma_f32_16x16x32_bf16 v[8:11], v[136:139], v[168:171], v[8:11]
	v_mfma_f32_16x16x32_bf16 v[60:63], v[132:135], v[148:151], v[60:63]
	v_mfma_f32_16x16x32_bf16 v[56:59], v[140:143], v[148:151], v[56:59]
	v_mfma_f32_16x16x32_bf16 v[44:47], v[132:135], v[156:159], v[44:47]
	v_mfma_f32_16x16x32_bf16 v[40:43], v[140:143], v[156:159], v[40:43]
	v_mfma_f32_16x16x32_bf16 v[28:31], v[132:135], v[164:167], v[28:31]
	v_mfma_f32_16x16x32_bf16 v[24:27], v[140:143], v[164:167], v[24:27]
	v_mfma_f32_16x16x32_bf16 v[12:15], v[132:135], v[172:175], v[12:15]
	s_barrier
; #define PG8_STAGE(bufoff, gbase, voff) do { _Pragma("unroll") for (int _i = 0; _i < 2; ++_i) \
;         __builtin_amdgcn_global_load_lds((const unsigned*)((const char*)(gbase) + (voff)[_i]), (LAS unsigned*)(lds + (bufoff) + ldsw + _i * 8192), 16, 0, 0); } while (0)
; #define PG8_LDA(dst, b, h) do { _Pragma("unroll") for (int m = 0; m < 4; ++m) _Pragma("unroll") for (int k = 0; k < 2; ++k) dst[m][k] = *(const LAS bf16x8*)(lds + PG8_SA(b, h) + aoff + m * 2048 + k * 1024); } while (0)
; #define PG8_LDB(dst, b, h) do { _Pragma("unroll") for (int n = 0; n < 2; ++n) _Pragma("unroll") for (int k = 0; k < 2; ++k) dst[n][k] = *(const LAS bf16x8*)(lds + PG8_SB(b, h) + boff + n * 2048 + k * 1024); } while (0)
; #define PG8_MMA(ai, bj, At, Bt) do { __builtin_amdgcn_s_setprio(1); _Pragma("unroll") for (int m = 0; m < 4; ++m) _Pragma("unroll") for (int n = 0; n < 2; ++n) _Pragma("unroll") for (int k = 0; k < 2; ++k) \
;         acc[ai][bj][m][n] = __builtin_amdgcn_mfma_f32_16x16x32_bf16(Bt[n][k], At[m][k], acc[ai][bj][m][n], 0, 0, 0); __builtin_amdgcn_s_setprio(0); } while (0)
; #define PG8_WAIT_V(n) asm volatile("s_waitcnt vmcnt(" #n ")" ::: "memory")
; #define PG8_WAIT_L(n) asm volatile("s_waitcnt lgkmcnt(" #n ")" ::: "memory")
; #define PG8_BAR __builtin_amdgcn_s_barrier()
; #define PG8_SCHED __builtin_amdgcn_sched_barrier(0)
; template <class Epi>
; __device__ __forceinline__ void gemm_phase(ldsp lds, const Gemm g, const StaticOrder& S, const Epi& E) {
;     ...
;             PG8_WAIT_V(10); PG8_BAR; PG8_WAIT_L(0); PG8_MMA(1, 0, At, B0); PG8_BAR; PG8_SCHED;
;             PG8_STAGE(PG8_SB(0, 1), b2 + hstep, voffB);
;             PG8_WAIT_V(10); PG8_BAR; PG8_MMA(1, 1, At, B1); PG8_BAR;
;             PG8_LDB(B0, 1, 0); PG8_SCHED; PG8_LDA(At, 1, 0); PG8_STAGE(PG8_SA(0, 1), a2 + hstep, voffA);
;             PG8_WAIT_L(8); PG8_WAIT_V(10); PG8_BAR; PG8_WAIT_L(0); PG8_MMA(0, 0, At, B0); PG8_BAR; PG8_SCHED;
;             PG8_LDB(B1, 1, 1); PG8_STAGE(PG8_SB(1, 0), b3, voffB);
;             PG8_WAIT_V(10); PG8_BAR; PG8_WAIT_L(0); PG8_MMA(0, 1, At, B1); PG8_BAR;
	v_mfma_f32_16x16x32_bf16 v[8:11], v[140:143], v[172:175], v[8:11]
	s_setprio 0
	s_add_u32 s44, s16, 0x160000
	s_addc_u32 s45, s17, 0
	s_add_i32 s43, s34, s21
	v_lshl_add_u64 v[128:129], s[44:45], 0, v[178:179]
	s_mov_b32 m0, s43
	s_nop 0
	global_load_lds_dwordx4 v[128:129], off
	v_lshl_add_u64 v[128:129], s[44:45], 0, v[182:183]
	s_add_i32 m0, s43, 0x2000
	s_nop 0
	global_load_lds_dwordx4 v[128:129], off
	s_waitcnt vmcnt(10)
	s_barrier
	s_setprio 1
	v_mfma_f32_16x16x32_bf16 v[52:55], v[192:195], v[144:147], v[52:55]
	v_mfma_f32_16x16x32_bf16 v[48:51], v[200:203], v[144:147], v[48:51]
	v_mfma_f32_16x16x32_bf16 v[36:39], v[192:195], v[152:155], v[36:39]
	v_mfma_f32_16x16x32_bf16 v[32:35], v[200:203], v[152:155], v[32:35]
	v_mfma_f32_16x16x32_bf16 v[20:23], v[192:195], v[160:163], v[20:23]
	v_mfma_f32_16x16x32_bf16 v[16:19], v[200:203], v[160:163], v[16:19]
	v_mfma_f32_16x16x32_bf16 v[4:7], v[192:195], v[168:171], v[4:7]
	v_mfma_f32_16x16x32_bf16 v[0:3], v[200:203], v[168:171], v[0:3]
	v_mfma_f32_16x16x32_bf16 v[52:55], v[196:199], v[148:151], v[52:55]
	v_mfma_f32_16x16x32_bf16 v[48:51], v[204:207], v[148:151], v[48:51]
	v_mfma_f32_16x16x32_bf16 v[36:39], v[196:199], v[156:159], v[36:39]
	v_mfma_f32_16x16x32_bf16 v[32:35], v[204:207], v[156:159], v[32:35]
	v_mfma_f32_16x16x32_bf16 v[20:23], v[196:199], v[164:167], v[20:23]
	v_mfma_f32_16x16x32_bf16 v[16:19], v[204:207], v[164:167], v[16:19]
	v_mfma_f32_16x16x32_bf16 v[4:7], v[196:199], v[172:175], v[4:7]
	s_barrier
	v_mfma_f32_16x16x32_bf16 v[0:3], v[204:207], v[172:175], v[0:3]
	s_setprio 0
	s_add_i32 s43, 0, 0x18000
	v_add_u32_e32 v140, s43, v209
	ds_read_b128 v[128:131], v140
	ds_read_b128 v[132:135], v140 offset:1024
	ds_read_b128 v[136:139], v140 offset:2048
	ds_read_b128 v[140:143], v140 offset:3072
	s_add_u32 s18, s18, 0x160000
	s_addc_u32 s19, s19, 0
	s_mov_b32 m0, s24
	v_lshl_add_u64 v[192:193], s[18:19], 0, v[176:177]
	ds_read_b128 v[144:147], v212 offset:32768
	ds_read_b128 v[148:151], v212 offset:33792
	ds_read_b128 v[152:155], v212 offset:34816
	ds_read_b128 v[156:159], v212 offset:35840
	ds_read_b128 v[160:163], v212 offset:36864
	ds_read_b128 v[164:167], v212 offset:37888
	ds_read_b128 v[168:171], v212 offset:38912
	ds_read_b128 v[172:175], v212 offset:39936
	global_load_lds_dwordx4 v[192:193], off
	v_lshl_add_u64 v[192:193], s[18:19], 0, v[180:181]
	s_mov_b32 m0, s25
	s_nop 0
	global_load_lds_dwordx4 v[192:193], off
	s_waitcnt lgkmcnt(8)
	s_waitcnt vmcnt(10)
	s_barrier
	s_waitcnt lgkmcnt(0)
	s_setprio 1
	s_waitcnt lgkmcnt(0)
	v_mfma_f32_16x16x32_bf16 v[124:127], v[128:131], v[144:147], v[124:127]
	v_mfma_f32_16x16x32_bf16 v[120:123], v[136:139], v[144:147], v[120:123]
	v_mfma_f32_16x16x32_bf16 v[108:111], v[128:131], v[152:155], v[108:111]
	v_mfma_f32_16x16x32_bf16 v[104:107], v[136:139], v[152:155], v[104:107]
	v_mfma_f32_16x16x32_bf16 v[92:95], v[128:131], v[160:163], v[92:95]
	v_mfma_f32_16x16x32_bf16 v[88:91], v[136:139], v[160:163], v[88:91]
	v_mfma_f32_16x16x32_bf16 v[76:79], v[128:131], v[168:171], v[76:79]
	v_mfma_f32_16x16x32_bf16 v[72:75], v[136:139], v[168:171], v[72:75]
	v_mfma_f32_16x16x32_bf16 v[124:127], v[132:135], v[148:151], v[124:127]
	v_mfma_f32_16x16x32_bf16 v[120:123], v[140:143], v[148:151], v[120:123]
	v_mfma_f32_16x16x32_bf16 v[108:111], v[132:135], v[156:159], v[108:111]
	v_mfma_f32_16x16x32_bf16 v[104:107], v[140:143], v[156:159], v[104:107]
	v_mfma_f32_16x16x32_bf16 v[92:95], v[132:135], v[164:167], v[92:95]
	v_mfma_f32_16x16x32_bf16 v[88:91], v[140:143], v[164:167], v[88:91]
	v_mfma_f32_16x16x32_bf16 v[76:79], v[132:135], v[172:175], v[76:79]
	s_barrier
	v_mfma_f32_16x16x32_bf16 v[72:75], v[140:143], v[172:175], v[72:75]
	s_setprio 0
	s_add_i32 s18, 0, 0x1c000
	s_add_i32 s19, s43, s21
	v_add_u32_e32 v204, s18, v209
	v_lshl_add_u64 v[216:217], v[216:217], 0, s[12:13]
	s_mov_b32 m0, s19
	ds_read_b128 v[192:195], v204
	ds_read_b128 v[196:199], v204 offset:1024
	ds_read_b128 v[200:203], v204 offset:2048
	ds_read_b128 v[204:207], v204 offset:3072
	global_load_lds_dwordx4 v[216:217], off
	v_lshl_add_u64 v[216:217], v[218:219], 0, s[12:13]
	s_add_i32 m0, s19, 0x2000
	s_nop 0
	global_load_lds_dwordx4 v[216:217], off
	s_waitcnt vmcnt(10)
	s_barrier
	s_waitcnt lgkmcnt(0)
	s_setprio 1
	s_waitcnt lgkmcnt(0)
	v_mfma_f32_16x16x32_bf16 v[116:119], v[192:195], v[144:147], v[116:119]
	v_mfma_f32_16x16x32_bf16 v[112:115], v[200:203], v[144:147], v[112:115]
	v_mfma_f32_16x16x32_bf16 v[100:103], v[192:195], v[152:155], v[100:103]
	v_mfma_f32_16x16x32_bf16 v[96:99], v[200:203], v[152:155], v[96:99]
	v_mfma_f32_16x16x32_bf16 v[84:87], v[192:195], v[160:163], v[84:87]
	v_mfma_f32_16x16x32_bf16 v[80:83], v[200:203], v[160:163], v[80:83]
	v_mfma_f32_16x16x32_bf16 v[68:71], v[192:195], v[168:171], v[68:71]
	v_mfma_f32_16x16x32_bf16 v[64:67], v[200:203], v[168:171], v[64:67]
	v_mfma_f32_16x16x32_bf16 v[116:119], v[196:199], v[148:151], v[116:119]
	v_mfma_f32_16x16x32_bf16 v[112:115], v[204:207], v[148:151], v[112:115]
	v_mfma_f32_16x16x32_bf16 v[100:103], v[196:199], v[156:159], v[100:103]
	v_mfma_f32_16x16x32_bf16 v[96:99], v[204:207], v[156:159], v[96:99]
	v_mfma_f32_16x16x32_bf16 v[84:87], v[196:199], v[164:167], v[84:87]
	v_mfma_f32_16x16x32_bf16 v[80:83], v[204:207], v[164:167], v[80:83]
	v_mfma_f32_16x16x32_bf16 v[68:71], v[196:199], v[172:175], v[68:71]
	s_barrier
; #define PG8_STAGE(bufoff, gbase, voff) do { _Pragma("unroll") for (int _i = 0; _i < 2; ++_i) \
;         __builtin_amdgcn_global_load_lds((const unsigned*)((const char*)(gbase) + (voff)[_i]), (LAS unsigned*)(lds + (bufoff) + ldsw + _i * 8192), 16, 0, 0); } while (0)
; #define PG8_LDA(dst, b, h) do { _Pragma("unroll") for (int m = 0; m < 4; ++m) _Pragma("unroll") for (int k = 0; k < 2; ++k) dst[m][k] = *(const LAS bf16x8*)(lds + PG8_SA(b, h) + aoff + m * 2048 + k * 1024); } while (0)
; #define PG8_MMA(ai, bj, At, Bt) do { __builtin_amdgcn_s_setprio(1); _Pragma("unroll") for (int m = 0; m < 4; ++m) _Pragma("unroll") for (int n = 0; n < 2; ++n) _Pragma("unroll") for (int k = 0; k < 2; ++k) \
;         acc[ai][bj][m][n] = __builtin_amdgcn_mfma_f32_16x16x32_bf16(Bt[n][k], At[m][k], acc[ai][bj][m][n], 0, 0, 0); __builtin_amdgcn_s_setprio(0); } while (0)
; #define PG8_WAIT_V(n) asm volatile("s_waitcnt vmcnt(" #n ")" ::: "memory")
; #define PG8_WAIT_L(n) asm volatile("s_waitcnt lgkmcnt(" #n ")" ::: "memory")
; #define PG8_BAR __builtin_amdgcn_s_barrier()
; #define PG8_SCHED __builtin_amdgcn_sched_barrier(0)
; template <class Epi>
; __device__ __forceinline__ void gemm_phase(ldsp lds, const Gemm g, const StaticOrder& S, const Epi& E) {
;     ...
;             PG8_WAIT_V(10); PG8_BAR; PG8_WAIT_L(0); PG8_MMA(0, 1, At, B1); PG8_BAR;
;             PG8_LDA(At, 1, 1); PG8_STAGE(PG8_SA(1, 0), a3, voffA);
;             PG8_WAIT_V(10); PG8_BAR; PG8_WAIT_L(0); PG8_MMA(1, 0, At, B0); PG8_BAR; PG8_SCHED;
;             PG8_STAGE(PG8_SB(1, 1), b3 + hstep, voffB);
;             PG8_WAIT_V(10); PG8_BAR; PG8_MMA(1, 1, At, B1); PG8_BAR;
;         }
	v_mfma_f32_16x16x32_bf16 v[64:67], v[204:207], v[172:175], v[64:67]
	s_setprio 0
	s_mov_b32 m0, s27
	v_lshl_add_u64 v[216:217], v[222:223], 0, s[12:13]
	ds_read_b128 v[144:147], v212 offset:49152
	ds_read_b128 v[148:151], v212 offset:50176
	ds_read_b128 v[152:155], v212 offset:51200
	ds_read_b128 v[156:159], v212 offset:52224
	ds_read_b128 v[160:163], v212 offset:53248
	ds_read_b128 v[164:167], v212 offset:54272
	ds_read_b128 v[168:171], v212 offset:55296
	ds_read_b128 v[172:175], v212 offset:56320
	global_load_lds_dwordx4 v[216:217], off
	v_lshl_add_u64 v[216:217], v[224:225], 0, s[12:13]
	s_mov_b32 m0, s28
	s_nop 0
	global_load_lds_dwordx4 v[216:217], off
	s_waitcnt vmcnt(10)
	s_barrier
	s_waitcnt lgkmcnt(0)
	s_setprio 1
	s_waitcnt lgkmcnt(0)
	v_mfma_f32_16x16x32_bf16 v[60:63], v[128:131], v[144:147], v[60:63]
	v_mfma_f32_16x16x32_bf16 v[56:59], v[136:139], v[144:147], v[56:59]
	v_mfma_f32_16x16x32_bf16 v[44:47], v[128:131], v[152:155], v[44:47]
	v_mfma_f32_16x16x32_bf16 v[40:43], v[136:139], v[152:155], v[40:43]
	v_mfma_f32_16x16x32_bf16 v[28:31], v[128:131], v[160:163], v[28:31]
	v_mfma_f32_16x16x32_bf16 v[24:27], v[136:139], v[160:163], v[24:27]
	v_mfma_f32_16x16x32_bf16 v[12:15], v[128:131], v[168:171], v[12:15]
	v_mfma_f32_16x16x32_bf16 v[8:11], v[136:139], v[168:171], v[8:11]
	v_mfma_f32_16x16x32_bf16 v[60:63], v[132:135], v[148:151], v[60:63]
	v_mfma_f32_16x16x32_bf16 v[56:59], v[140:143], v[148:151], v[56:59]
	v_mfma_f32_16x16x32_bf16 v[44:47], v[132:135], v[156:159], v[44:47]
	v_mfma_f32_16x16x32_bf16 v[40:43], v[140:143], v[156:159], v[40:43]
	v_mfma_f32_16x16x32_bf16 v[28:31], v[132:135], v[164:167], v[28:31]
	v_mfma_f32_16x16x32_bf16 v[24:27], v[140:143], v[164:167], v[24:27]
	v_mfma_f32_16x16x32_bf16 v[12:15], v[132:135], v[172:175], v[12:15]
	s_barrier
	v_mfma_f32_16x16x32_bf16 v[8:11], v[140:143], v[172:175], v[8:11]
	s_setprio 0
	s_add_u32 s16, s16, 0x160080
	s_addc_u32 s17, s17, 0
	s_add_i32 s18, s18, s21
	v_lshl_add_u64 v[128:129], s[16:17], 0, v[178:179]
	s_mov_b32 m0, s18
	s_nop 0
	global_load_lds_dwordx4 v[128:129], off
	v_lshl_add_u64 v[128:129], s[16:17], 0, v[182:183]
	s_add_i32 m0, s18, 0x2000
	s_nop 0
	global_load_lds_dwordx4 v[128:129], off
	s_waitcnt vmcnt(10)
	s_barrier
	s_setprio 1
	v_mfma_f32_16x16x32_bf16 v[52:55], v[192:195], v[144:147], v[52:55]
	v_mfma_f32_16x16x32_bf16 v[48:51], v[200:203], v[144:147], v[48:51]
	v_mfma_f32_16x16x32_bf16 v[36:39], v[192:195], v[152:155], v[36:39]
	v_mfma_f32_16x16x32_bf16 v[32:35], v[200:203], v[152:155], v[32:35]
	v_mfma_f32_16x16x32_bf16 v[20:23], v[192:195], v[160:163], v[20:23]
	v_mfma_f32_16x16x32_bf16 v[16:19], v[200:203], v[160:163], v[16:19]
	v_mfma_f32_16x16x32_bf16 v[4:7], v[192:195], v[168:171], v[4:7]
	v_mfma_f32_16x16x32_bf16 v[0:3], v[200:203], v[168:171], v[0:3]
	v_mfma_f32_16x16x32_bf16 v[52:55], v[196:199], v[148:151], v[52:55]
	v_mfma_f32_16x16x32_bf16 v[48:51], v[204:207], v[148:151], v[48:51]
	v_mfma_f32_16x16x32_bf16 v[36:39], v[196:199], v[156:159], v[36:39]
	v_mfma_f32_16x16x32_bf16 v[32:35], v[204:207], v[156:159], v[32:35]
	v_mfma_f32_16x16x32_bf16 v[20:23], v[196:199], v[164:167], v[20:23]
	v_mfma_f32_16x16x32_bf16 v[16:19], v[204:207], v[164:167], v[16:19]
	v_mfma_f32_16x16x32_bf16 v[4:7], v[196:199], v[172:175], v[4:7]
	s_barrier
	v_mfma_f32_16x16x32_bf16 v[0:3], v[204:207], v[172:175], v[0:3]
	s_setprio 0
	s_add_i32 s42, s42, 2
	s_add_u32 s14, s14, 0x100
	s_addc_u32 s15, s15, 0
	s_add_u32 s40, s40, 0x100
	s_addc_u32 s41, s41, 0
	s_cmpk_gt_u32 s42, 0x55
	s_cbranch_scc0 .LBB0_899
;     __device__ __forceinline__ void ld(f32x4 (&xv)[2][2][2], int row0, int col0, int ai, int mh) const {
; #pragma unroll
;         for (int mm = 0; mm < 2; ++mm)
; #pragma unroll
;             for (int bj = 0; bj < 2; ++bj) { const size_t off = (size_t)(row0 + ai * 128 + (2 * mh + mm) * 16) * 2048 + col0 + bj * 128;
;                 xv[mm][bj][0] = *(const f32x4*)(base + off); xv[mm][bj][1] = *(const f32x4*)(base + off + 4); }
;     }
;     __device__ __forceinline__ void fin(const f32x4 (&acc)[2][2][4][2], const f32x4 (&xv)[2][2][2], int row0, int col0, int fq, int ai, int mh) const {
; #pragma unroll
;         for (int mm = 0; mm < 2; ++mm) { const int m = 2 * mh + mm; const int row = row0 + ai * 128 + m * 16; float sq = 0.f;
; #pragma unroll
;             for (int bj = 0; bj < 2; ++bj) { const size_t off = (size_t)row * 2048 + col0 + bj * 128;
;                 const f32x4 y0 = xv[mm][bj][0] + acc[ai][bj][m][0], y1 = xv[mm][bj][1] + acc[ai][bj][m][1];
;                 *(f32x4*)(out + off) = y0; *(f32x4*)(out + off + 4) = y1;
;                 if (ob) *(u32x4*)(ob + off) = pack8(y0, y1);
;                 sq += (y0[0] * y0[0] + y0[1] * y0[1]) + (y0[2] * y0[2] + y0[3] * y0[3]) + (y1[0] * y1[0] + y1[1] * y1[1]) + (y1[2] * y1[2] + y1[3] * y1[3]); }
;             sq += __shfl_xor(sq, 16); sq += __shfl_xor(sq, 32);
;             if (fq == 0) atomicAdd(ssq + row, (unsigned long long)(sq * 16777216.0f + 0.5f)); }
	v_lshl_add_u32 v192, s38, 8, v208
	v_lshl_or_b32 v128, s39, 8, v210
	v_ashrrev_i32_e32 v193, 31, v192
	v_ashrrev_i32_e32 v129, 31, v128
	v_lshlrev_b64 v[130:131], 13, v[192:193]
	v_lshl_add_u64 v[130:131], s[70:71], 0, v[130:131]
	v_lshlrev_b64 v[194:195], 2, v[128:129]
	v_lshl_add_u64 v[234:235], v[130:131], 0, v[194:195]
	global_load_dwordx4 v[216:219], v[234:235], off
	global_load_dwordx4 v[222:225], v[234:235], off offset:16
	global_load_dwordx4 v[226:229], v[234:235], off offset:512
	global_load_dwordx4 v[230:233], v[234:235], off offset:528
	v_or_b32_e32 v204, 16, v192
	v_or_b32_e32 v200, 32, v192
	v_or_b32_e32 v196, 48, v192
	v_ashrrev_i32_e32 v205, 31, v204
	v_ashrrev_i32_e32 v201, 31, v200
	v_ashrrev_i32_e32 v197, 31, v196
	v_lshlrev_b64 v[128:129], 13, v[204:205]
	v_lshlrev_b64 v[130:131], 13, v[200:201]
	v_lshlrev_b64 v[132:133], 13, v[196:197]
	v_lshl_add_u64 v[128:129], s[70:71], 0, v[128:129]
	v_lshl_add_u64 v[130:131], s[70:71], 0, v[130:131]
	v_lshl_add_u64 v[132:133], s[70:71], 0, v[132:133]
	v_lshl_add_u64 v[206:207], v[128:129], 0, v[194:195]
	v_lshl_add_u64 v[202:203], v[130:131], 0, v[194:195]
	v_lshl_add_u64 v[198:199], v[132:133], 0, v[194:195]
	global_load_dwordx4 v[168:171], v[206:207], off offset:16
	global_load_dwordx4 v[172:175], v[206:207], off
	global_load_dwordx4 v[160:163], v[206:207], off offset:528
	global_load_dwordx4 v[164:167], v[206:207], off offset:512
	global_load_dwordx4 v[152:155], v[202:203], off offset:16
	global_load_dwordx4 v[156:159], v[202:203], off
	global_load_dwordx4 v[144:147], v[202:203], off offset:528
	global_load_dwordx4 v[148:151], v[202:203], off offset:512
	global_load_dwordx4 v[136:139], v[198:199], off offset:16
	global_load_dwordx4 v[140:143], v[198:199], off
	global_load_dwordx4 v[128:131], v[198:199], off offset:528
	global_load_dwordx4 v[132:135], v[198:199], off offset:512
	v_and_b32_e32 v221, 64, v214
	v_xor_b32_e32 v215, 16, v214
	v_add_u32_e32 v221, 64, v221
	v_cmp_lt_i32_e32 vcc, v215, v221
	s_waitcnt vmcnt(0)
	v_pk_add_f32 v[126:127], v[126:127], v[218:219]
	v_pk_add_f32 v[124:125], v[124:125], v[216:217]
	v_pk_add_f32 v[118:119], v[118:119], v[228:229]
	v_pk_add_f32 v[116:117], v[116:117], v[226:227]
	v_pk_add_f32 v[120:121], v[120:121], v[222:223]
	v_pk_add_f32 v[222:223], v[112:113], v[230:231]
	v_mul_f32_e32 v112, v125, v125
	v_mul_f32_e32 v113, v127, v127
	v_mul_f32_e32 v216, v117, v117
	v_mul_f32_e32 v217, v119, v119
	v_pk_add_f32 v[122:123], v[122:123], v[224:225]
	v_pk_add_f32 v[224:225], v[114:115], v[232:233]
	v_mul_f32_e32 v114, v121, v121
	v_mul_f32_e32 v218, v223, v223
	v_fmac_f32_e32 v112, v124, v124
	v_fmac_f32_e32 v113, v126, v126
	v_fmac_f32_e32 v216, v116, v116
	v_fmac_f32_e32 v217, v118, v118
	v_mul_f32_e32 v115, v123, v123
	v_mul_f32_e32 v219, v225, v225
	v_fmac_f32_e32 v114, v120, v120
	v_fmac_f32_e32 v218, v222, v222
	v_add_f32_e32 v112, v112, v113
	v_add_f32_e32 v113, v216, v217
	v_fmac_f32_e32 v115, v122, v122
	v_fmac_f32_e32 v219, v224, v224
	v_add_f32_e32 v112, v112, v114
	v_add_f32_e32 v113, v113, v218
	v_cndmask_b32_e32 v215, v214, v215, vcc
	v_add_f32_e32 v112, v115, v112
	v_add_f32_e32 v113, v219, v113
	v_lshlrev_b32_e32 v215, 2, v215
	v_add_f32_e32 v112, v112, v113
	ds_bpermute_b32 v113, v215, v112
	v_xor_b32_e32 v114, 32, v214
	v_cmp_lt_i32_e32 vcc, v114, v221
	global_store_dwordx4 v[234:235], v[124:127], off
	global_store_dwordx4 v[234:235], v[120:123], off offset:16
	global_store_dwordx4 v[234:235], v[116:119], off offset:512
	global_store_dwordx4 v[234:235], v[222:225], off offset:528
	v_cndmask_b32_e32 v114, v214, v114, vcc
	v_lshlrev_b32_e32 v216, 2, v114
	s_waitcnt lgkmcnt(0)
	v_add_f32_e32 v112, v112, v113
	ds_bpermute_b32 v113, v216, v112
	s_and_saveexec_b64 s[14:15], s[2:3]
	s_cbranch_execz .LBB0_902
	s_waitcnt lgkmcnt(0)
	v_add_f32_e32 v112, v112, v113
	v_fma_f32 v112, v112, s35, 0.5
	v_trunc_f32_e32 v112, v112
	v_mul_f32_e32 v113, 0x2f800000, v112
	v_floor_f32_e32 v113, v113
	v_fmac_f32_e32 v112, 0xcf800000, v113
	v_cvt_u32_f32_e32 v112, v112
	v_cvt_u32_f32_e32 v113, v113
	v_lshl_add_u64 v[114:115], v[192:193], 3, s[8:9]
	global_atomic_add_x2 v[114:115], v[112:113], off
